# v33 + one static s_setprio 1 for waves 4-7 before each GEMM main loop (8 of 9 loops), reset to 0 at loop exit
# speedup vs baseline: 1.0080x; 1.0080x over previous
; #define PG8_STAGE(bufoff, gbase, voff) do { _Pragma("unroll") for (int _i = 0; _i < 2; ++_i) \
;         __builtin_amdgcn_global_load_lds((const unsigned*)((const char*)(gbase) + (voff)[_i]), (LAS unsigned*)(lds + (bufoff) + ldsw + _i * 8192), 16, 0, 0); } while (0)
; #define PG8_LDA(dst, b, h) do { _Pragma("unroll") for (int m = 0; m < 4; ++m) _Pragma("unroll") for (int k = 0; k < 2; ++k) dst[m][k] = *(const LAS bf16x8*)(lds + PG8_SA(b, h) + aoff + m * 2048 + k * 1024); } while (0)
; #define PG8_LDB(dst, b, h) do { _Pragma("unroll") for (int n = 0; n < 2; ++n) _Pragma("unroll") for (int k = 0; k < 2; ++k) dst[n][k] = *(const LAS bf16x8*)(lds + PG8_SB(b, h) + boff + n * 2048 + k * 1024); } while (0)
; #define PG8_WAIT_V(n) asm volatile("s_waitcnt vmcnt(" #n ")" ::: "memory")
; #define PG8_WAIT_L(n) asm volatile("s_waitcnt lgkmcnt(" #n ")" ::: "memory")
; #define PG8_BAR __builtin_amdgcn_s_barrier()
; #define PG8_SCHED __builtin_amdgcn_sched_barrier(0)
; template <class Epi, class Sched>
; __device__ __forceinline__ void gemm_phase(LAS unsigned char* lds, const Gemm g, const Sched& S, const Epi& E) {
;     ...
; #pragma unroll
;     for (int a = 0; a < 2; ++a)
; #pragma unroll
;         for (int b = 0; b < 2; ++b)
; #pragma unroll
;             for (int m = 0; m < 4; ++m)
; #pragma unroll
;                 for (int n = 0; n < 2; ++n) acc[a][b][m][n] = (f32x4){0.f, 0.f, 0.f, 0.f};
;     ...
;         const bool has_next = S.next(ui + 1, nxt);
;         const char* nA = has_next ? (const char*)g.A + nxt.offA : cA; const char* nB = has_next ? (const char*)g.Bt + nxt.offB : cB;
;         for (int t = 0; t < nt; t += 2) {
;             const bool last = (t == nt - 2);
;             const char* a1 = cA + (size_t)(t + 1) * kstep;
;             const char* a2 = last ? nA : cA + (size_t)(t + 2) * kstep; const char* b2 = last ? nB : cB + (size_t)(t + 2) * kstep;
;             const char* a3 = a2 + kstep; const char* b3 = b2 + kstep;
;             if constexpr (Epi::MIDK) { if (t == (nt >> 1)) { int fr_ = fr, fq_ = fq; asm volatile("" : "+v"(fr_), "+v"(fq_)); E.mid(acc, cur, wr, wc, fr_, fq_); } }
;             PG8_LDB(B0, 0, 0); PG8_LDB(B1, 0, 1); PG8_SCHED; PG8_LDA(At, 0, 0); PG8_STAGE(PG8_SA(1, 1), a1 + hsA, voffA);
;             PG8_WAIT_V(8); PG8_WAIT_L(0); PG8_BAR; PG8_MMA(0, 0, At, B0); PG8_MMA(0, 1, At, B1); PG8_BAR; PG8_SCHED;
.LBB0_220:
	s_add_u32 s50, s2, s46
	s_addc_u32 s51, s3, s47
	s_add_u32 s76, s7, s48
	s_addc_u32 s77, s11, s49
	s_andn2_b64 vcc, exec, s[74:75]
	s_cbranch_vccnz .Lzc_6242
	s_and_b64 s[8:9], s[36:37], exec
	s_cselect_b32 s10, s51, s1
	s_cselect_b32 s43, s50, s0
	s_cselect_b32 s45, s77, s39
	s_cselect_b32 vcc_lo, s76, s38
	s_add_u32 s0, s0, 0x40080
	s_addc_u32 s1, s1, 0
	s_add_u32 vcc_hi, s38, 0x100
	v_mov_b32_e32 v6, 0
	s_mov_b64 s[22:23], s[74:75]
	s_addc_u32 s8, s39, 0
	s_mov_b32 s9, 0
	v_mov_b32_e32 v7, v6
	v_mov_b32_e32 v8, v6
	v_mov_b32_e32 v9, v6
	v_mov_b32_e32 v14, v6
	v_mov_b32_e32 v15, v6
	v_mov_b32_e32 v16, v6
	v_mov_b32_e32 v17, v6
	v_mov_b32_e32 v22, v6
	v_mov_b32_e32 v23, v6
	v_mov_b32_e32 v24, v6
	v_mov_b32_e32 v25, v6
	v_mov_b32_e32 v30, v6
	v_mov_b32_e32 v31, v6
	v_mov_b32_e32 v32, v6
	v_mov_b32_e32 v33, v6
	v_mov_b32_e32 v38, v6
	v_mov_b32_e32 v39, v6
	v_mov_b32_e32 v40, v6
	v_mov_b32_e32 v41, v6
	v_mov_b32_e32 v46, v6
	v_mov_b32_e32 v47, v6
	v_mov_b32_e32 v48, v6
	v_mov_b32_e32 v49, v6
	v_mov_b32_e32 v54, v6
	v_mov_b32_e32 v55, v6
	v_mov_b32_e32 v56, v6
	v_mov_b32_e32 v57, v6
	v_mov_b32_e32 v62, v6
	v_mov_b32_e32 v63, v6
	v_mov_b32_e32 v64, v6
	v_mov_b32_e32 v65, v6
	v_mov_b32_e32 v2, v6
	v_mov_b32_e32 v3, v6
	v_mov_b32_e32 v4, v6
	v_mov_b32_e32 v5, v6
	v_mov_b32_e32 v10, v6
	v_mov_b32_e32 v11, v6
	v_mov_b32_e32 v12, v6
	v_mov_b32_e32 v13, v6
	v_mov_b32_e32 v18, v6
	v_mov_b32_e32 v19, v6
	v_mov_b32_e32 v20, v6
	v_mov_b32_e32 v21, v6
	v_mov_b32_e32 v26, v6
	v_mov_b32_e32 v27, v6
	v_mov_b32_e32 v28, v6
	v_mov_b32_e32 v29, v6
	v_mov_b32_e32 v34, v6
	v_mov_b32_e32 v35, v6
	v_mov_b32_e32 v36, v6
	v_mov_b32_e32 v37, v6
	v_mov_b32_e32 v42, v6
	v_mov_b32_e32 v43, v6
	v_mov_b32_e32 v44, v6
	v_mov_b32_e32 v45, v6
	v_mov_b32_e32 v50, v6
	v_mov_b32_e32 v51, v6
	v_mov_b32_e32 v52, v6
	v_mov_b32_e32 v53, v6
	v_mov_b32_e32 v58, v6
	v_mov_b32_e32 v59, v6
	v_mov_b32_e32 v60, v6
	v_mov_b32_e32 v61, v6
	v_mov_b32_e32 v70, v6
	v_mov_b32_e32 v71, v6
	v_mov_b32_e32 v72, v6
	v_mov_b32_e32 v73, v6
	v_mov_b32_e32 v78, v6
	v_mov_b32_e32 v79, v6
	v_mov_b32_e32 v80, v6
	v_mov_b32_e32 v81, v6
	v_mov_b32_e32 v86, v6
	v_mov_b32_e32 v87, v6
	v_mov_b32_e32 v88, v6
	v_mov_b32_e32 v89, v6
	v_mov_b32_e32 v94, v6
	v_mov_b32_e32 v95, v6
	v_mov_b32_e32 v96, v6
	v_mov_b32_e32 v97, v6
	v_mov_b32_e32 v102, v6
	v_mov_b32_e32 v103, v6
	v_mov_b32_e32 v104, v6
	v_mov_b32_e32 v105, v6
	v_mov_b32_e32 v110, v6
	v_mov_b32_e32 v111, v6
	v_mov_b32_e32 v112, v6
	v_mov_b32_e32 v113, v6
	v_mov_b32_e32 v118, v6
	v_mov_b32_e32 v119, v6
	v_mov_b32_e32 v120, v6
	v_mov_b32_e32 v121, v6
	v_mov_b32_e32 v126, v6
	v_mov_b32_e32 v127, v6
	v_mov_b32_e32 v128, v6
	v_mov_b32_e32 v129, v6
	v_mov_b32_e32 v66, v6
	v_mov_b32_e32 v67, v6
	v_mov_b32_e32 v68, v6
	v_mov_b32_e32 v69, v6
	v_mov_b32_e32 v74, v6
	v_mov_b32_e32 v75, v6
	v_mov_b32_e32 v76, v6
	v_mov_b32_e32 v77, v6
	v_mov_b32_e32 v82, v6
	v_mov_b32_e32 v83, v6
	v_mov_b32_e32 v84, v6
	v_mov_b32_e32 v85, v6
	v_mov_b32_e32 v90, v6
	v_mov_b32_e32 v91, v6
	v_mov_b32_e32 v92, v6
	v_mov_b32_e32 v93, v6
	v_mov_b32_e32 v98, v6
	v_mov_b32_e32 v99, v6
	v_mov_b32_e32 v100, v6
	v_mov_b32_e32 v101, v6
	v_mov_b32_e32 v106, v6
	v_mov_b32_e32 v107, v6
	v_mov_b32_e32 v108, v6
	v_mov_b32_e32 v109, v6
	v_mov_b32_e32 v114, v6
	v_mov_b32_e32 v115, v6
	v_mov_b32_e32 v116, v6
	v_mov_b32_e32 v117, v6
	v_mov_b32_e32 v122, v6
	v_mov_b32_e32 v123, v6
	v_mov_b32_e32 v124, v6
	v_mov_b32_e32 v125, v6
	v_readfirstlane_b32 s96, v193
	s_lshr_b32 s96, s96, 8
	s_cmp_eq_u32 s96, 1
	s_cbranch_scc0 .Lnp_222
	s_setprio 1
.Lnp_222:
.LBB0_222:
	s_add_i32 s96, s9, 2
	s_add_u32 s20, s0, 0xfffc0080
	s_addc_u32 s21, s1, -1
	s_add_i32 s74, 0, 0x10000
	s_cmp_eq_u32 s82, s9
	s_cselect_b32 s85, s10, s21
	s_cselect_b32 s84, s43, s20
	s_cselect_b32 s39, s45, s8
	s_cselect_b32 s38, vcc_lo, vcc_hi
	s_add_i32 s9, 0, 0x14000
	v_add_u32_e32 v154, s74, v160
	v_add_u32_e32 v174, s9, v160
	ds_read_b128 v[142:145], v154
	ds_read_b128 v[146:149], v154 offset:1024
	ds_read_b128 v[150:153], v154 offset:2048
	ds_read_b128 v[154:157], v154 offset:3072
	ds_read_b128 v[162:165], v174
	ds_read_b128 v[166:169], v174 offset:1024
	ds_read_b128 v[170:173], v174 offset:2048
	ds_read_b128 v[174:177], v174 offset:3072
	v_lshl_add_u64 v[190:191], s[0:1], 0, v[138:139]
	s_add_i32 m0, s16, 0xc000
	ds_read_b128 v[178:181], v161
	ds_read_b128 v[182:185], v161 offset:1024
	ds_read_b128 v[186:189], v161 offset:2048
	ds_read_b128 v[208:211], v161 offset:3072
	ds_read_b128 v[212:215], v161 offset:4096
	ds_read_b128 v[216:219], v161 offset:5120
	ds_read_b128 v[220:223], v161 offset:6144
	ds_read_b128 v[224:227], v161 offset:7168
	global_load_lds_dwordx4 v[190:191], off
	v_lshl_add_u64 v[190:191], s[0:1], 0, v[140:141]
	s_add_i32 m0, s16, 0xe000
	s_nop 0
	global_load_lds_dwordx4 v[190:191], off
	s_waitcnt vmcnt(8)
	s_waitcnt lgkmcnt(0)
	s_barrier
; #define PG8_STAGE(bufoff, gbase, voff) do { _Pragma("unroll") for (int _i = 0; _i < 2; ++_i) \
;         __builtin_amdgcn_global_load_lds((const unsigned*)((const char*)(gbase) + (voff)[_i]), (LAS unsigned*)(lds + (bufoff) + ldsw + _i * 8192), 16, 0, 0); } while (0)
; #define PG8_LDA(dst, b, h) do { _Pragma("unroll") for (int m = 0; m < 4; ++m) _Pragma("unroll") for (int k = 0; k < 2; ++k) dst[m][k] = *(const LAS bf16x8*)(lds + PG8_SA(b, h) + aoff + m * 2048 + k * 1024); } while (0)
; #define PG8_MMA(ai, bj, At, Bt) do { __builtin_amdgcn_s_setprio(1); _Pragma("unroll") for (int m = 0; m < 4; ++m) _Pragma("unroll") for (int n = 0; n < 2; ++n) _Pragma("unroll") for (int k = 0; k < 2; ++k) \
;         acc[ai][bj][m][n] = __builtin_amdgcn_mfma_f32_16x16x32_bf16(Bt[n][k], At[m][k], acc[ai][bj][m][n], 0, 0, 0); __builtin_amdgcn_s_setprio(0); } while (0)
; #define PG8_WAIT_V(n) asm volatile("s_waitcnt vmcnt(" #n ")" ::: "memory")
; #define PG8_WAIT_L(n) asm volatile("s_waitcnt lgkmcnt(" #n ")" ::: "memory")
; #define PG8_BAR __builtin_amdgcn_s_barrier()
; #define PG8_SCHED __builtin_amdgcn_sched_barrier(0)
; template <class Epi, class Sched>
; __device__ __forceinline__ void gemm_phase(LAS unsigned char* lds, const Gemm g, const Sched& S, const Epi& E) {
;     ...
;             PG8_WAIT_V(8); PG8_WAIT_L(0); PG8_BAR; PG8_MMA(0, 0, At, B0); PG8_MMA(0, 1, At, B1); PG8_BAR; PG8_SCHED;
;             PG8_LDA(At, 0, 1); PG8_STAGE(PG8_SB(0, 0), b2, voffB); PG8_STAGE(PG8_SB(0, 1), b2 + hsB, voffB); PG8_STAGE(PG8_SA(0, 0), a2, voffA);
;             PG8_WAIT_V(8); PG8_WAIT_L(0); PG8_BAR; PG8_MMA(1, 0, At, B0); PG8_MMA(1, 1, At, B1); PG8_BAR; PG8_SCHED;
	s_waitcnt lgkmcnt(0)
	v_mfma_f32_16x16x32_bf16 v[122:125], v[142:145], v[178:181], v[122:125]
	v_mfma_f32_16x16x32_bf16 v[114:117], v[150:153], v[178:181], v[114:117]
	v_mfma_f32_16x16x32_bf16 v[106:109], v[142:145], v[186:189], v[106:109]
	v_mfma_f32_16x16x32_bf16 v[98:101], v[150:153], v[186:189], v[98:101]
	v_mfma_f32_16x16x32_bf16 v[90:93], v[142:145], v[212:215], v[90:93]
	v_mfma_f32_16x16x32_bf16 v[82:85], v[150:153], v[212:215], v[82:85]
	v_mfma_f32_16x16x32_bf16 v[74:77], v[142:145], v[220:223], v[74:77]
	v_mfma_f32_16x16x32_bf16 v[66:69], v[150:153], v[220:223], v[66:69]
	v_mfma_f32_16x16x32_bf16 v[122:125], v[146:149], v[182:185], v[122:125]
	v_mfma_f32_16x16x32_bf16 v[114:117], v[154:157], v[182:185], v[114:117]
	v_mfma_f32_16x16x32_bf16 v[106:109], v[146:149], v[208:211], v[106:109]
	v_mfma_f32_16x16x32_bf16 v[98:101], v[154:157], v[208:211], v[98:101]
	v_mfma_f32_16x16x32_bf16 v[90:93], v[146:149], v[216:219], v[90:93]
	v_mfma_f32_16x16x32_bf16 v[82:85], v[154:157], v[216:219], v[82:85]
	v_mfma_f32_16x16x32_bf16 v[74:77], v[146:149], v[224:227], v[74:77]
	v_mfma_f32_16x16x32_bf16 v[66:69], v[154:157], v[224:227], v[66:69]
	v_mfma_f32_16x16x32_bf16 v[126:129], v[162:165], v[178:181], v[126:129]
	v_mfma_f32_16x16x32_bf16 v[118:121], v[170:173], v[178:181], v[118:121]
	v_mfma_f32_16x16x32_bf16 v[110:113], v[162:165], v[186:189], v[110:113]
	v_mfma_f32_16x16x32_bf16 v[102:105], v[170:173], v[186:189], v[102:105]
	v_mfma_f32_16x16x32_bf16 v[94:97], v[162:165], v[212:215], v[94:97]
	v_mfma_f32_16x16x32_bf16 v[86:89], v[170:173], v[212:215], v[86:89]
	v_mfma_f32_16x16x32_bf16 v[78:81], v[162:165], v[220:223], v[78:81]
	v_mfma_f32_16x16x32_bf16 v[70:73], v[170:173], v[220:223], v[70:73]
	v_mfma_f32_16x16x32_bf16 v[126:129], v[166:169], v[182:185], v[126:129]
	v_mfma_f32_16x16x32_bf16 v[118:121], v[174:177], v[182:185], v[118:121]
	v_mfma_f32_16x16x32_bf16 v[110:113], v[166:169], v[208:211], v[110:113]
	v_mfma_f32_16x16x32_bf16 v[102:105], v[174:177], v[208:211], v[102:105]
	v_mfma_f32_16x16x32_bf16 v[94:97], v[166:169], v[216:219], v[94:97]
	v_mfma_f32_16x16x32_bf16 v[86:89], v[174:177], v[216:219], v[86:89]
	v_mfma_f32_16x16x32_bf16 v[78:81], v[166:169], v[224:227], v[78:81]
	v_mfma_f32_16x16x32_bf16 v[70:73], v[174:177], v[224:227], v[70:73]
	s_barrier
	s_add_i32 s20, s74, s12
	v_lshl_add_u64 v[190:191], s[38:39], 0, v[0:1]
	s_mov_b32 m0, s20
	ds_read_b128 v[178:181], v161 offset:16384
	ds_read_b128 v[182:185], v161 offset:17408
	ds_read_b128 v[186:189], v161 offset:18432
	ds_read_b128 v[208:211], v161 offset:19456
	ds_read_b128 v[212:215], v161 offset:20480
	ds_read_b128 v[216:219], v161 offset:21504
	ds_read_b128 v[220:223], v161 offset:22528
	ds_read_b128 v[224:227], v161 offset:23552
	global_load_lds_dwordx4 v[190:191], off
	s_add_i32 m0, s20, 0x2000
	s_add_u32 s20, s38, 0x40000
	v_lshl_add_u64 v[228:229], s[38:39], 0, v[130:131]
	s_addc_u32 s21, s39, 0
	s_add_i32 s9, s9, s12
	global_load_lds_dwordx4 v[228:229], off
	v_lshl_add_u64 v[230:231], s[20:21], 0, v[0:1]
	s_mov_b32 m0, s9
	v_lshl_add_u64 v[232:233], s[84:85], 0, v[132:133]
	global_load_lds_dwordx4 v[230:231], off
	v_lshl_add_u64 v[230:231], s[20:21], 0, v[130:131]
	s_add_i32 m0, s9, 0x2000
	s_nop 0
	global_load_lds_dwordx4 v[230:231], off
	v_lshl_add_u64 v[230:231], s[84:85], 0, v[134:135]
	s_mov_b32 m0, s16
	s_nop 0
	global_load_lds_dwordx4 v[230:231], off
	s_mov_b32 m0, s30
	s_nop 0
	global_load_lds_dwordx4 v[232:233], off
	s_waitcnt vmcnt(8)
	s_waitcnt lgkmcnt(0)
	s_barrier
	s_waitcnt lgkmcnt(0)
	v_mfma_f32_16x16x32_bf16 v[58:61], v[142:145], v[178:181], v[58:61]
	v_mfma_f32_16x16x32_bf16 v[50:53], v[150:153], v[178:181], v[50:53]
	v_mfma_f32_16x16x32_bf16 v[42:45], v[142:145], v[186:189], v[42:45]
	v_mfma_f32_16x16x32_bf16 v[34:37], v[150:153], v[186:189], v[34:37]
	v_mfma_f32_16x16x32_bf16 v[26:29], v[142:145], v[212:215], v[26:29]
	v_mfma_f32_16x16x32_bf16 v[18:21], v[150:153], v[212:215], v[18:21]
	v_mfma_f32_16x16x32_bf16 v[10:13], v[142:145], v[220:223], v[10:13]
	v_mfma_f32_16x16x32_bf16 v[2:5], v[150:153], v[220:223], v[2:5]
	v_mfma_f32_16x16x32_bf16 v[58:61], v[146:149], v[182:185], v[58:61]
	v_mfma_f32_16x16x32_bf16 v[50:53], v[154:157], v[182:185], v[50:53]
	v_mfma_f32_16x16x32_bf16 v[42:45], v[146:149], v[208:211], v[42:45]
	v_mfma_f32_16x16x32_bf16 v[34:37], v[154:157], v[208:211], v[34:37]
	v_mfma_f32_16x16x32_bf16 v[26:29], v[146:149], v[216:219], v[26:29]
	v_mfma_f32_16x16x32_bf16 v[18:21], v[154:157], v[216:219], v[18:21]
	v_mfma_f32_16x16x32_bf16 v[10:13], v[146:149], v[224:227], v[10:13]
	v_mfma_f32_16x16x32_bf16 v[2:5], v[154:157], v[224:227], v[2:5]
	v_mfma_f32_16x16x32_bf16 v[62:65], v[162:165], v[178:181], v[62:65]
	v_mfma_f32_16x16x32_bf16 v[54:57], v[170:173], v[178:181], v[54:57]
	v_mfma_f32_16x16x32_bf16 v[46:49], v[162:165], v[186:189], v[46:49]
	v_mfma_f32_16x16x32_bf16 v[38:41], v[170:173], v[186:189], v[38:41]
	v_mfma_f32_16x16x32_bf16 v[30:33], v[162:165], v[212:215], v[30:33]
	v_mfma_f32_16x16x32_bf16 v[22:25], v[170:173], v[212:215], v[22:25]
	v_mfma_f32_16x16x32_bf16 v[14:17], v[162:165], v[220:223], v[14:17]
	v_mfma_f32_16x16x32_bf16 v[6:9], v[170:173], v[220:223], v[6:9]
	v_mfma_f32_16x16x32_bf16 v[62:65], v[166:169], v[182:185], v[62:65]
	v_mfma_f32_16x16x32_bf16 v[54:57], v[174:177], v[182:185], v[54:57]
	v_mfma_f32_16x16x32_bf16 v[46:49], v[166:169], v[208:211], v[46:49]
	v_mfma_f32_16x16x32_bf16 v[38:41], v[174:177], v[208:211], v[38:41]
	v_mfma_f32_16x16x32_bf16 v[30:33], v[166:169], v[216:219], v[30:33]
	v_mfma_f32_16x16x32_bf16 v[22:25], v[174:177], v[216:219], v[22:25]
	v_mfma_f32_16x16x32_bf16 v[14:17], v[166:169], v[224:227], v[14:17]
	v_mfma_f32_16x16x32_bf16 v[6:9], v[174:177], v[224:227], v[6:9]
	s_barrier
; #define PG8_STAGE(bufoff, gbase, voff) do { _Pragma("unroll") for (int _i = 0; _i < 2; ++_i) \
;         __builtin_amdgcn_global_load_lds((const unsigned*)((const char*)(gbase) + (voff)[_i]), (LAS unsigned*)(lds + (bufoff) + ldsw + _i * 8192), 16, 0, 0); } while (0)
; #define PG8_LDA(dst, b, h) do { _Pragma("unroll") for (int m = 0; m < 4; ++m) _Pragma("unroll") for (int k = 0; k < 2; ++k) dst[m][k] = *(const LAS bf16x8*)(lds + PG8_SA(b, h) + aoff + m * 2048 + k * 1024); } while (0)
; #define PG8_LDB(dst, b, h) do { _Pragma("unroll") for (int n = 0; n < 2; ++n) _Pragma("unroll") for (int k = 0; k < 2; ++k) dst[n][k] = *(const LAS bf16x8*)(lds + PG8_SB(b, h) + boff + n * 2048 + k * 1024); } while (0)
; #define PG8_MMA(ai, bj, At, Bt) do { __builtin_amdgcn_s_setprio(1); _Pragma("unroll") for (int m = 0; m < 4; ++m) _Pragma("unroll") for (int n = 0; n < 2; ++n) _Pragma("unroll") for (int k = 0; k < 2; ++k) \
;         acc[ai][bj][m][n] = __builtin_amdgcn_mfma_f32_16x16x32_bf16(Bt[n][k], At[m][k], acc[ai][bj][m][n], 0, 0, 0); __builtin_amdgcn_s_setprio(0); } while (0)
; #define PG8_WAIT_V(n) asm volatile("s_waitcnt vmcnt(" #n ")" ::: "memory")
; #define PG8_WAIT_L(n) asm volatile("s_waitcnt lgkmcnt(" #n ")" ::: "memory")
; #define PG8_BAR __builtin_amdgcn_s_barrier()
; #define PG8_SCHED __builtin_amdgcn_sched_barrier(0)
; template <class Epi, class Sched>
; __device__ __forceinline__ void gemm_phase(LAS unsigned char* lds, const Gemm g, const Sched& S, const Epi& E) {
;     ...
;             PG8_LDB(B0, 1, 0); PG8_LDB(B1, 1, 1); PG8_SCHED; PG8_LDA(At, 1, 0); PG8_STAGE(PG8_SA(0, 1), a2 + hsA, voffA);
;             PG8_WAIT_V(8); PG8_WAIT_L(0); PG8_BAR; PG8_MMA(0, 0, At, B0); PG8_MMA(0, 1, At, B1); PG8_BAR; PG8_SCHED;
	s_add_i32 s9, 0, 0x18000
	s_add_i32 s74, 0, 0x1c000
	v_add_u32_e32 v154, s9, v160
	v_add_u32_e32 v174, s74, v160
	ds_read_b128 v[142:145], v154
	ds_read_b128 v[146:149], v154 offset:1024
	ds_read_b128 v[150:153], v154 offset:2048
	ds_read_b128 v[154:157], v154 offset:3072
	ds_read_b128 v[162:165], v174
	ds_read_b128 v[166:169], v174 offset:1024
	ds_read_b128 v[170:173], v174 offset:2048
	ds_read_b128 v[174:177], v174 offset:3072
	s_add_u32 s20, s84, 0x40000
	s_addc_u32 s21, s85, 0
	s_mov_b32 m0, s52
	v_lshl_add_u64 v[238:239], s[20:21], 0, v[134:135]
	ds_read_b128 v[178:181], v161 offset:32768
	ds_read_b128 v[182:185], v161 offset:33792
	ds_read_b128 v[186:189], v161 offset:34816
	ds_read_b128 v[208:211], v161 offset:35840
	ds_read_b128 v[212:215], v161 offset:36864
	ds_read_b128 v[216:219], v161 offset:37888
	ds_read_b128 v[220:223], v161 offset:38912
	ds_read_b128 v[224:227], v161 offset:39936
	global_load_lds_dwordx4 v[238:239], off
	v_lshl_add_u64 v[238:239], s[20:21], 0, v[132:133]
	s_mov_b32 m0, s56
	s_nop 0
	global_load_lds_dwordx4 v[238:239], off
	s_waitcnt vmcnt(8)
	s_waitcnt lgkmcnt(0)
	s_barrier
	s_waitcnt lgkmcnt(0)
	v_mfma_f32_16x16x32_bf16 v[122:125], v[142:145], v[178:181], v[122:125]
	v_mfma_f32_16x16x32_bf16 v[114:117], v[150:153], v[178:181], v[114:117]
	v_mfma_f32_16x16x32_bf16 v[106:109], v[142:145], v[186:189], v[106:109]
	v_mfma_f32_16x16x32_bf16 v[98:101], v[150:153], v[186:189], v[98:101]
	v_mfma_f32_16x16x32_bf16 v[90:93], v[142:145], v[212:215], v[90:93]
	v_mfma_f32_16x16x32_bf16 v[82:85], v[150:153], v[212:215], v[82:85]
	v_mfma_f32_16x16x32_bf16 v[74:77], v[142:145], v[220:223], v[74:77]
	v_mfma_f32_16x16x32_bf16 v[66:69], v[150:153], v[220:223], v[66:69]
	v_mfma_f32_16x16x32_bf16 v[122:125], v[146:149], v[182:185], v[122:125]
	v_mfma_f32_16x16x32_bf16 v[114:117], v[154:157], v[182:185], v[114:117]
	v_mfma_f32_16x16x32_bf16 v[106:109], v[146:149], v[208:211], v[106:109]
	v_mfma_f32_16x16x32_bf16 v[98:101], v[154:157], v[208:211], v[98:101]
	v_mfma_f32_16x16x32_bf16 v[90:93], v[146:149], v[216:219], v[90:93]
	v_mfma_f32_16x16x32_bf16 v[82:85], v[154:157], v[216:219], v[82:85]
	v_mfma_f32_16x16x32_bf16 v[74:77], v[146:149], v[224:227], v[74:77]
	v_mfma_f32_16x16x32_bf16 v[66:69], v[154:157], v[224:227], v[66:69]
	v_mfma_f32_16x16x32_bf16 v[126:129], v[162:165], v[178:181], v[126:129]
	v_mfma_f32_16x16x32_bf16 v[118:121], v[170:173], v[178:181], v[118:121]
	v_mfma_f32_16x16x32_bf16 v[110:113], v[162:165], v[186:189], v[110:113]
	v_mfma_f32_16x16x32_bf16 v[102:105], v[170:173], v[186:189], v[102:105]
	v_mfma_f32_16x16x32_bf16 v[94:97], v[162:165], v[212:215], v[94:97]
	v_mfma_f32_16x16x32_bf16 v[86:89], v[170:173], v[212:215], v[86:89]
	v_mfma_f32_16x16x32_bf16 v[78:81], v[162:165], v[220:223], v[78:81]
	v_mfma_f32_16x16x32_bf16 v[70:73], v[170:173], v[220:223], v[70:73]
	v_mfma_f32_16x16x32_bf16 v[126:129], v[166:169], v[182:185], v[126:129]
	v_mfma_f32_16x16x32_bf16 v[118:121], v[174:177], v[182:185], v[118:121]
	v_mfma_f32_16x16x32_bf16 v[110:113], v[166:169], v[208:211], v[110:113]
	v_mfma_f32_16x16x32_bf16 v[102:105], v[174:177], v[208:211], v[102:105]
	v_mfma_f32_16x16x32_bf16 v[94:97], v[166:169], v[216:219], v[94:97]
	v_mfma_f32_16x16x32_bf16 v[86:89], v[174:177], v[216:219], v[86:89]
	v_mfma_f32_16x16x32_bf16 v[78:81], v[166:169], v[224:227], v[78:81]
	v_mfma_f32_16x16x32_bf16 v[70:73], v[174:177], v[224:227], v[70:73]
	s_barrier
; #define PG8_STAGE(bufoff, gbase, voff) do { _Pragma("unroll") for (int _i = 0; _i < 2; ++_i) \
;         __builtin_amdgcn_global_load_lds((const unsigned*)((const char*)(gbase) + (voff)[_i]), (LAS unsigned*)(lds + (bufoff) + ldsw + _i * 8192), 16, 0, 0); } while (0)
; #define PG8_LDA(dst, b, h) do { _Pragma("unroll") for (int m = 0; m < 4; ++m) _Pragma("unroll") for (int k = 0; k < 2; ++k) dst[m][k] = *(const LAS bf16x8*)(lds + PG8_SA(b, h) + aoff + m * 2048 + k * 1024); } while (0)
; #define PG8_MMA(ai, bj, At, Bt) do { __builtin_amdgcn_s_setprio(1); _Pragma("unroll") for (int m = 0; m < 4; ++m) _Pragma("unroll") for (int n = 0; n < 2; ++n) _Pragma("unroll") for (int k = 0; k < 2; ++k) \
;         acc[ai][bj][m][n] = __builtin_amdgcn_mfma_f32_16x16x32_bf16(Bt[n][k], At[m][k], acc[ai][bj][m][n], 0, 0, 0); __builtin_amdgcn_s_setprio(0); } while (0)
; #define PG8_WAIT_V(n) asm volatile("s_waitcnt vmcnt(" #n ")" ::: "memory")
; #define PG8_WAIT_L(n) asm volatile("s_waitcnt lgkmcnt(" #n ")" ::: "memory")
; #define PG8_BAR __builtin_amdgcn_s_barrier()
; #define PG8_SCHED __builtin_amdgcn_sched_barrier(0)
; template <class Epi, class Sched>
; __device__ __forceinline__ void gemm_phase(LAS unsigned char* lds, const Gemm g, const Sched& S, const Epi& E) {
;     ...
;             PG8_LDA(At, 1, 1); PG8_STAGE(PG8_SB(1, 0), b3, voffB); PG8_STAGE(PG8_SB(1, 1), b3 + hsB, voffB); PG8_STAGE(PG8_SA(1, 0), a3, voffA);
;             PG8_WAIT_V(8); PG8_WAIT_L(0); PG8_BAR; PG8_MMA(1, 0, At, B0); PG8_MMA(1, 1, At, B1); PG8_BAR; PG8_SCHED;
;         }
	s_add_i32 s9, s9, s12
	v_lshl_add_u64 v[190:191], v[190:191], 0, s[18:19]
	s_mov_b32 m0, s9
	ds_read_b128 v[178:181], v161 offset:49152
	ds_read_b128 v[182:185], v161 offset:50176
	ds_read_b128 v[186:189], v161 offset:51200
	ds_read_b128 v[208:211], v161 offset:52224
	ds_read_b128 v[212:215], v161 offset:53248
	ds_read_b128 v[216:219], v161 offset:54272
	ds_read_b128 v[220:223], v161 offset:55296
	ds_read_b128 v[224:227], v161 offset:56320
	global_load_lds_dwordx4 v[190:191], off
	s_add_i32 m0, s9, 0x2000
	s_add_u32 s20, s38, 0x40080
	v_lshl_add_u64 v[190:191], v[228:229], 0, s[18:19]
	s_addc_u32 s21, s39, 0
	s_add_i32 s9, s74, s12
	global_load_lds_dwordx4 v[190:191], off
	v_lshl_add_u64 v[190:191], s[20:21], 0, v[0:1]
	s_mov_b32 m0, s9
	s_nop 0
	global_load_lds_dwordx4 v[190:191], off
	v_lshl_add_u64 v[190:191], s[20:21], 0, v[130:131]
	s_add_i32 m0, s9, 0x2000
	s_nop 0
	global_load_lds_dwordx4 v[190:191], off
	v_lshl_add_u64 v[190:191], v[230:231], 0, s[18:19]
	s_mov_b32 m0, s78
	s_nop 0
	global_load_lds_dwordx4 v[190:191], off
	v_lshl_add_u64 v[190:191], v[232:233], 0, s[18:19]
	s_mov_b32 m0, s80
	s_nop 0
	global_load_lds_dwordx4 v[190:191], off
	s_waitcnt vmcnt(8)
	s_waitcnt lgkmcnt(0)
	s_barrier
	s_waitcnt lgkmcnt(0)
	v_mfma_f32_16x16x32_bf16 v[58:61], v[142:145], v[178:181], v[58:61]
	v_mfma_f32_16x16x32_bf16 v[50:53], v[150:153], v[178:181], v[50:53]
	v_mfma_f32_16x16x32_bf16 v[42:45], v[142:145], v[186:189], v[42:45]
	v_mfma_f32_16x16x32_bf16 v[34:37], v[150:153], v[186:189], v[34:37]
	v_mfma_f32_16x16x32_bf16 v[26:29], v[142:145], v[212:215], v[26:29]
	v_mfma_f32_16x16x32_bf16 v[18:21], v[150:153], v[212:215], v[18:21]
	v_mfma_f32_16x16x32_bf16 v[10:13], v[142:145], v[220:223], v[10:13]
	v_mfma_f32_16x16x32_bf16 v[2:5], v[150:153], v[220:223], v[2:5]
	v_mfma_f32_16x16x32_bf16 v[58:61], v[146:149], v[182:185], v[58:61]
	v_mfma_f32_16x16x32_bf16 v[50:53], v[154:157], v[182:185], v[50:53]
	v_mfma_f32_16x16x32_bf16 v[42:45], v[146:149], v[208:211], v[42:45]
	v_mfma_f32_16x16x32_bf16 v[34:37], v[154:157], v[208:211], v[34:37]
	v_mfma_f32_16x16x32_bf16 v[26:29], v[146:149], v[216:219], v[26:29]
	v_mfma_f32_16x16x32_bf16 v[18:21], v[154:157], v[216:219], v[18:21]
	v_mfma_f32_16x16x32_bf16 v[10:13], v[146:149], v[224:227], v[10:13]
	v_mfma_f32_16x16x32_bf16 v[2:5], v[154:157], v[224:227], v[2:5]
	v_mfma_f32_16x16x32_bf16 v[62:65], v[162:165], v[178:181], v[62:65]
	v_mfma_f32_16x16x32_bf16 v[54:57], v[170:173], v[178:181], v[54:57]
	v_mfma_f32_16x16x32_bf16 v[46:49], v[162:165], v[186:189], v[46:49]
	v_mfma_f32_16x16x32_bf16 v[38:41], v[170:173], v[186:189], v[38:41]
	v_mfma_f32_16x16x32_bf16 v[30:33], v[162:165], v[212:215], v[30:33]
	v_mfma_f32_16x16x32_bf16 v[22:25], v[170:173], v[212:215], v[22:25]
	v_mfma_f32_16x16x32_bf16 v[14:17], v[162:165], v[220:223], v[14:17]
	v_mfma_f32_16x16x32_bf16 v[6:9], v[170:173], v[220:223], v[6:9]
	v_mfma_f32_16x16x32_bf16 v[62:65], v[166:169], v[182:185], v[62:65]
	v_mfma_f32_16x16x32_bf16 v[54:57], v[174:177], v[182:185], v[54:57]
	v_mfma_f32_16x16x32_bf16 v[46:49], v[166:169], v[208:211], v[46:49]
	v_mfma_f32_16x16x32_bf16 v[38:41], v[174:177], v[208:211], v[38:41]
	v_mfma_f32_16x16x32_bf16 v[30:33], v[166:169], v[216:219], v[30:33]
	v_mfma_f32_16x16x32_bf16 v[22:25], v[174:177], v[216:219], v[22:25]
	v_mfma_f32_16x16x32_bf16 v[14:17], v[166:169], v[224:227], v[14:17]
	v_mfma_f32_16x16x32_bf16 v[6:9], v[174:177], v[224:227], v[6:9]
	s_barrier
	s_add_u32 s0, s0, 0x100
	s_addc_u32 s1, s1, 0
	s_add_u32 vcc_hi, vcc_hi, 0x100
	s_addc_u32 s8, s8, 0
	s_cmp_ge_i32 s96, s57
	s_mov_b32 s9, s96
	s_cbranch_scc0 .LBB0_222
	s_setprio 0
	v_readlane_b32 s96, v250, 43
	s_mov_b64 s[74:75], s[22:23]

; #define PG8_STAGE(bufoff, gbase, voff) do { _Pragma("unroll") for (int _i = 0; _i < 2; ++_i) \
;         __builtin_amdgcn_global_load_lds((const unsigned*)((const char*)(gbase) + (voff)[_i]), (LAS unsigned*)(lds + (bufoff) + ldsw + _i * 8192), 16, 0, 0); } while (0)
; #define PG8_LDA(dst, b, h) do { _Pragma("unroll") for (int m = 0; m < 4; ++m) _Pragma("unroll") for (int k = 0; k < 2; ++k) dst[m][k] = *(const LAS bf16x8*)(lds + PG8_SA(b, h) + aoff + m * 2048 + k * 1024); } while (0)
; #define PG8_LDB(dst, b, h) do { _Pragma("unroll") for (int n = 0; n < 2; ++n) _Pragma("unroll") for (int k = 0; k < 2; ++k) dst[n][k] = *(const LAS bf16x8*)(lds + PG8_SB(b, h) + boff + n * 2048 + k * 1024); } while (0)
; #define PG8_WAIT_V(n) asm volatile("s_waitcnt vmcnt(" #n ")" ::: "memory")
; #define PG8_WAIT_L(n) asm volatile("s_waitcnt lgkmcnt(" #n ")" ::: "memory")
; #define PG8_BAR __builtin_amdgcn_s_barrier()
; #define PG8_SCHED __builtin_amdgcn_sched_barrier(0)
; template <class Epi, class Sched>
; __device__ __forceinline__ void gemm_phase(LAS unsigned char* lds, const Gemm g, const Sched& S, const Epi& E) {
;     ...
; #pragma unroll
;     for (int a = 0; a < 2; ++a)
; #pragma unroll
;         for (int b = 0; b < 2; ++b)
; #pragma unroll
;             for (int m = 0; m < 4; ++m)
; #pragma unroll
;                 for (int n = 0; n < 2; ++n) acc[a][b][m][n] = (f32x4){0.f, 0.f, 0.f, 0.f};
;     ...
;         const bool has_next = S.next(ui + 1, nxt);
;         const char* nA = has_next ? (const char*)g.A + nxt.offA : cA; const char* nB = has_next ? (const char*)g.Bt + nxt.offB : cB;
;         for (int t = 0; t < nt; t += 2) {
;             const bool last = (t == nt - 2);
;             const char* a1 = cA + (size_t)(t + 1) * kstep;
;             const char* a2 = last ? nA : cA + (size_t)(t + 2) * kstep; const char* b2 = last ? nB : cB + (size_t)(t + 2) * kstep;
;             const char* a3 = a2 + kstep; const char* b3 = b2 + kstep;
;             if constexpr (Epi::MIDK) { if (t == (nt >> 1)) { int fr_ = fr, fq_ = fq; asm volatile("" : "+v"(fr_), "+v"(fq_)); E.mid(acc, cur, wr, wc, fr_, fq_); } }
;             PG8_LDB(B0, 0, 0); PG8_LDB(B1, 0, 1); PG8_SCHED; PG8_LDA(At, 0, 0); PG8_STAGE(PG8_SA(1, 1), a1 + hsA, voffA);
;             PG8_WAIT_V(8); PG8_WAIT_L(0); PG8_BAR; PG8_MMA(0, 0, At, B0); PG8_MMA(0, 1, At, B1); PG8_BAR; PG8_SCHED;
.LBB0_296:
	s_add_u32 s76, s66, s50
	s_addc_u32 s77, s67, s51
	v_readlane_b32 s22, v250, 44
	s_add_u32 s34, s73, s0
	v_readlane_b32 s23, v250, 45
	s_addc_u32 s35, s74, s1
	s_andn2_b64 vcc, exec, s[22:23]
	s_cbranch_vccnz .Lzc_8429
	s_and_b64 s[38:39], s[36:37], exec
	s_mov_b32 s22, s73
	s_cselect_b32 s43, s77, s9
	s_cselect_b32 s73, s76, s8
	s_cselect_b32 s82, s35, s21
	s_cselect_b32 s83, s34, s20
	s_add_u32 s84, s20, 0x100
	v_mov_b32_e32 v2, 0
	s_mov_b32 vcc_lo, s75
	s_mov_b32 s23, s74
	s_addc_u32 s85, s21, 0
	s_mov_b32 s38, 0
	s_waitcnt lgkmcnt(0)
	v_mov_b32_e32 v3, v2
	v_mov_b32_e32 v4, v2
	v_mov_b32_e32 v5, v2
	v_mov_b32_e32 v6, v2
	v_mov_b32_e32 v7, v2
	v_mov_b32_e32 v8, v2
	v_mov_b32_e32 v9, v2
	v_mov_b32_e32 v10, v2
	v_mov_b32_e32 v11, v2
	v_mov_b32_e32 v12, v2
	v_mov_b32_e32 v13, v2
	v_mov_b32_e32 v14, v2
	v_mov_b32_e32 v15, v2
	v_mov_b32_e32 v16, v2
	v_mov_b32_e32 v17, v2
	v_mov_b32_e32 v22, v2
	v_mov_b32_e32 v23, v2
	v_mov_b32_e32 v24, v2
	v_mov_b32_e32 v25, v2
	v_mov_b32_e32 v30, v2
	v_mov_b32_e32 v31, v2
	v_mov_b32_e32 v32, v2
	v_mov_b32_e32 v33, v2
	v_mov_b32_e32 v38, v2
	v_mov_b32_e32 v39, v2
	v_mov_b32_e32 v40, v2
	v_mov_b32_e32 v41, v2
	v_mov_b32_e32 v46, v2
	v_mov_b32_e32 v47, v2
	v_mov_b32_e32 v48, v2
	v_mov_b32_e32 v49, v2
	v_mov_b32_e32 v18, v2
	v_mov_b32_e32 v19, v2
	v_mov_b32_e32 v20, v2
	v_mov_b32_e32 v21, v2
	v_mov_b32_e32 v26, v2
	v_mov_b32_e32 v27, v2
	v_mov_b32_e32 v28, v2
	v_mov_b32_e32 v29, v2
	v_mov_b32_e32 v34, v2
	v_mov_b32_e32 v35, v2
	v_mov_b32_e32 v36, v2
	v_mov_b32_e32 v37, v2
	v_mov_b32_e32 v42, v2
	v_mov_b32_e32 v43, v2
	v_mov_b32_e32 v44, v2
	v_mov_b32_e32 v45, v2
	v_mov_b32_e32 v50, v2
	v_mov_b32_e32 v51, v2
	v_mov_b32_e32 v52, v2
	v_mov_b32_e32 v53, v2
	v_mov_b32_e32 v54, v2
	v_mov_b32_e32 v55, v2
	v_mov_b32_e32 v56, v2
	v_mov_b32_e32 v57, v2
	v_mov_b32_e32 v58, v2
	v_mov_b32_e32 v59, v2
	v_mov_b32_e32 v60, v2
	v_mov_b32_e32 v61, v2
	v_mov_b32_e32 v62, v2
	v_mov_b32_e32 v63, v2
	v_mov_b32_e32 v64, v2
	v_mov_b32_e32 v65, v2
	v_mov_b32_e32 v66, v2
	v_mov_b32_e32 v67, v2
	v_mov_b32_e32 v68, v2
	v_mov_b32_e32 v69, v2
	v_mov_b32_e32 v70, v2
	v_mov_b32_e32 v71, v2
	v_mov_b32_e32 v72, v2
	v_mov_b32_e32 v73, v2
	v_mov_b32_e32 v74, v2
	v_mov_b32_e32 v75, v2
	v_mov_b32_e32 v76, v2
	v_mov_b32_e32 v77, v2
	v_mov_b32_e32 v78, v2
	v_mov_b32_e32 v79, v2
	v_mov_b32_e32 v80, v2
	v_mov_b32_e32 v81, v2
	v_mov_b32_e32 v86, v2
	v_mov_b32_e32 v87, v2
	v_mov_b32_e32 v88, v2
	v_mov_b32_e32 v89, v2
	v_mov_b32_e32 v94, v2
	v_mov_b32_e32 v95, v2
	v_mov_b32_e32 v96, v2
	v_mov_b32_e32 v97, v2
	v_mov_b32_e32 v102, v2
	v_mov_b32_e32 v103, v2
	v_mov_b32_e32 v104, v2
	v_mov_b32_e32 v105, v2
	v_mov_b32_e32 v110, v2
	v_mov_b32_e32 v111, v2
	v_mov_b32_e32 v112, v2
	v_mov_b32_e32 v113, v2
	v_mov_b32_e32 v82, v2
	v_mov_b32_e32 v83, v2
	v_mov_b32_e32 v84, v2
	v_mov_b32_e32 v85, v2
	v_mov_b32_e32 v90, v2
	v_mov_b32_e32 v91, v2
	v_mov_b32_e32 v92, v2
	v_mov_b32_e32 v93, v2
	v_mov_b32_e32 v98, v2
	v_mov_b32_e32 v99, v2
	v_mov_b32_e32 v100, v2
	v_mov_b32_e32 v101, v2
	v_mov_b32_e32 v106, v2
	v_mov_b32_e32 v107, v2
	v_mov_b32_e32 v108, v2
	v_mov_b32_e32 v109, v2
	v_mov_b32_e32 v114, v2
	v_mov_b32_e32 v115, v2
	v_mov_b32_e32 v116, v2
	v_mov_b32_e32 v117, v2
	v_mov_b32_e32 v118, v2
	v_mov_b32_e32 v119, v2
	v_mov_b32_e32 v120, v2
	v_mov_b32_e32 v121, v2
	v_mov_b32_e32 v122, v2
	v_mov_b32_e32 v123, v2
	v_mov_b32_e32 v124, v2
	v_mov_b32_e32 v125, v2
	v_mov_b32_e32 v126, v2
	v_mov_b32_e32 v127, v2
	v_mov_b32_e32 v128, v2
	v_mov_b32_e32 v129, v2
	v_readfirstlane_b32 s96, v193
	s_lshr_b32 s96, s96, 8
	s_cmp_eq_u32 s96, 1
	s_cbranch_scc0 .Lnp_298
	s_setprio 1
.Lnp_298:
.LBB0_298:
	s_add_i32 s96, s38, 2
	s_add_u32 s20, s8, 0x100
	s_addc_u32 s21, s9, 0
	s_add_i32 s74, 0, 0x10000
	s_cmp_eq_u32 s26, s38
	s_cselect_b32 s41, s43, s21
	s_cselect_b32 s40, s73, s20
	s_cselect_b32 s39, s82, s85
	s_cselect_b32 s38, s83, s84
	s_add_i32 s75, 0, 0x14000
	v_add_u32_e32 v152, s74, v206
	v_add_u32_e32 v168, s75, v206
	ds_read_b128 v[140:143], v152
	ds_read_b128 v[144:147], v152 offset:1024
	ds_read_b128 v[148:151], v152 offset:2048
	ds_read_b128 v[152:155], v152 offset:3072
	ds_read_b128 v[156:159], v168
	ds_read_b128 v[160:163], v168 offset:1024
	ds_read_b128 v[164:167], v168 offset:2048
	ds_read_b128 v[168:171], v168 offset:3072
	v_lshl_add_u64 v[208:209], s[8:9], 0, v[136:137]
	s_add_i32 m0, s30, 0xc000
	ds_read_b128 v[172:175], v210
	ds_read_b128 v[176:179], v210 offset:1024
	ds_read_b128 v[180:183], v210 offset:2048
	ds_read_b128 v[184:187], v210 offset:3072
	ds_read_b128 v[188:191], v210 offset:4096
	ds_read_b128 v[212:215], v210 offset:5120
	ds_read_b128 v[216:219], v210 offset:6144
	ds_read_b128 v[220:223], v210 offset:7168
	global_load_lds_dwordx4 v[208:209], off
	v_lshl_add_u64 v[208:209], s[8:9], 0, v[138:139]
	s_add_i32 m0, s30, 0xe000
	s_nop 0
	global_load_lds_dwordx4 v[208:209], off
	s_waitcnt vmcnt(8)
	s_waitcnt lgkmcnt(0)
	s_barrier
; #define PG8_STAGE(bufoff, gbase, voff) do { _Pragma("unroll") for (int _i = 0; _i < 2; ++_i) \
;         __builtin_amdgcn_global_load_lds((const unsigned*)((const char*)(gbase) + (voff)[_i]), (LAS unsigned*)(lds + (bufoff) + ldsw + _i * 8192), 16, 0, 0); } while (0)
; #define PG8_LDA(dst, b, h) do { _Pragma("unroll") for (int m = 0; m < 4; ++m) _Pragma("unroll") for (int k = 0; k < 2; ++k) dst[m][k] = *(const LAS bf16x8*)(lds + PG8_SA(b, h) + aoff + m * 2048 + k * 1024); } while (0)
; #define PG8_MMA(ai, bj, At, Bt) do { __builtin_amdgcn_s_setprio(1); _Pragma("unroll") for (int m = 0; m < 4; ++m) _Pragma("unroll") for (int n = 0; n < 2; ++n) _Pragma("unroll") for (int k = 0; k < 2; ++k) \
;         acc[ai][bj][m][n] = __builtin_amdgcn_mfma_f32_16x16x32_bf16(Bt[n][k], At[m][k], acc[ai][bj][m][n], 0, 0, 0); __builtin_amdgcn_s_setprio(0); } while (0)
; #define PG8_WAIT_V(n) asm volatile("s_waitcnt vmcnt(" #n ")" ::: "memory")
; #define PG8_WAIT_L(n) asm volatile("s_waitcnt lgkmcnt(" #n ")" ::: "memory")
; #define PG8_BAR __builtin_amdgcn_s_barrier()
; #define PG8_SCHED __builtin_amdgcn_sched_barrier(0)
; template <class Epi, class Sched>
; __device__ __forceinline__ void gemm_phase(LAS unsigned char* lds, const Gemm g, const Sched& S, const Epi& E) {
;     ...
;             PG8_WAIT_V(8); PG8_WAIT_L(0); PG8_BAR; PG8_MMA(0, 0, At, B0); PG8_MMA(0, 1, At, B1); PG8_BAR; PG8_SCHED;
;             PG8_LDA(At, 0, 1); PG8_STAGE(PG8_SB(0, 0), b2, voffB); PG8_STAGE(PG8_SB(0, 1), b2 + hsB, voffB); PG8_STAGE(PG8_SA(0, 0), a2, voffA);
;             PG8_WAIT_V(8); PG8_WAIT_L(0); PG8_BAR; PG8_MMA(1, 0, At, B0); PG8_MMA(1, 1, At, B1); PG8_BAR; PG8_SCHED;
	s_waitcnt lgkmcnt(0)
	v_mfma_f32_16x16x32_bf16 v[126:129], v[140:143], v[172:175], v[126:129]
	v_mfma_f32_16x16x32_bf16 v[122:125], v[148:151], v[172:175], v[122:125]
	v_mfma_f32_16x16x32_bf16 v[118:121], v[140:143], v[180:183], v[118:121]
	v_mfma_f32_16x16x32_bf16 v[114:117], v[148:151], v[180:183], v[114:117]
	v_mfma_f32_16x16x32_bf16 v[106:109], v[140:143], v[188:191], v[106:109]
	v_mfma_f32_16x16x32_bf16 v[98:101], v[148:151], v[188:191], v[98:101]
	v_mfma_f32_16x16x32_bf16 v[90:93], v[140:143], v[216:219], v[90:93]
	v_mfma_f32_16x16x32_bf16 v[82:85], v[148:151], v[216:219], v[82:85]
	v_mfma_f32_16x16x32_bf16 v[126:129], v[144:147], v[176:179], v[126:129]
	v_mfma_f32_16x16x32_bf16 v[122:125], v[152:155], v[176:179], v[122:125]
	v_mfma_f32_16x16x32_bf16 v[118:121], v[144:147], v[184:187], v[118:121]
	v_mfma_f32_16x16x32_bf16 v[114:117], v[152:155], v[184:187], v[114:117]
	v_mfma_f32_16x16x32_bf16 v[106:109], v[144:147], v[212:215], v[106:109]
	v_mfma_f32_16x16x32_bf16 v[98:101], v[152:155], v[212:215], v[98:101]
	v_mfma_f32_16x16x32_bf16 v[90:93], v[144:147], v[220:223], v[90:93]
	v_mfma_f32_16x16x32_bf16 v[82:85], v[152:155], v[220:223], v[82:85]
	v_mfma_f32_16x16x32_bf16 v[110:113], v[156:159], v[172:175], v[110:113]
	v_mfma_f32_16x16x32_bf16 v[102:105], v[164:167], v[172:175], v[102:105]
	v_mfma_f32_16x16x32_bf16 v[94:97], v[156:159], v[180:183], v[94:97]
	v_mfma_f32_16x16x32_bf16 v[86:89], v[164:167], v[180:183], v[86:89]
	v_mfma_f32_16x16x32_bf16 v[78:81], v[156:159], v[188:191], v[78:81]
	v_mfma_f32_16x16x32_bf16 v[74:77], v[164:167], v[188:191], v[74:77]
	v_mfma_f32_16x16x32_bf16 v[70:73], v[156:159], v[216:219], v[70:73]
	v_mfma_f32_16x16x32_bf16 v[66:69], v[164:167], v[216:219], v[66:69]
	v_mfma_f32_16x16x32_bf16 v[110:113], v[160:163], v[176:179], v[110:113]
	v_mfma_f32_16x16x32_bf16 v[102:105], v[168:171], v[176:179], v[102:105]
	v_mfma_f32_16x16x32_bf16 v[94:97], v[160:163], v[184:187], v[94:97]
	v_mfma_f32_16x16x32_bf16 v[86:89], v[168:171], v[184:187], v[86:89]
	v_mfma_f32_16x16x32_bf16 v[78:81], v[160:163], v[212:215], v[78:81]
	v_mfma_f32_16x16x32_bf16 v[74:77], v[168:171], v[212:215], v[74:77]
	v_mfma_f32_16x16x32_bf16 v[70:73], v[160:163], v[220:223], v[70:73]
	v_mfma_f32_16x16x32_bf16 v[66:69], v[168:171], v[220:223], v[66:69]
	s_barrier
	s_add_i32 s8, s74, s24
	v_lshl_add_u64 v[208:209], s[38:39], 0, v[0:1]
	s_mov_b32 m0, s8
	ds_read_b128 v[172:175], v210 offset:16384
	ds_read_b128 v[176:179], v210 offset:17408
	ds_read_b128 v[180:183], v210 offset:18432
	ds_read_b128 v[184:187], v210 offset:19456
	ds_read_b128 v[188:191], v210 offset:20480
	ds_read_b128 v[212:215], v210 offset:21504
	ds_read_b128 v[216:219], v210 offset:22528
	ds_read_b128 v[220:223], v210 offset:23552
	global_load_lds_dwordx4 v[208:209], off
	s_add_i32 m0, s8, 0x2000
	s_add_u32 s8, s38, 0xb0000
	v_lshl_add_u64 v[224:225], s[38:39], 0, v[130:131]
	s_addc_u32 s9, s39, 0
	s_add_i32 s74, s75, s24
	global_load_lds_dwordx4 v[224:225], off
	v_lshl_add_u64 v[226:227], s[8:9], 0, v[0:1]
	s_mov_b32 m0, s74
	v_lshl_add_u64 v[228:229], s[40:41], 0, v[132:133]
	global_load_lds_dwordx4 v[226:227], off
	v_lshl_add_u64 v[226:227], s[8:9], 0, v[130:131]
	s_add_i32 m0, s74, 0x2000
	s_nop 0
	global_load_lds_dwordx4 v[226:227], off
	v_lshl_add_u64 v[226:227], s[40:41], 0, v[134:135]
	s_mov_b32 m0, s30
	s_nop 0
	global_load_lds_dwordx4 v[226:227], off
	s_mov_b32 m0, s52
	s_nop 0
	global_load_lds_dwordx4 v[228:229], off
	s_waitcnt vmcnt(8)
	s_waitcnt lgkmcnt(0)
	s_barrier
	s_waitcnt lgkmcnt(0)
	v_mfma_f32_16x16x32_bf16 v[62:65], v[140:143], v[172:175], v[62:65]
	v_mfma_f32_16x16x32_bf16 v[58:61], v[148:151], v[172:175], v[58:61]
	v_mfma_f32_16x16x32_bf16 v[54:57], v[140:143], v[180:183], v[54:57]
	v_mfma_f32_16x16x32_bf16 v[50:53], v[148:151], v[180:183], v[50:53]
	v_mfma_f32_16x16x32_bf16 v[42:45], v[140:143], v[188:191], v[42:45]
	v_mfma_f32_16x16x32_bf16 v[34:37], v[148:151], v[188:191], v[34:37]
	v_mfma_f32_16x16x32_bf16 v[26:29], v[140:143], v[216:219], v[26:29]
	v_mfma_f32_16x16x32_bf16 v[18:21], v[148:151], v[216:219], v[18:21]
	v_mfma_f32_16x16x32_bf16 v[62:65], v[144:147], v[176:179], v[62:65]
	v_mfma_f32_16x16x32_bf16 v[58:61], v[152:155], v[176:179], v[58:61]
	v_mfma_f32_16x16x32_bf16 v[54:57], v[144:147], v[184:187], v[54:57]
	v_mfma_f32_16x16x32_bf16 v[50:53], v[152:155], v[184:187], v[50:53]
	v_mfma_f32_16x16x32_bf16 v[42:45], v[144:147], v[212:215], v[42:45]
	v_mfma_f32_16x16x32_bf16 v[34:37], v[152:155], v[212:215], v[34:37]
	v_mfma_f32_16x16x32_bf16 v[26:29], v[144:147], v[220:223], v[26:29]
	v_mfma_f32_16x16x32_bf16 v[18:21], v[152:155], v[220:223], v[18:21]
	v_mfma_f32_16x16x32_bf16 v[46:49], v[156:159], v[172:175], v[46:49]
	v_mfma_f32_16x16x32_bf16 v[38:41], v[164:167], v[172:175], v[38:41]
	v_mfma_f32_16x16x32_bf16 v[30:33], v[156:159], v[180:183], v[30:33]
	v_mfma_f32_16x16x32_bf16 v[22:25], v[164:167], v[180:183], v[22:25]
	v_mfma_f32_16x16x32_bf16 v[14:17], v[156:159], v[188:191], v[14:17]
	v_mfma_f32_16x16x32_bf16 v[10:13], v[164:167], v[188:191], v[10:13]
	v_mfma_f32_16x16x32_bf16 v[6:9], v[156:159], v[216:219], v[6:9]
	v_mfma_f32_16x16x32_bf16 v[2:5], v[164:167], v[216:219], v[2:5]
	v_mfma_f32_16x16x32_bf16 v[46:49], v[160:163], v[176:179], v[46:49]
	v_mfma_f32_16x16x32_bf16 v[38:41], v[168:171], v[176:179], v[38:41]
	v_mfma_f32_16x16x32_bf16 v[30:33], v[160:163], v[184:187], v[30:33]
	v_mfma_f32_16x16x32_bf16 v[22:25], v[168:171], v[184:187], v[22:25]
	v_mfma_f32_16x16x32_bf16 v[14:17], v[160:163], v[212:215], v[14:17]
	v_mfma_f32_16x16x32_bf16 v[10:13], v[168:171], v[212:215], v[10:13]
	v_mfma_f32_16x16x32_bf16 v[6:9], v[160:163], v[220:223], v[6:9]
	v_mfma_f32_16x16x32_bf16 v[2:5], v[168:171], v[220:223], v[2:5]
	s_barrier
; #define PG8_STAGE(bufoff, gbase, voff) do { _Pragma("unroll") for (int _i = 0; _i < 2; ++_i) \
;         __builtin_amdgcn_global_load_lds((const unsigned*)((const char*)(gbase) + (voff)[_i]), (LAS unsigned*)(lds + (bufoff) + ldsw + _i * 8192), 16, 0, 0); } while (0)
; #define PG8_LDA(dst, b, h) do { _Pragma("unroll") for (int m = 0; m < 4; ++m) _Pragma("unroll") for (int k = 0; k < 2; ++k) dst[m][k] = *(const LAS bf16x8*)(lds + PG8_SA(b, h) + aoff + m * 2048 + k * 1024); } while (0)
; #define PG8_LDB(dst, b, h) do { _Pragma("unroll") for (int n = 0; n < 2; ++n) _Pragma("unroll") for (int k = 0; k < 2; ++k) dst[n][k] = *(const LAS bf16x8*)(lds + PG8_SB(b, h) + boff + n * 2048 + k * 1024); } while (0)
; #define PG8_MMA(ai, bj, At, Bt) do { __builtin_amdgcn_s_setprio(1); _Pragma("unroll") for (int m = 0; m < 4; ++m) _Pragma("unroll") for (int n = 0; n < 2; ++n) _Pragma("unroll") for (int k = 0; k < 2; ++k) \
;         acc[ai][bj][m][n] = __builtin_amdgcn_mfma_f32_16x16x32_bf16(Bt[n][k], At[m][k], acc[ai][bj][m][n], 0, 0, 0); __builtin_amdgcn_s_setprio(0); } while (0)
; #define PG8_WAIT_V(n) asm volatile("s_waitcnt vmcnt(" #n ")" ::: "memory")
; #define PG8_WAIT_L(n) asm volatile("s_waitcnt lgkmcnt(" #n ")" ::: "memory")
; #define PG8_BAR __builtin_amdgcn_s_barrier()
; #define PG8_SCHED __builtin_amdgcn_sched_barrier(0)
; template <class Epi, class Sched>
; __device__ __forceinline__ void gemm_phase(LAS unsigned char* lds, const Gemm g, const Sched& S, const Epi& E) {
;     ...
;             PG8_LDB(B0, 1, 0); PG8_LDB(B1, 1, 1); PG8_SCHED; PG8_LDA(At, 1, 0); PG8_STAGE(PG8_SA(0, 1), a2 + hsA, voffA);
;             PG8_WAIT_V(8); PG8_WAIT_L(0); PG8_BAR; PG8_MMA(0, 0, At, B0); PG8_MMA(0, 1, At, B1); PG8_BAR; PG8_SCHED;
;             PG8_LDA(At, 1, 1); PG8_STAGE(PG8_SB(1, 0), b3, voffB); PG8_STAGE(PG8_SB(1, 1), b3 + hsB, voffB); PG8_STAGE(PG8_SA(1, 0), a3, voffA);
;             PG8_WAIT_V(8); PG8_WAIT_L(0); PG8_BAR; PG8_MMA(1, 0, At, B0); PG8_MMA(1, 1, At, B1); PG8_BAR; PG8_SCHED;
	s_add_i32 s74, 0, 0x18000
	s_add_i32 s75, 0, 0x1c000
	v_add_u32_e32 v152, s74, v206
	v_add_u32_e32 v168, s75, v206
	ds_read_b128 v[140:143], v152
	ds_read_b128 v[144:147], v152 offset:1024
	ds_read_b128 v[148:151], v152 offset:2048
	ds_read_b128 v[152:155], v152 offset:3072
	ds_read_b128 v[156:159], v168
	ds_read_b128 v[160:163], v168 offset:1024
	ds_read_b128 v[164:167], v168 offset:2048
	ds_read_b128 v[168:171], v168 offset:3072
	s_add_u32 s8, s40, 0xb0000
	s_addc_u32 s9, s41, 0
	s_mov_b32 m0, s64
	v_lshl_add_u64 v[230:231], s[8:9], 0, v[134:135]
	ds_read_b128 v[172:175], v210 offset:32768
	ds_read_b128 v[176:179], v210 offset:33792
	ds_read_b128 v[180:183], v210 offset:34816
	ds_read_b128 v[184:187], v210 offset:35840
	ds_read_b128 v[188:191], v210 offset:36864
	ds_read_b128 v[212:215], v210 offset:37888
	ds_read_b128 v[216:219], v210 offset:38912
	ds_read_b128 v[220:223], v210 offset:39936
	global_load_lds_dwordx4 v[230:231], off
	v_lshl_add_u64 v[230:231], s[8:9], 0, v[132:133]
	s_mov_b32 m0, s78
	s_nop 0
	global_load_lds_dwordx4 v[230:231], off
	s_waitcnt vmcnt(8)
	s_waitcnt lgkmcnt(0)
	s_barrier
	s_waitcnt lgkmcnt(0)
	v_mfma_f32_16x16x32_bf16 v[126:129], v[140:143], v[172:175], v[126:129]
	v_mfma_f32_16x16x32_bf16 v[122:125], v[148:151], v[172:175], v[122:125]
	v_mfma_f32_16x16x32_bf16 v[118:121], v[140:143], v[180:183], v[118:121]
	v_mfma_f32_16x16x32_bf16 v[114:117], v[148:151], v[180:183], v[114:117]
	v_mfma_f32_16x16x32_bf16 v[106:109], v[140:143], v[188:191], v[106:109]
	v_mfma_f32_16x16x32_bf16 v[98:101], v[148:151], v[188:191], v[98:101]
	v_mfma_f32_16x16x32_bf16 v[90:93], v[140:143], v[216:219], v[90:93]
	v_mfma_f32_16x16x32_bf16 v[82:85], v[148:151], v[216:219], v[82:85]
	v_mfma_f32_16x16x32_bf16 v[126:129], v[144:147], v[176:179], v[126:129]
	v_mfma_f32_16x16x32_bf16 v[122:125], v[152:155], v[176:179], v[122:125]
	v_mfma_f32_16x16x32_bf16 v[118:121], v[144:147], v[184:187], v[118:121]
	v_mfma_f32_16x16x32_bf16 v[114:117], v[152:155], v[184:187], v[114:117]
	v_mfma_f32_16x16x32_bf16 v[106:109], v[144:147], v[212:215], v[106:109]
	v_mfma_f32_16x16x32_bf16 v[98:101], v[152:155], v[212:215], v[98:101]
	v_mfma_f32_16x16x32_bf16 v[90:93], v[144:147], v[220:223], v[90:93]
	v_mfma_f32_16x16x32_bf16 v[82:85], v[152:155], v[220:223], v[82:85]
	v_mfma_f32_16x16x32_bf16 v[110:113], v[156:159], v[172:175], v[110:113]
	v_mfma_f32_16x16x32_bf16 v[102:105], v[164:167], v[172:175], v[102:105]
	v_mfma_f32_16x16x32_bf16 v[94:97], v[156:159], v[180:183], v[94:97]
	v_mfma_f32_16x16x32_bf16 v[86:89], v[164:167], v[180:183], v[86:89]
	v_mfma_f32_16x16x32_bf16 v[78:81], v[156:159], v[188:191], v[78:81]
	v_mfma_f32_16x16x32_bf16 v[74:77], v[164:167], v[188:191], v[74:77]
	v_mfma_f32_16x16x32_bf16 v[70:73], v[156:159], v[216:219], v[70:73]
	v_mfma_f32_16x16x32_bf16 v[66:69], v[164:167], v[216:219], v[66:69]
	v_mfma_f32_16x16x32_bf16 v[110:113], v[160:163], v[176:179], v[110:113]
	v_mfma_f32_16x16x32_bf16 v[102:105], v[168:171], v[176:179], v[102:105]
	v_mfma_f32_16x16x32_bf16 v[94:97], v[160:163], v[184:187], v[94:97]
	v_mfma_f32_16x16x32_bf16 v[86:89], v[168:171], v[184:187], v[86:89]
	v_mfma_f32_16x16x32_bf16 v[78:81], v[160:163], v[212:215], v[78:81]
	v_mfma_f32_16x16x32_bf16 v[74:77], v[168:171], v[212:215], v[74:77]
	v_mfma_f32_16x16x32_bf16 v[70:73], v[160:163], v[220:223], v[70:73]
	v_mfma_f32_16x16x32_bf16 v[66:69], v[168:171], v[220:223], v[66:69]
	s_barrier
	s_add_i32 s8, s74, s24
	v_lshl_add_u64 v[208:209], v[208:209], 0, s[18:19]
	s_mov_b32 m0, s8
	ds_read_b128 v[172:175], v210 offset:49152
	ds_read_b128 v[176:179], v210 offset:50176
	ds_read_b128 v[180:183], v210 offset:51200
	ds_read_b128 v[184:187], v210 offset:52224
	ds_read_b128 v[188:191], v210 offset:53248
	ds_read_b128 v[212:215], v210 offset:54272
	ds_read_b128 v[216:219], v210 offset:55296
	ds_read_b128 v[220:223], v210 offset:56320
	global_load_lds_dwordx4 v[208:209], off
	s_add_i32 m0, s8, 0x2000
	s_add_u32 s8, s38, 0xb0080
	v_lshl_add_u64 v[208:209], v[224:225], 0, s[18:19]
	s_addc_u32 s9, s39, 0
	s_add_i32 s38, s75, s24
	global_load_lds_dwordx4 v[208:209], off
	v_lshl_add_u64 v[208:209], s[8:9], 0, v[0:1]
	s_mov_b32 m0, s38
	s_nop 0
	global_load_lds_dwordx4 v[208:209], off
	v_lshl_add_u64 v[208:209], s[8:9], 0, v[130:131]
	s_add_i32 m0, s38, 0x2000
	s_nop 0
	global_load_lds_dwordx4 v[208:209], off
	v_lshl_add_u64 v[208:209], v[226:227], 0, s[18:19]
	s_mov_b32 m0, s16
	s_nop 0
	global_load_lds_dwordx4 v[208:209], off
	v_lshl_add_u64 v[208:209], v[228:229], 0, s[18:19]
	s_mov_b32 m0, s7
	s_nop 0
	global_load_lds_dwordx4 v[208:209], off
	s_waitcnt vmcnt(8)
	s_waitcnt lgkmcnt(0)
	s_barrier
; #define PG8_MMA(ai, bj, At, Bt) do { __builtin_amdgcn_s_setprio(1); _Pragma("unroll") for (int m = 0; m < 4; ++m) _Pragma("unroll") for (int n = 0; n < 2; ++n) _Pragma("unroll") for (int k = 0; k < 2; ++k) \
;         acc[ai][bj][m][n] = __builtin_amdgcn_mfma_f32_16x16x32_bf16(Bt[n][k], At[m][k], acc[ai][bj][m][n], 0, 0, 0); __builtin_amdgcn_s_setprio(0); } while (0)
; #define PG8_WAIT_V(n) asm volatile("s_waitcnt vmcnt(" #n ")" ::: "memory")
; #define PG8_WAIT_L(n) asm volatile("s_waitcnt lgkmcnt(" #n ")" ::: "memory")
; #define PG8_BAR __builtin_amdgcn_s_barrier()
; #define PG8_SCHED __builtin_amdgcn_sched_barrier(0)
; template <class Epi, class Sched>
; __device__ __forceinline__ void gemm_phase(LAS unsigned char* lds, const Gemm g, const Sched& S, const Epi& E) {
;     ...
;             PG8_WAIT_V(8); PG8_WAIT_L(0); PG8_BAR; PG8_MMA(1, 0, At, B0); PG8_MMA(1, 1, At, B1); PG8_BAR; PG8_SCHED;
;         }
;     __device__ __forceinline__ void operator()(const Acc& acc, const Unit& u, int wr, int wc, int fr, int fq) const {
;     ...
;                     const f32x4 o0 = b0 + acc[ai][bj][m][0] * scale, o1 = b1 + acc[ai][bj][m][1] * scale;
	s_waitcnt lgkmcnt(0)
	v_mfma_f32_16x16x32_bf16 v[62:65], v[140:143], v[172:175], v[62:65]
	v_mfma_f32_16x16x32_bf16 v[58:61], v[148:151], v[172:175], v[58:61]
	v_mfma_f32_16x16x32_bf16 v[54:57], v[140:143], v[180:183], v[54:57]
	v_mfma_f32_16x16x32_bf16 v[50:53], v[148:151], v[180:183], v[50:53]
	v_mfma_f32_16x16x32_bf16 v[42:45], v[140:143], v[188:191], v[42:45]
	v_mfma_f32_16x16x32_bf16 v[34:37], v[148:151], v[188:191], v[34:37]
	v_mfma_f32_16x16x32_bf16 v[26:29], v[140:143], v[216:219], v[26:29]
	v_mfma_f32_16x16x32_bf16 v[18:21], v[148:151], v[216:219], v[18:21]
	v_mfma_f32_16x16x32_bf16 v[62:65], v[144:147], v[176:179], v[62:65]
	v_mfma_f32_16x16x32_bf16 v[58:61], v[152:155], v[176:179], v[58:61]
	v_mfma_f32_16x16x32_bf16 v[54:57], v[144:147], v[184:187], v[54:57]
	v_mfma_f32_16x16x32_bf16 v[50:53], v[152:155], v[184:187], v[50:53]
	v_mfma_f32_16x16x32_bf16 v[42:45], v[144:147], v[212:215], v[42:45]
	v_mfma_f32_16x16x32_bf16 v[34:37], v[152:155], v[212:215], v[34:37]
	v_mfma_f32_16x16x32_bf16 v[26:29], v[144:147], v[220:223], v[26:29]
	v_mfma_f32_16x16x32_bf16 v[18:21], v[152:155], v[220:223], v[18:21]
	v_mfma_f32_16x16x32_bf16 v[46:49], v[156:159], v[172:175], v[46:49]
	v_mfma_f32_16x16x32_bf16 v[38:41], v[164:167], v[172:175], v[38:41]
	v_mfma_f32_16x16x32_bf16 v[30:33], v[156:159], v[180:183], v[30:33]
	v_mfma_f32_16x16x32_bf16 v[22:25], v[164:167], v[180:183], v[22:25]
	v_mfma_f32_16x16x32_bf16 v[14:17], v[156:159], v[188:191], v[14:17]
	v_mfma_f32_16x16x32_bf16 v[10:13], v[164:167], v[188:191], v[10:13]
	v_mfma_f32_16x16x32_bf16 v[6:9], v[156:159], v[216:219], v[6:9]
	v_mfma_f32_16x16x32_bf16 v[2:5], v[164:167], v[216:219], v[2:5]
	v_mfma_f32_16x16x32_bf16 v[46:49], v[160:163], v[176:179], v[46:49]
	v_mfma_f32_16x16x32_bf16 v[38:41], v[168:171], v[176:179], v[38:41]
	v_mfma_f32_16x16x32_bf16 v[30:33], v[160:163], v[184:187], v[30:33]
	v_mfma_f32_16x16x32_bf16 v[22:25], v[168:171], v[184:187], v[22:25]
	v_mfma_f32_16x16x32_bf16 v[14:17], v[160:163], v[212:215], v[14:17]
	v_mfma_f32_16x16x32_bf16 v[10:13], v[168:171], v[212:215], v[10:13]
	v_mfma_f32_16x16x32_bf16 v[6:9], v[160:163], v[220:223], v[6:9]
	v_mfma_f32_16x16x32_bf16 v[2:5], v[168:171], v[220:223], v[2:5]
	s_barrier
	s_add_u32 s84, s84, 0x100
	s_addc_u32 s85, s85, 0
	s_cmp_ge_i32 s96, s12
	s_mov_b64 s[8:9], s[20:21]
	s_mov_b32 s38, s96
	s_cbranch_scc0 .LBB0_298
	s_setprio 0
	v_pk_mul_f32 v[182:183], v[128:129], 0.5 op_sel_hi:[1,0]
	v_pk_mul_f32 v[184:185], v[126:127], 0.5 op_sel_hi:[1,0]
	v_pk_mul_f32 v[186:187], v[124:125], 0.5 op_sel_hi:[1,0]
	v_pk_mul_f32 v[188:189], v[122:123], 0.5 op_sel_hi:[1,0]
	v_pk_mul_f32 v[180:181], v[112:113], 0.5 op_sel_hi:[1,0]
	v_pk_mul_f32 v[178:179], v[110:111], 0.5 op_sel_hi:[1,0]
	v_pk_mul_f32 v[176:177], v[104:105], 0.5 op_sel_hi:[1,0]
	v_pk_mul_f32 v[174:175], v[102:103], 0.5 op_sel_hi:[1,0]
	v_pk_mul_f32 v[170:171], v[120:121], 0.5 op_sel_hi:[1,0]
	v_pk_mul_f32 v[168:169], v[118:119], 0.5 op_sel_hi:[1,0]
	v_pk_mul_f32 v[166:167], v[116:117], 0.5 op_sel_hi:[1,0]
	v_pk_mul_f32 v[164:165], v[114:115], 0.5 op_sel_hi:[1,0]
	v_pk_mul_f32 v[162:163], v[96:97], 0.5 op_sel_hi:[1,0]
	v_pk_mul_f32 v[160:161], v[94:95], 0.5 op_sel_hi:[1,0]
	v_pk_mul_f32 v[158:159], v[88:89], 0.5 op_sel_hi:[1,0]
	v_pk_mul_f32 v[156:157], v[86:87], 0.5 op_sel_hi:[1,0]
	v_pk_mul_f32 v[150:151], v[108:109], 0.5 op_sel_hi:[1,0]
	v_pk_mul_f32 v[148:149], v[106:107], 0.5 op_sel_hi:[1,0]
	v_pk_mul_f32 v[146:147], v[100:101], 0.5 op_sel_hi:[1,0]
	v_pk_mul_f32 v[144:145], v[98:99], 0.5 op_sel_hi:[1,0]
	v_pk_mul_f32 v[142:143], v[80:81], 0.5 op_sel_hi:[1,0]
	v_pk_mul_f32 v[140:141], v[78:79], 0.5 op_sel_hi:[1,0]
	v_pk_mul_f32 v[128:129], v[76:77], 0.5 op_sel_hi:[1,0]
	v_pk_mul_f32 v[126:127], v[74:75], 0.5 op_sel_hi:[1,0]
	v_pk_mul_f32 v[124:125], v[92:93], 0.5 op_sel_hi:[1,0]
	v_pk_mul_f32 v[122:123], v[90:91], 0.5 op_sel_hi:[1,0]
	v_pk_mul_f32 v[120:121], v[84:85], 0.5 op_sel_hi:[1,0]
	v_pk_mul_f32 v[118:119], v[82:83], 0.5 op_sel_hi:[1,0]
	v_pk_mul_f32 v[116:117], v[72:73], 0.5 op_sel_hi:[1,0]
	v_pk_mul_f32 v[114:115], v[70:71], 0.5 op_sel_hi:[1,0]
	v_pk_mul_f32 v[112:113], v[68:69], 0.5 op_sel_hi:[1,0]
	v_pk_mul_f32 v[110:111], v[66:67], 0.5 op_sel_hi:[1,0]
	v_pk_mul_f32 v[102:103], v[64:65], 0.5 op_sel_hi:[1,0]
	v_pk_mul_f32 v[104:105], v[62:63], 0.5 op_sel_hi:[1,0]
	v_pk_mul_f32 v[106:107], v[60:61], 0.5 op_sel_hi:[1,0]
	v_pk_mul_f32 v[108:109], v[58:59], 0.5 op_sel_hi:[1,0]
	v_pk_mul_f32 v[100:101], v[48:49], 0.5 op_sel_hi:[1,0]
	v_pk_mul_f32 v[98:99], v[46:47], 0.5 op_sel_hi:[1,0]
	v_pk_mul_f32 v[96:97], v[40:41], 0.5 op_sel_hi:[1,0]
	v_pk_mul_f32 v[94:95], v[38:39], 0.5 op_sel_hi:[1,0]
	v_pk_mul_f32 v[92:93], v[56:57], 0.5 op_sel_hi:[1,0]
	v_pk_mul_f32 v[90:91], v[54:55], 0.5 op_sel_hi:[1,0]
	v_pk_mul_f32 v[88:89], v[52:53], 0.5 op_sel_hi:[1,0]
	v_pk_mul_f32 v[86:87], v[50:51], 0.5 op_sel_hi:[1,0]
	v_pk_mul_f32 v[82:83], v[32:33], 0.5 op_sel_hi:[1,0]
	v_pk_mul_f32 v[80:81], v[30:31], 0.5 op_sel_hi:[1,0]
	v_pk_mul_f32 v[78:79], v[24:25], 0.5 op_sel_hi:[1,0]
	v_pk_mul_f32 v[76:77], v[22:23], 0.5 op_sel_hi:[1,0]
	v_pk_mul_f32 v[72:73], v[44:45], 0.5 op_sel_hi:[1,0]
	v_pk_mul_f32 v[70:71], v[42:43], 0.5 op_sel_hi:[1,0]
	v_pk_mul_f32 v[68:69], v[36:37], 0.5 op_sel_hi:[1,0]
	v_pk_mul_f32 v[66:67], v[34:35], 0.5 op_sel_hi:[1,0]
	v_pk_mul_f32 v[64:65], v[16:17], 0.5 op_sel_hi:[1,0]
	v_pk_mul_f32 v[62:63], v[14:15], 0.5 op_sel_hi:[1,0]
	v_pk_mul_f32 v[60:61], v[12:13], 0.5 op_sel_hi:[1,0]
	v_pk_mul_f32 v[58:59], v[10:11], 0.5 op_sel_hi:[1,0]
	v_pk_mul_f32 v[56:57], v[28:29], 0.5 op_sel_hi:[1,0]
	v_pk_mul_f32 v[54:55], v[26:27], 0.5 op_sel_hi:[1,0]
	v_pk_mul_f32 v[52:53], v[20:21], 0.5 op_sel_hi:[1,0]
	v_pk_mul_f32 v[50:51], v[18:19], 0.5 op_sel_hi:[1,0]
	v_pk_mul_f32 v[48:49], v[8:9], 0.5 op_sel_hi:[1,0]
	v_pk_mul_f32 v[46:47], v[6:7], 0.5 op_sel_hi:[1,0]
	v_pk_mul_f32 v[44:45], v[4:5], 0.5 op_sel_hi:[1,0]
	v_pk_mul_f32 v[42:43], v[2:3], 0.5 op_sel_hi:[1,0]
	v_readlane_b32 s96, v250, 43
	s_mov_b32 s73, s22
	s_mov_b32 s74, s23
	s_mov_b32 s75, vcc_lo

; #define PG8_STAGE(bufoff, gbase, voff) do { _Pragma("unroll") for (int _i = 0; _i < 2; ++_i) \
;         __builtin_amdgcn_global_load_lds((const unsigned*)((const char*)(gbase) + (voff)[_i]), (LAS unsigned*)(lds + (bufoff) + ldsw + _i * 8192), 16, 0, 0); } while (0)
; #define PG8_LDA(dst, b, h) do { _Pragma("unroll") for (int m = 0; m < 4; ++m) _Pragma("unroll") for (int k = 0; k < 2; ++k) dst[m][k] = *(const LAS bf16x8*)(lds + PG8_SA(b, h) + aoff + m * 2048 + k * 1024); } while (0)
; #define PG8_LDB(dst, b, h) do { _Pragma("unroll") for (int n = 0; n < 2; ++n) _Pragma("unroll") for (int k = 0; k < 2; ++k) dst[n][k] = *(const LAS bf16x8*)(lds + PG8_SB(b, h) + boff + n * 2048 + k * 1024); } while (0)
; #define PG8_WAIT_V(n) asm volatile("s_waitcnt vmcnt(" #n ")" ::: "memory")
; #define PG8_WAIT_L(n) asm volatile("s_waitcnt lgkmcnt(" #n ")" ::: "memory")
; #define PG8_BAR __builtin_amdgcn_s_barrier()
; template <class Epi, class Sched>
; __device__ __forceinline__ void gemm_phase(LAS unsigned char* lds, const Gemm g, const Sched& S, const Epi& E) {
;     ...
;         const bool has_next = S.next(ui + 1, nxt);
;         const char* nA = has_next ? (const char*)g.A + nxt.offA : cA; const char* nB = has_next ? (const char*)g.Bt + nxt.offB : cB;
;         for (int t = 0; t < nt; t += 2) {
;             const bool last = (t == nt - 2);
;             const char* a1 = cA + (size_t)(t + 1) * kstep;
;             const char* a2 = last ? nA : cA + (size_t)(t + 2) * kstep; const char* b2 = last ? nB : cB + (size_t)(t + 2) * kstep;
;             const char* a3 = a2 + kstep; const char* b3 = b2 + kstep;
;             if constexpr (Epi::MIDK) { if (t == (nt >> 1)) { int fr_ = fr, fq_ = fq; asm volatile("" : "+v"(fr_), "+v"(fq_)); E.mid(acc, cur, wr, wc, fr_, fq_); } }
;             PG8_LDB(B0, 0, 0); PG8_LDB(B1, 0, 1); PG8_SCHED; PG8_LDA(At, 0, 0); PG8_STAGE(PG8_SA(1, 1), a1 + hsA, voffA);
;             PG8_WAIT_V(8); PG8_WAIT_L(0); PG8_BAR; PG8_MMA(0, 0, At, B0); PG8_MMA(0, 1, At, B1); PG8_BAR; PG8_SCHED;
;     ...
; #pragma unroll
;         for (int a = 0; a < 2; ++a)
; #pragma unroll
;             for (int b = 0; b < 2; ++b)
; #pragma unroll
;                 for (int m = 0; m < 4; ++m)
; #pragma unroll
;                     for (int n = 0; n < 2; ++n) acc[a][b][m][n] = (f32x4){0.f, 0.f, 0.f, 0.f};
;         cur = nxt; cA = nA; cB = nB; ++ui;
.LBB0_483:
	s_add_u32 s76, s2, s50
	s_addc_u32 s77, s3, s51
	v_readlane_b32 s8, v254, 4
	v_readlane_b32 s9, v254, 5
	s_add_u32 s8, s8, s36
	s_addc_u32 s9, s9, s37
	s_andn2_b64 vcc, exec, s[34:35]
	s_cbranch_vccnz .Lzc_11212
	s_and_b64 s[42:43], s[20:21], exec
	s_cselect_b32 s47, s77, s39
	s_cselect_b32 s49, s76, s38
	s_cselect_b32 s73, s9, s41
	s_cselect_b32 s82, s8, s40
	s_add_u32 s38, s38, 0x40080
	s_addc_u32 s39, s39, 0
	s_add_u32 s83, s40, 0x100
	v_mov_b32_e32 v6, 0
	s_addc_u32 s84, s41, 0
	s_mov_b32 s40, 0
	v_mov_b32_e32 v7, v6
	v_mov_b32_e32 v8, v6
	v_mov_b32_e32 v9, v6
	v_mov_b32_e32 v14, v6
	v_mov_b32_e32 v15, v6
	v_mov_b32_e32 v16, v6
	v_mov_b32_e32 v17, v6
	v_mov_b32_e32 v22, v6
	v_mov_b32_e32 v23, v6
	v_mov_b32_e32 v24, v6
	v_mov_b32_e32 v25, v6
	v_mov_b32_e32 v26, v6
	v_mov_b32_e32 v27, v6
	v_mov_b32_e32 v28, v6
	v_mov_b32_e32 v29, v6
	v_mov_b32_e32 v38, v6
	v_mov_b32_e32 v39, v6
	v_mov_b32_e32 v40, v6
	v_mov_b32_e32 v41, v6
	v_mov_b32_e32 v42, v6
	v_mov_b32_e32 v43, v6
	v_mov_b32_e32 v44, v6
	v_mov_b32_e32 v45, v6
	v_mov_b32_e32 v54, v6
	v_mov_b32_e32 v55, v6
	v_mov_b32_e32 v56, v6
	v_mov_b32_e32 v57, v6
	v_mov_b32_e32 v58, v6
	v_mov_b32_e32 v59, v6
	v_mov_b32_e32 v60, v6
	v_mov_b32_e32 v61, v6
	v_mov_b32_e32 v2, v6
	v_mov_b32_e32 v3, v6
	v_mov_b32_e32 v4, v6
	v_mov_b32_e32 v5, v6
	v_mov_b32_e32 v10, v6
	v_mov_b32_e32 v11, v6
	v_mov_b32_e32 v12, v6
	v_mov_b32_e32 v13, v6
	v_mov_b32_e32 v18, v6
	v_mov_b32_e32 v19, v6
	v_mov_b32_e32 v20, v6
	v_mov_b32_e32 v21, v6
	v_mov_b32_e32 v30, v6
	v_mov_b32_e32 v31, v6
	v_mov_b32_e32 v32, v6
	v_mov_b32_e32 v33, v6
	v_mov_b32_e32 v34, v6
	v_mov_b32_e32 v35, v6
	v_mov_b32_e32 v36, v6
	v_mov_b32_e32 v37, v6
	v_mov_b32_e32 v46, v6
	v_mov_b32_e32 v47, v6
	v_mov_b32_e32 v48, v6
	v_mov_b32_e32 v49, v6
	v_mov_b32_e32 v50, v6
	v_mov_b32_e32 v51, v6
	v_mov_b32_e32 v52, v6
	v_mov_b32_e32 v53, v6
	v_mov_b32_e32 v62, v6
	v_mov_b32_e32 v63, v6
	v_mov_b32_e32 v64, v6
	v_mov_b32_e32 v65, v6
	v_mov_b32_e32 v70, v6
	v_mov_b32_e32 v71, v6
	v_mov_b32_e32 v72, v6
	v_mov_b32_e32 v73, v6
	v_mov_b32_e32 v74, v6
	v_mov_b32_e32 v75, v6
	v_mov_b32_e32 v76, v6
	v_mov_b32_e32 v77, v6
	v_mov_b32_e32 v86, v6
	v_mov_b32_e32 v87, v6
	v_mov_b32_e32 v88, v6
	v_mov_b32_e32 v89, v6
	v_mov_b32_e32 v90, v6
	v_mov_b32_e32 v91, v6
	v_mov_b32_e32 v92, v6
	v_mov_b32_e32 v93, v6
	v_mov_b32_e32 v102, v6
	v_mov_b32_e32 v103, v6
	v_mov_b32_e32 v104, v6
	v_mov_b32_e32 v105, v6
	v_mov_b32_e32 v106, v6
	v_mov_b32_e32 v107, v6
	v_mov_b32_e32 v108, v6
	v_mov_b32_e32 v109, v6
	v_mov_b32_e32 v118, v6
	v_mov_b32_e32 v119, v6
	v_mov_b32_e32 v120, v6
	v_mov_b32_e32 v121, v6
	v_mov_b32_e32 v126, v6
	v_mov_b32_e32 v127, v6
	v_mov_b32_e32 v128, v6
	v_mov_b32_e32 v129, v6
	v_mov_b32_e32 v66, v6
	v_mov_b32_e32 v67, v6
	v_mov_b32_e32 v68, v6
	v_mov_b32_e32 v69, v6
	v_mov_b32_e32 v78, v6
	v_mov_b32_e32 v79, v6
	v_mov_b32_e32 v80, v6
	v_mov_b32_e32 v81, v6
	v_mov_b32_e32 v82, v6
	v_mov_b32_e32 v83, v6
	v_mov_b32_e32 v84, v6
	v_mov_b32_e32 v85, v6
	v_mov_b32_e32 v94, v6
	v_mov_b32_e32 v95, v6
	v_mov_b32_e32 v96, v6
	v_mov_b32_e32 v97, v6
	v_mov_b32_e32 v98, v6
	v_mov_b32_e32 v99, v6
	v_mov_b32_e32 v100, v6
	v_mov_b32_e32 v101, v6
	v_mov_b32_e32 v110, v6
	v_mov_b32_e32 v111, v6
	v_mov_b32_e32 v112, v6
	v_mov_b32_e32 v113, v6
	v_mov_b32_e32 v114, v6
	v_mov_b32_e32 v115, v6
	v_mov_b32_e32 v116, v6
	v_mov_b32_e32 v117, v6
	v_mov_b32_e32 v122, v6
	v_mov_b32_e32 v123, v6
	v_mov_b32_e32 v124, v6
	v_mov_b32_e32 v125, v6
	v_readfirstlane_b32 s85, v193
	s_lshr_b32 s85, s85, 8
	s_cmp_eq_u32 s85, 1
	s_cbranch_scc0 .Lnp_485
	s_setprio 1
.Lnp_485:
.LBB0_485:
	s_add_i32 s85, s40, 2
	s_add_u32 s41, s38, 0xfffc0080
	s_addc_u32 s42, s39, -1
	s_add_i32 s74, 0, 0x10000
	s_cmp_eq_u32 s26, s40
	s_cselect_b32 s43, s47, s42
	s_cselect_b32 s42, s49, s41
	s_cselect_b32 s41, s73, s84
	s_cselect_b32 s40, s82, s83
	s_add_i32 s75, 0, 0x14000
	v_add_u32_e32 v154, s74, v165
	v_add_u32_e32 v162, s75, v165
	ds_read_b128 v[142:145], v154
	ds_read_b128 v[146:149], v154 offset:1024
	ds_read_b128 v[150:153], v154 offset:2048
	ds_read_b128 v[154:157], v154 offset:3072
	ds_read_b128 v[158:161], v162
	ds_read_b128 v[168:171], v162 offset:1024
	ds_read_b128 v[172:175], v162 offset:2048
	ds_read_b128 v[176:179], v162 offset:3072
	v_lshl_add_u64 v[228:229], s[38:39], 0, v[138:139]
	s_add_i32 m0, s16, 0xc000
	ds_read_b128 v[180:183], v166
	ds_read_b128 v[184:187], v166 offset:1024
	ds_read_b128 v[188:191], v166 offset:2048
	ds_read_b128 v[208:211], v166 offset:3072
	ds_read_b128 v[212:215], v166 offset:4096
	ds_read_b128 v[216:219], v166 offset:5120
	ds_read_b128 v[220:223], v166 offset:6144
	ds_read_b128 v[224:227], v166 offset:7168
	global_load_lds_dwordx4 v[228:229], off
	v_lshl_add_u64 v[228:229], s[38:39], 0, v[140:141]
	s_add_i32 m0, s16, 0xe000
	s_nop 0
	global_load_lds_dwordx4 v[228:229], off
	s_waitcnt vmcnt(8)
	s_waitcnt lgkmcnt(0)
	s_barrier
; #define PG8_STAGE(bufoff, gbase, voff) do { _Pragma("unroll") for (int _i = 0; _i < 2; ++_i) \
;         __builtin_amdgcn_global_load_lds((const unsigned*)((const char*)(gbase) + (voff)[_i]), (LAS unsigned*)(lds + (bufoff) + ldsw + _i * 8192), 16, 0, 0); } while (0)
; #define PG8_LDA(dst, b, h) do { _Pragma("unroll") for (int m = 0; m < 4; ++m) _Pragma("unroll") for (int k = 0; k < 2; ++k) dst[m][k] = *(const LAS bf16x8*)(lds + PG8_SA(b, h) + aoff + m * 2048 + k * 1024); } while (0)
; #define PG8_MMA(ai, bj, At, Bt) do { __builtin_amdgcn_s_setprio(1); _Pragma("unroll") for (int m = 0; m < 4; ++m) _Pragma("unroll") for (int n = 0; n < 2; ++n) _Pragma("unroll") for (int k = 0; k < 2; ++k) \
;         acc[ai][bj][m][n] = __builtin_amdgcn_mfma_f32_16x16x32_bf16(Bt[n][k], At[m][k], acc[ai][bj][m][n], 0, 0, 0); __builtin_amdgcn_s_setprio(0); } while (0)
; #define PG8_WAIT_V(n) asm volatile("s_waitcnt vmcnt(" #n ")" ::: "memory")
; #define PG8_WAIT_L(n) asm volatile("s_waitcnt lgkmcnt(" #n ")" ::: "memory")
; #define PG8_BAR __builtin_amdgcn_s_barrier()
; #define PG8_SCHED __builtin_amdgcn_sched_barrier(0)
; template <class Epi, class Sched>
; __device__ __forceinline__ void gemm_phase(LAS unsigned char* lds, const Gemm g, const Sched& S, const Epi& E) {
;     ...
;             PG8_WAIT_V(8); PG8_WAIT_L(0); PG8_BAR; PG8_MMA(0, 0, At, B0); PG8_MMA(0, 1, At, B1); PG8_BAR; PG8_SCHED;
;             PG8_LDA(At, 0, 1); PG8_STAGE(PG8_SB(0, 0), b2, voffB); PG8_STAGE(PG8_SB(0, 1), b2 + hsB, voffB); PG8_STAGE(PG8_SA(0, 0), a2, voffA);
;             PG8_WAIT_V(8); PG8_WAIT_L(0); PG8_BAR; PG8_MMA(1, 0, At, B0); PG8_MMA(1, 1, At, B1); PG8_BAR; PG8_SCHED;
	s_waitcnt lgkmcnt(0)
	v_mfma_f32_16x16x32_bf16 v[122:125], v[142:145], v[180:183], v[122:125]
	v_mfma_f32_16x16x32_bf16 v[114:117], v[150:153], v[180:183], v[114:117]
	v_mfma_f32_16x16x32_bf16 v[110:113], v[142:145], v[188:191], v[110:113]
	v_mfma_f32_16x16x32_bf16 v[98:101], v[150:153], v[188:191], v[98:101]
	v_mfma_f32_16x16x32_bf16 v[94:97], v[142:145], v[212:215], v[94:97]
	v_mfma_f32_16x16x32_bf16 v[82:85], v[150:153], v[212:215], v[82:85]
	v_mfma_f32_16x16x32_bf16 v[78:81], v[142:145], v[220:223], v[78:81]
	v_mfma_f32_16x16x32_bf16 v[66:69], v[150:153], v[220:223], v[66:69]
	v_mfma_f32_16x16x32_bf16 v[122:125], v[146:149], v[184:187], v[122:125]
	v_mfma_f32_16x16x32_bf16 v[114:117], v[154:157], v[184:187], v[114:117]
	v_mfma_f32_16x16x32_bf16 v[110:113], v[146:149], v[208:211], v[110:113]
	v_mfma_f32_16x16x32_bf16 v[98:101], v[154:157], v[208:211], v[98:101]
	v_mfma_f32_16x16x32_bf16 v[94:97], v[146:149], v[216:219], v[94:97]
	v_mfma_f32_16x16x32_bf16 v[82:85], v[154:157], v[216:219], v[82:85]
	v_mfma_f32_16x16x32_bf16 v[78:81], v[146:149], v[224:227], v[78:81]
	v_mfma_f32_16x16x32_bf16 v[66:69], v[154:157], v[224:227], v[66:69]
	v_mfma_f32_16x16x32_bf16 v[126:129], v[158:161], v[180:183], v[126:129]
	v_mfma_f32_16x16x32_bf16 v[118:121], v[172:175], v[180:183], v[118:121]
	v_mfma_f32_16x16x32_bf16 v[106:109], v[158:161], v[188:191], v[106:109]
	v_mfma_f32_16x16x32_bf16 v[102:105], v[172:175], v[188:191], v[102:105]
	v_mfma_f32_16x16x32_bf16 v[90:93], v[158:161], v[212:215], v[90:93]
	v_mfma_f32_16x16x32_bf16 v[86:89], v[172:175], v[212:215], v[86:89]
	v_mfma_f32_16x16x32_bf16 v[74:77], v[158:161], v[220:223], v[74:77]
	v_mfma_f32_16x16x32_bf16 v[70:73], v[172:175], v[220:223], v[70:73]
	v_mfma_f32_16x16x32_bf16 v[126:129], v[168:171], v[184:187], v[126:129]
	v_mfma_f32_16x16x32_bf16 v[118:121], v[176:179], v[184:187], v[118:121]
	v_mfma_f32_16x16x32_bf16 v[106:109], v[168:171], v[208:211], v[106:109]
	v_mfma_f32_16x16x32_bf16 v[102:105], v[176:179], v[208:211], v[102:105]
	v_mfma_f32_16x16x32_bf16 v[90:93], v[168:171], v[216:219], v[90:93]
	v_mfma_f32_16x16x32_bf16 v[86:89], v[176:179], v[216:219], v[86:89]
	v_mfma_f32_16x16x32_bf16 v[74:77], v[168:171], v[224:227], v[74:77]
	v_mfma_f32_16x16x32_bf16 v[70:73], v[176:179], v[224:227], v[70:73]
	s_barrier
	s_add_i32 s74, s74, s12
	v_lshl_add_u64 v[228:229], s[40:41], 0, v[0:1]
	s_mov_b32 m0, s74
	ds_read_b128 v[180:183], v166 offset:16384
	ds_read_b128 v[184:187], v166 offset:17408
	ds_read_b128 v[188:191], v166 offset:18432
	ds_read_b128 v[208:211], v166 offset:19456
	ds_read_b128 v[212:215], v166 offset:20480
	ds_read_b128 v[216:219], v166 offset:21504
	ds_read_b128 v[220:223], v166 offset:22528
	ds_read_b128 v[224:227], v166 offset:23552
	global_load_lds_dwordx4 v[228:229], off
	s_add_i32 m0, s74, 0x2000
	s_add_u32 vcc_lo, s40, 0x40000
	v_lshl_add_u64 v[230:231], s[40:41], 0, v[130:131]
	s_addc_u32 vcc_hi, s41, 0
	s_add_i32 s74, s75, s12
	global_load_lds_dwordx4 v[230:231], off
	v_lshl_add_u64 v[232:233], vcc, 0, v[0:1]
	s_mov_b32 m0, s74
	v_lshl_add_u64 v[238:239], s[42:43], 0, v[132:133]
	global_load_lds_dwordx4 v[232:233], off
	v_lshl_add_u64 v[232:233], vcc, 0, v[130:131]
	s_add_i32 m0, s74, 0x2000
	s_nop 0
	global_load_lds_dwordx4 v[232:233], off
	v_lshl_add_u64 v[232:233], s[42:43], 0, v[134:135]
	s_mov_b32 m0, s16
	s_nop 0
	global_load_lds_dwordx4 v[232:233], off
	s_mov_b32 m0, s52
	s_nop 0
	global_load_lds_dwordx4 v[238:239], off
	s_waitcnt vmcnt(8)
	s_waitcnt lgkmcnt(0)
	s_barrier
	s_waitcnt lgkmcnt(0)
	v_mfma_f32_16x16x32_bf16 v[62:65], v[142:145], v[180:183], v[62:65]
	v_mfma_f32_16x16x32_bf16 v[50:53], v[150:153], v[180:183], v[50:53]
	v_mfma_f32_16x16x32_bf16 v[46:49], v[142:145], v[188:191], v[46:49]
	v_mfma_f32_16x16x32_bf16 v[34:37], v[150:153], v[188:191], v[34:37]
	v_mfma_f32_16x16x32_bf16 v[30:33], v[142:145], v[212:215], v[30:33]
	v_mfma_f32_16x16x32_bf16 v[18:21], v[150:153], v[212:215], v[18:21]
	v_mfma_f32_16x16x32_bf16 v[10:13], v[142:145], v[220:223], v[10:13]
	v_mfma_f32_16x16x32_bf16 v[2:5], v[150:153], v[220:223], v[2:5]
	v_mfma_f32_16x16x32_bf16 v[62:65], v[146:149], v[184:187], v[62:65]
	v_mfma_f32_16x16x32_bf16 v[50:53], v[154:157], v[184:187], v[50:53]
	v_mfma_f32_16x16x32_bf16 v[46:49], v[146:149], v[208:211], v[46:49]
	v_mfma_f32_16x16x32_bf16 v[34:37], v[154:157], v[208:211], v[34:37]
	v_mfma_f32_16x16x32_bf16 v[30:33], v[146:149], v[216:219], v[30:33]
	v_mfma_f32_16x16x32_bf16 v[18:21], v[154:157], v[216:219], v[18:21]
	v_mfma_f32_16x16x32_bf16 v[10:13], v[146:149], v[224:227], v[10:13]
	v_mfma_f32_16x16x32_bf16 v[2:5], v[154:157], v[224:227], v[2:5]
	v_mfma_f32_16x16x32_bf16 v[58:61], v[158:161], v[180:183], v[58:61]
	v_mfma_f32_16x16x32_bf16 v[54:57], v[172:175], v[180:183], v[54:57]
	v_mfma_f32_16x16x32_bf16 v[42:45], v[158:161], v[188:191], v[42:45]
	v_mfma_f32_16x16x32_bf16 v[38:41], v[172:175], v[188:191], v[38:41]
	v_mfma_f32_16x16x32_bf16 v[26:29], v[158:161], v[212:215], v[26:29]
	v_mfma_f32_16x16x32_bf16 v[22:25], v[172:175], v[212:215], v[22:25]
	v_mfma_f32_16x16x32_bf16 v[14:17], v[158:161], v[220:223], v[14:17]
	v_mfma_f32_16x16x32_bf16 v[6:9], v[172:175], v[220:223], v[6:9]
	v_mfma_f32_16x16x32_bf16 v[58:61], v[168:171], v[184:187], v[58:61]
	v_mfma_f32_16x16x32_bf16 v[54:57], v[176:179], v[184:187], v[54:57]
	v_mfma_f32_16x16x32_bf16 v[42:45], v[168:171], v[208:211], v[42:45]
	v_mfma_f32_16x16x32_bf16 v[38:41], v[176:179], v[208:211], v[38:41]
	v_mfma_f32_16x16x32_bf16 v[26:29], v[168:171], v[216:219], v[26:29]
	v_mfma_f32_16x16x32_bf16 v[22:25], v[176:179], v[216:219], v[22:25]
	v_mfma_f32_16x16x32_bf16 v[14:17], v[168:171], v[224:227], v[14:17]
	v_mfma_f32_16x16x32_bf16 v[6:9], v[176:179], v[224:227], v[6:9]
	s_barrier
; #define PG8_STAGE(bufoff, gbase, voff) do { _Pragma("unroll") for (int _i = 0; _i < 2; ++_i) \
;         __builtin_amdgcn_global_load_lds((const unsigned*)((const char*)(gbase) + (voff)[_i]), (LAS unsigned*)(lds + (bufoff) + ldsw + _i * 8192), 16, 0, 0); } while (0)
; #define PG8_LDA(dst, b, h) do { _Pragma("unroll") for (int m = 0; m < 4; ++m) _Pragma("unroll") for (int k = 0; k < 2; ++k) dst[m][k] = *(const LAS bf16x8*)(lds + PG8_SA(b, h) + aoff + m * 2048 + k * 1024); } while (0)
; #define PG8_LDB(dst, b, h) do { _Pragma("unroll") for (int n = 0; n < 2; ++n) _Pragma("unroll") for (int k = 0; k < 2; ++k) dst[n][k] = *(const LAS bf16x8*)(lds + PG8_SB(b, h) + boff + n * 2048 + k * 1024); } while (0)
; #define PG8_MMA(ai, bj, At, Bt) do { __builtin_amdgcn_s_setprio(1); _Pragma("unroll") for (int m = 0; m < 4; ++m) _Pragma("unroll") for (int n = 0; n < 2; ++n) _Pragma("unroll") for (int k = 0; k < 2; ++k) \
;         acc[ai][bj][m][n] = __builtin_amdgcn_mfma_f32_16x16x32_bf16(Bt[n][k], At[m][k], acc[ai][bj][m][n], 0, 0, 0); __builtin_amdgcn_s_setprio(0); } while (0)
; #define PG8_WAIT_V(n) asm volatile("s_waitcnt vmcnt(" #n ")" ::: "memory")
; #define PG8_WAIT_L(n) asm volatile("s_waitcnt lgkmcnt(" #n ")" ::: "memory")
; #define PG8_BAR __builtin_amdgcn_s_barrier()
; #define PG8_SCHED __builtin_amdgcn_sched_barrier(0)
; template <class Epi, class Sched>
; __device__ __forceinline__ void gemm_phase(LAS unsigned char* lds, const Gemm g, const Sched& S, const Epi& E) {
;     ...
;             PG8_LDB(B0, 1, 0); PG8_LDB(B1, 1, 1); PG8_SCHED; PG8_LDA(At, 1, 0); PG8_STAGE(PG8_SA(0, 1), a2 + hsA, voffA);
;             PG8_WAIT_V(8); PG8_WAIT_L(0); PG8_BAR; PG8_MMA(0, 0, At, B0); PG8_MMA(0, 1, At, B1); PG8_BAR; PG8_SCHED;
	s_add_i32 s74, 0, 0x18000
	s_add_i32 s75, 0, 0x1c000
	v_add_u32_e32 v154, s74, v165
	v_add_u32_e32 v162, s75, v165
	ds_read_b128 v[142:145], v154
	ds_read_b128 v[146:149], v154 offset:1024
	ds_read_b128 v[150:153], v154 offset:2048
	ds_read_b128 v[154:157], v154 offset:3072
	ds_read_b128 v[158:161], v162
	ds_read_b128 v[168:171], v162 offset:1024
	ds_read_b128 v[172:175], v162 offset:2048
	ds_read_b128 v[176:179], v162 offset:3072
	s_add_u32 s42, s42, 0x40000
	s_addc_u32 s43, s43, 0
	s_mov_b32 m0, s64
	v_lshl_add_u64 v[240:241], s[42:43], 0, v[134:135]
	ds_read_b128 v[180:183], v166 offset:32768
	ds_read_b128 v[184:187], v166 offset:33792
	ds_read_b128 v[188:191], v166 offset:34816
	ds_read_b128 v[208:211], v166 offset:35840
	ds_read_b128 v[212:215], v166 offset:36864
	ds_read_b128 v[216:219], v166 offset:37888
	ds_read_b128 v[220:223], v166 offset:38912
	ds_read_b128 v[224:227], v166 offset:39936
	global_load_lds_dwordx4 v[240:241], off
	v_lshl_add_u64 v[240:241], s[42:43], 0, v[132:133]
	s_mov_b32 m0, s78
	s_nop 0
	global_load_lds_dwordx4 v[240:241], off
	s_waitcnt vmcnt(8)
	s_waitcnt lgkmcnt(0)
	s_barrier
	s_waitcnt lgkmcnt(0)
	v_mfma_f32_16x16x32_bf16 v[122:125], v[142:145], v[180:183], v[122:125]
	v_mfma_f32_16x16x32_bf16 v[114:117], v[150:153], v[180:183], v[114:117]
	v_mfma_f32_16x16x32_bf16 v[110:113], v[142:145], v[188:191], v[110:113]
	v_mfma_f32_16x16x32_bf16 v[98:101], v[150:153], v[188:191], v[98:101]
	v_mfma_f32_16x16x32_bf16 v[94:97], v[142:145], v[212:215], v[94:97]
	v_mfma_f32_16x16x32_bf16 v[82:85], v[150:153], v[212:215], v[82:85]
	v_mfma_f32_16x16x32_bf16 v[78:81], v[142:145], v[220:223], v[78:81]
	v_mfma_f32_16x16x32_bf16 v[66:69], v[150:153], v[220:223], v[66:69]
	v_mfma_f32_16x16x32_bf16 v[122:125], v[146:149], v[184:187], v[122:125]
	v_mfma_f32_16x16x32_bf16 v[114:117], v[154:157], v[184:187], v[114:117]
	v_mfma_f32_16x16x32_bf16 v[110:113], v[146:149], v[208:211], v[110:113]
	v_mfma_f32_16x16x32_bf16 v[98:101], v[154:157], v[208:211], v[98:101]
	v_mfma_f32_16x16x32_bf16 v[94:97], v[146:149], v[216:219], v[94:97]
	v_mfma_f32_16x16x32_bf16 v[82:85], v[154:157], v[216:219], v[82:85]
	v_mfma_f32_16x16x32_bf16 v[78:81], v[146:149], v[224:227], v[78:81]
	v_mfma_f32_16x16x32_bf16 v[66:69], v[154:157], v[224:227], v[66:69]
	v_mfma_f32_16x16x32_bf16 v[126:129], v[158:161], v[180:183], v[126:129]
	v_mfma_f32_16x16x32_bf16 v[118:121], v[172:175], v[180:183], v[118:121]
	v_mfma_f32_16x16x32_bf16 v[106:109], v[158:161], v[188:191], v[106:109]
	v_mfma_f32_16x16x32_bf16 v[102:105], v[172:175], v[188:191], v[102:105]
	v_mfma_f32_16x16x32_bf16 v[90:93], v[158:161], v[212:215], v[90:93]
	v_mfma_f32_16x16x32_bf16 v[86:89], v[172:175], v[212:215], v[86:89]
	v_mfma_f32_16x16x32_bf16 v[74:77], v[158:161], v[220:223], v[74:77]
	v_mfma_f32_16x16x32_bf16 v[70:73], v[172:175], v[220:223], v[70:73]
	v_mfma_f32_16x16x32_bf16 v[126:129], v[168:171], v[184:187], v[126:129]
	v_mfma_f32_16x16x32_bf16 v[118:121], v[176:179], v[184:187], v[118:121]
	v_mfma_f32_16x16x32_bf16 v[106:109], v[168:171], v[208:211], v[106:109]
	v_mfma_f32_16x16x32_bf16 v[102:105], v[176:179], v[208:211], v[102:105]
	v_mfma_f32_16x16x32_bf16 v[90:93], v[168:171], v[216:219], v[90:93]
	v_mfma_f32_16x16x32_bf16 v[86:89], v[176:179], v[216:219], v[86:89]
	v_mfma_f32_16x16x32_bf16 v[74:77], v[168:171], v[224:227], v[74:77]
	v_mfma_f32_16x16x32_bf16 v[70:73], v[176:179], v[224:227], v[70:73]
	s_barrier
; #define PG8_STAGE(bufoff, gbase, voff) do { _Pragma("unroll") for (int _i = 0; _i < 2; ++_i) \
;         __builtin_amdgcn_global_load_lds((const unsigned*)((const char*)(gbase) + (voff)[_i]), (LAS unsigned*)(lds + (bufoff) + ldsw + _i * 8192), 16, 0, 0); } while (0)
; #define PG8_LDA(dst, b, h) do { _Pragma("unroll") for (int m = 0; m < 4; ++m) _Pragma("unroll") for (int k = 0; k < 2; ++k) dst[m][k] = *(const LAS bf16x8*)(lds + PG8_SA(b, h) + aoff + m * 2048 + k * 1024); } while (0)
; #define PG8_MMA(ai, bj, At, Bt) do { __builtin_amdgcn_s_setprio(1); _Pragma("unroll") for (int m = 0; m < 4; ++m) _Pragma("unroll") for (int n = 0; n < 2; ++n) _Pragma("unroll") for (int k = 0; k < 2; ++k) \
;         acc[ai][bj][m][n] = __builtin_amdgcn_mfma_f32_16x16x32_bf16(Bt[n][k], At[m][k], acc[ai][bj][m][n], 0, 0, 0); __builtin_amdgcn_s_setprio(0); } while (0)
; #define PG8_WAIT_V(n) asm volatile("s_waitcnt vmcnt(" #n ")" ::: "memory")
; #define PG8_WAIT_L(n) asm volatile("s_waitcnt lgkmcnt(" #n ")" ::: "memory")
; #define PG8_BAR __builtin_amdgcn_s_barrier()
; #define PG8_SCHED __builtin_amdgcn_sched_barrier(0)
; template <class Epi, class Sched>
; __device__ __forceinline__ void gemm_phase(LAS unsigned char* lds, const Gemm g, const Sched& S, const Epi& E) {
;     ...
;             PG8_LDA(At, 1, 1); PG8_STAGE(PG8_SB(1, 0), b3, voffB); PG8_STAGE(PG8_SB(1, 1), b3 + hsB, voffB); PG8_STAGE(PG8_SA(1, 0), a3, voffA);
;             PG8_WAIT_V(8); PG8_WAIT_L(0); PG8_BAR; PG8_MMA(1, 0, At, B0); PG8_MMA(1, 1, At, B1); PG8_BAR; PG8_SCHED;
;         }
	s_add_i32 s42, s74, s12
	v_lshl_add_u64 v[228:229], v[228:229], 0, s[18:19]
	s_mov_b32 m0, s42
	ds_read_b128 v[180:183], v166 offset:49152
	ds_read_b128 v[184:187], v166 offset:50176
	ds_read_b128 v[188:191], v166 offset:51200
	ds_read_b128 v[208:211], v166 offset:52224
	ds_read_b128 v[212:215], v166 offset:53248
	ds_read_b128 v[216:219], v166 offset:54272
	ds_read_b128 v[220:223], v166 offset:55296
	ds_read_b128 v[224:227], v166 offset:56320
	global_load_lds_dwordx4 v[228:229], off
	s_add_i32 m0, s42, 0x2000
	s_add_u32 s40, s40, 0x40080
	v_lshl_add_u64 v[228:229], v[230:231], 0, s[18:19]
	s_addc_u32 s41, s41, 0
	s_add_i32 s42, s75, s12
	global_load_lds_dwordx4 v[228:229], off
	v_lshl_add_u64 v[228:229], s[40:41], 0, v[0:1]
	s_mov_b32 m0, s42
	s_nop 0
	global_load_lds_dwordx4 v[228:229], off
	v_lshl_add_u64 v[228:229], s[40:41], 0, v[130:131]
	s_add_i32 m0, s42, 0x2000
	s_nop 0
	global_load_lds_dwordx4 v[228:229], off
	v_lshl_add_u64 v[228:229], v[232:233], 0, s[18:19]
	s_mov_b32 m0, s1
	s_nop 0
	global_load_lds_dwordx4 v[228:229], off
	v_lshl_add_u64 v[228:229], v[238:239], 0, s[18:19]
	s_mov_b32 m0, s7
	s_nop 0
	global_load_lds_dwordx4 v[228:229], off
	s_waitcnt vmcnt(8)
	s_waitcnt lgkmcnt(0)
	s_barrier
	s_waitcnt lgkmcnt(0)
	v_mfma_f32_16x16x32_bf16 v[62:65], v[142:145], v[180:183], v[62:65]
	v_mfma_f32_16x16x32_bf16 v[50:53], v[150:153], v[180:183], v[50:53]
	v_mfma_f32_16x16x32_bf16 v[46:49], v[142:145], v[188:191], v[46:49]
	v_mfma_f32_16x16x32_bf16 v[34:37], v[150:153], v[188:191], v[34:37]
	v_mfma_f32_16x16x32_bf16 v[30:33], v[142:145], v[212:215], v[30:33]
	v_mfma_f32_16x16x32_bf16 v[18:21], v[150:153], v[212:215], v[18:21]
	v_mfma_f32_16x16x32_bf16 v[10:13], v[142:145], v[220:223], v[10:13]
	v_mfma_f32_16x16x32_bf16 v[2:5], v[150:153], v[220:223], v[2:5]
	v_mfma_f32_16x16x32_bf16 v[62:65], v[146:149], v[184:187], v[62:65]
	v_mfma_f32_16x16x32_bf16 v[50:53], v[154:157], v[184:187], v[50:53]
	v_mfma_f32_16x16x32_bf16 v[46:49], v[146:149], v[208:211], v[46:49]
	v_mfma_f32_16x16x32_bf16 v[34:37], v[154:157], v[208:211], v[34:37]
	v_mfma_f32_16x16x32_bf16 v[30:33], v[146:149], v[216:219], v[30:33]
	v_mfma_f32_16x16x32_bf16 v[18:21], v[154:157], v[216:219], v[18:21]
	v_mfma_f32_16x16x32_bf16 v[10:13], v[146:149], v[224:227], v[10:13]
	v_mfma_f32_16x16x32_bf16 v[2:5], v[154:157], v[224:227], v[2:5]
	v_mfma_f32_16x16x32_bf16 v[58:61], v[158:161], v[180:183], v[58:61]
	v_mfma_f32_16x16x32_bf16 v[54:57], v[172:175], v[180:183], v[54:57]
	v_mfma_f32_16x16x32_bf16 v[42:45], v[158:161], v[188:191], v[42:45]
	v_mfma_f32_16x16x32_bf16 v[38:41], v[172:175], v[188:191], v[38:41]
	v_mfma_f32_16x16x32_bf16 v[26:29], v[158:161], v[212:215], v[26:29]
	v_mfma_f32_16x16x32_bf16 v[22:25], v[172:175], v[212:215], v[22:25]
	v_mfma_f32_16x16x32_bf16 v[14:17], v[158:161], v[220:223], v[14:17]
	v_mfma_f32_16x16x32_bf16 v[6:9], v[172:175], v[220:223], v[6:9]
	v_mfma_f32_16x16x32_bf16 v[58:61], v[168:171], v[184:187], v[58:61]
	v_mfma_f32_16x16x32_bf16 v[54:57], v[176:179], v[184:187], v[54:57]
	v_mfma_f32_16x16x32_bf16 v[42:45], v[168:171], v[208:211], v[42:45]
	v_mfma_f32_16x16x32_bf16 v[38:41], v[176:179], v[208:211], v[38:41]
	v_mfma_f32_16x16x32_bf16 v[26:29], v[168:171], v[216:219], v[26:29]
	v_mfma_f32_16x16x32_bf16 v[22:25], v[176:179], v[216:219], v[22:25]
	v_mfma_f32_16x16x32_bf16 v[14:17], v[168:171], v[224:227], v[14:17]
	v_mfma_f32_16x16x32_bf16 v[6:9], v[176:179], v[224:227], v[6:9]
	s_barrier
	s_add_u32 s38, s38, 0x100
	s_addc_u32 s39, s39, 0
	s_add_u32 s83, s83, 0x100
	s_addc_u32 s84, s84, 0
	s_cmp_ge_i32 s85, s11
	s_mov_b32 s40, s85
	s_cbranch_scc0 .LBB0_485
	s_setprio 0

; #define PG8_STAGE(bufoff, gbase, voff) do { _Pragma("unroll") for (int _i = 0; _i < 2; ++_i) \
;         __builtin_amdgcn_global_load_lds((const unsigned*)((const char*)(gbase) + (voff)[_i]), (LAS unsigned*)(lds + (bufoff) + ldsw + _i * 8192), 16, 0, 0); } while (0)
; #define PG8_LDA(dst, b, h) do { _Pragma("unroll") for (int m = 0; m < 4; ++m) _Pragma("unroll") for (int k = 0; k < 2; ++k) dst[m][k] = *(const LAS bf16x8*)(lds + PG8_SA(b, h) + aoff + m * 2048 + k * 1024); } while (0)
; #define PG8_LDB(dst, b, h) do { _Pragma("unroll") for (int n = 0; n < 2; ++n) _Pragma("unroll") for (int k = 0; k < 2; ++k) dst[n][k] = *(const LAS bf16x8*)(lds + PG8_SB(b, h) + boff + n * 2048 + k * 1024); } while (0)
; #define PG8_WAIT_V(n) asm volatile("s_waitcnt vmcnt(" #n ")" ::: "memory")
; #define PG8_WAIT_L(n) asm volatile("s_waitcnt lgkmcnt(" #n ")" ::: "memory")
; #define PG8_BAR __builtin_amdgcn_s_barrier()
; template <class Epi, class Sched>
; __device__ __forceinline__ void gemm_phase(LAS unsigned char* lds, const Gemm g, const Sched& S, const Epi& E) {
;     ...
;         const bool has_next = S.next(ui + 1, nxt);
;         const char* nA = has_next ? (const char*)g.A + nxt.offA : cA; const char* nB = has_next ? (const char*)g.Bt + nxt.offB : cB;
;         for (int t = 0; t < nt; t += 2) {
;             const bool last = (t == nt - 2);
;             const char* a1 = cA + (size_t)(t + 1) * kstep;
;             const char* a2 = last ? nA : cA + (size_t)(t + 2) * kstep; const char* b2 = last ? nB : cB + (size_t)(t + 2) * kstep;
;             const char* a3 = a2 + kstep; const char* b3 = b2 + kstep;
;             if constexpr (Epi::MIDK) { if (t == (nt >> 1)) { int fr_ = fr, fq_ = fq; asm volatile("" : "+v"(fr_), "+v"(fq_)); E.mid(acc, cur, wr, wc, fr_, fq_); } }
;             PG8_LDB(B0, 0, 0); PG8_LDB(B1, 0, 1); PG8_SCHED; PG8_LDA(At, 0, 0); PG8_STAGE(PG8_SA(1, 1), a1 + hsA, voffA);
;             PG8_WAIT_V(8); PG8_WAIT_L(0); PG8_BAR; PG8_MMA(0, 0, At, B0); PG8_MMA(0, 1, At, B1); PG8_BAR; PG8_SCHED;
;     ...
; #pragma unroll
;         for (int a = 0; a < 2; ++a)
; #pragma unroll
;             for (int b = 0; b < 2; ++b)
; #pragma unroll
;                 for (int m = 0; m < 4; ++m)
; #pragma unroll
;                     for (int n = 0; n < 2; ++n) acc[a][b][m][n] = (f32x4){0.f, 0.f, 0.f, 0.f};
;         cur = nxt; cA = nA; cB = nB; ++ui;
.LBB0_534:
	v_readlane_b32 s22, v251, 29
	v_readlane_b32 s23, v251, 30
	s_add_u32 s40, s22, s34
	s_addc_u32 s41, s23, s35
	s_add_u32 s42, s2, s36
	s_addc_u32 s43, s3, s37
	s_andn2_b64 vcc, exec, s[8:9]
	s_cbranch_vccnz .Lzc_13474
	s_and_b64 s[76:77], s[38:39], exec
	s_cselect_b32 s73, s41, s45
	s_cselect_b32 s76, s40, s44
	s_cselect_b32 s77, s43, s47
	s_cselect_b32 s78, s42, s46
	s_add_u32 s44, s44, 0x40080
	s_addc_u32 s45, s45, 0
	s_add_u32 s80, s46, 0x100
	v_mov_b32_e32 v2, 0
	s_addc_u32 s82, s47, 0
	s_mov_b32 s46, 0
	v_mov_b32_e32 v3, v2
	v_mov_b32_e32 v4, v2
	v_mov_b32_e32 v5, v2
	v_mov_b32_e32 v6, v2
	v_mov_b32_e32 v7, v2
	v_mov_b32_e32 v8, v2
	v_mov_b32_e32 v9, v2
	v_mov_b32_e32 v18, v2
	v_mov_b32_e32 v19, v2
	v_mov_b32_e32 v20, v2
	v_mov_b32_e32 v21, v2
	v_mov_b32_e32 v22, v2
	v_mov_b32_e32 v23, v2
	v_mov_b32_e32 v24, v2
	v_mov_b32_e32 v25, v2
	v_mov_b32_e32 v34, v2
	v_mov_b32_e32 v35, v2
	v_mov_b32_e32 v36, v2
	v_mov_b32_e32 v37, v2
	v_mov_b32_e32 v38, v2
	v_mov_b32_e32 v39, v2
	v_mov_b32_e32 v40, v2
	v_mov_b32_e32 v41, v2
	v_mov_b32_e32 v50, v2
	v_mov_b32_e32 v51, v2
	v_mov_b32_e32 v52, v2
	v_mov_b32_e32 v53, v2
	v_mov_b32_e32 v54, v2
	v_mov_b32_e32 v55, v2
	v_mov_b32_e32 v56, v2
	v_mov_b32_e32 v57, v2
	v_mov_b32_e32 v10, v2
	v_mov_b32_e32 v11, v2
	v_mov_b32_e32 v12, v2
	v_mov_b32_e32 v13, v2
	v_mov_b32_e32 v14, v2
	v_mov_b32_e32 v15, v2
	v_mov_b32_e32 v16, v2
	v_mov_b32_e32 v17, v2
	v_mov_b32_e32 v26, v2
	v_mov_b32_e32 v27, v2
	v_mov_b32_e32 v28, v2
	v_mov_b32_e32 v29, v2
	v_mov_b32_e32 v30, v2
	v_mov_b32_e32 v31, v2
	v_mov_b32_e32 v32, v2
	v_mov_b32_e32 v33, v2
	v_mov_b32_e32 v42, v2
	v_mov_b32_e32 v43, v2
	v_mov_b32_e32 v44, v2
	v_mov_b32_e32 v45, v2
	v_mov_b32_e32 v46, v2
	v_mov_b32_e32 v47, v2
	v_mov_b32_e32 v48, v2
	v_mov_b32_e32 v49, v2
	v_mov_b32_e32 v58, v2
	v_mov_b32_e32 v59, v2
	v_mov_b32_e32 v60, v2
	v_mov_b32_e32 v61, v2
	v_mov_b32_e32 v62, v2
	v_mov_b32_e32 v63, v2
	v_mov_b32_e32 v64, v2
	v_mov_b32_e32 v65, v2
	v_mov_b32_e32 v66, v2
	v_mov_b32_e32 v67, v2
	v_mov_b32_e32 v68, v2
	v_mov_b32_e32 v69, v2
	v_mov_b32_e32 v70, v2
	v_mov_b32_e32 v71, v2
	v_mov_b32_e32 v72, v2
	v_mov_b32_e32 v73, v2
	v_mov_b32_e32 v82, v2
	v_mov_b32_e32 v83, v2
	v_mov_b32_e32 v84, v2
	v_mov_b32_e32 v85, v2
	v_mov_b32_e32 v86, v2
	v_mov_b32_e32 v87, v2
	v_mov_b32_e32 v88, v2
	v_mov_b32_e32 v89, v2
	v_mov_b32_e32 v98, v2
	v_mov_b32_e32 v99, v2
	v_mov_b32_e32 v100, v2
	v_mov_b32_e32 v101, v2
	v_mov_b32_e32 v102, v2
	v_mov_b32_e32 v103, v2
	v_mov_b32_e32 v104, v2
	v_mov_b32_e32 v105, v2
	v_mov_b32_e32 v114, v2
	v_mov_b32_e32 v115, v2
	v_mov_b32_e32 v116, v2
	v_mov_b32_e32 v117, v2
	v_mov_b32_e32 v118, v2
	v_mov_b32_e32 v119, v2
	v_mov_b32_e32 v120, v2
	v_mov_b32_e32 v121, v2
	v_mov_b32_e32 v74, v2
	v_mov_b32_e32 v75, v2
	v_mov_b32_e32 v76, v2
	v_mov_b32_e32 v77, v2
	v_mov_b32_e32 v78, v2
	v_mov_b32_e32 v79, v2
	v_mov_b32_e32 v80, v2
	v_mov_b32_e32 v81, v2
	v_mov_b32_e32 v90, v2
	v_mov_b32_e32 v91, v2
	v_mov_b32_e32 v92, v2
	v_mov_b32_e32 v93, v2
	v_mov_b32_e32 v94, v2
	v_mov_b32_e32 v95, v2
	v_mov_b32_e32 v96, v2
	v_mov_b32_e32 v97, v2
	v_mov_b32_e32 v106, v2
	v_mov_b32_e32 v107, v2
	v_mov_b32_e32 v108, v2
	v_mov_b32_e32 v109, v2
	v_mov_b32_e32 v110, v2
	v_mov_b32_e32 v111, v2
	v_mov_b32_e32 v112, v2
	v_mov_b32_e32 v113, v2
	v_mov_b32_e32 v126, v2
	v_mov_b32_e32 v127, v2
	v_mov_b32_e32 v128, v2
	v_mov_b32_e32 v129, v2
	v_mov_b32_e32 v122, v2
	v_mov_b32_e32 v123, v2
	v_mov_b32_e32 v124, v2
	v_mov_b32_e32 v125, v2
	s_mov_b64 s[22:23], 0x800
	s_mov_b64 vcc, 0x880
	v_readfirstlane_b32 s83, v193
	s_lshr_b32 s83, s83, 8
	s_cmp_eq_u32 s83, 1
	s_cbranch_scc0 .Lnp_536
	s_setprio 1
.Lnp_536:
.LBB0_536:
	s_add_i32 s83, s46, 2
	s_add_u32 s74, s44, 0xfffc0080
	s_addc_u32 s47, s45, -1
	s_add_i32 s75, 0, 0x10000
	s_cmp_eq_u32 s51, s46
	s_cselect_b32 s47, s73, s47
	s_cselect_b32 s46, s76, s74
	v_add_u32_e32 v144, s75, v148
	s_cselect_b32 s85, s77, s82
	s_cselect_b32 s84, s78, s80
	s_add_i32 s74, 0, 0x14000
	ds_read_b128 v[140:143], v144
	ds_read_b128 v[150:153], v144 offset:1024
	ds_read_b128 v[154:157], v144 offset:2048
	ds_read_b128 v[158:161], v144 offset:3072
	v_add_u32_e32 v144, s74, v148
	ds_read_b128 v[162:165], v144
	ds_read_b128 v[166:169], v144 offset:1024
	ds_read_b128 v[170:173], v144 offset:2048
	ds_read_b128 v[174:177], v144 offset:3072
	v_lshl_add_u64 v[144:145], s[44:45], 0, v[136:137]
	s_add_i32 m0, s11, 0xc000
	ds_read_b128 v[178:181], v149
	ds_read_b128 v[182:185], v149 offset:1024
	ds_read_b128 v[186:189], v149 offset:2048
	ds_read_b128 v[208:211], v149 offset:3072
	ds_read_b128 v[212:215], v149 offset:4096
	ds_read_b128 v[216:219], v149 offset:5120
	ds_read_b128 v[220:223], v149 offset:6144
	ds_read_b128 v[224:227], v149 offset:7168
	global_load_lds_dwordx4 v[144:145], off
	v_lshl_add_u64 v[144:145], s[44:45], 0, v[138:139]
	s_add_i32 m0, s11, 0xe000
	s_nop 0
	global_load_lds_dwordx4 v[144:145], off
	s_waitcnt vmcnt(8)
	s_waitcnt lgkmcnt(0)
	s_barrier
; #define PG8_STAGE(bufoff, gbase, voff) do { _Pragma("unroll") for (int _i = 0; _i < 2; ++_i) \
;         __builtin_amdgcn_global_load_lds((const unsigned*)((const char*)(gbase) + (voff)[_i]), (LAS unsigned*)(lds + (bufoff) + ldsw + _i * 8192), 16, 0, 0); } while (0)
; #define PG8_LDA(dst, b, h) do { _Pragma("unroll") for (int m = 0; m < 4; ++m) _Pragma("unroll") for (int k = 0; k < 2; ++k) dst[m][k] = *(const LAS bf16x8*)(lds + PG8_SA(b, h) + aoff + m * 2048 + k * 1024); } while (0)
; #define PG8_MMA(ai, bj, At, Bt) do { __builtin_amdgcn_s_setprio(1); _Pragma("unroll") for (int m = 0; m < 4; ++m) _Pragma("unroll") for (int n = 0; n < 2; ++n) _Pragma("unroll") for (int k = 0; k < 2; ++k) \
;         acc[ai][bj][m][n] = __builtin_amdgcn_mfma_f32_16x16x32_bf16(Bt[n][k], At[m][k], acc[ai][bj][m][n], 0, 0, 0); __builtin_amdgcn_s_setprio(0); } while (0)
; #define PG8_WAIT_V(n) asm volatile("s_waitcnt vmcnt(" #n ")" ::: "memory")
; #define PG8_WAIT_L(n) asm volatile("s_waitcnt lgkmcnt(" #n ")" ::: "memory")
; #define PG8_BAR __builtin_amdgcn_s_barrier()
; #define PG8_SCHED __builtin_amdgcn_sched_barrier(0)
; template <class Epi, class Sched>
; __device__ __forceinline__ void gemm_phase(LAS unsigned char* lds, const Gemm g, const Sched& S, const Epi& E) {
;     ...
;             PG8_WAIT_V(8); PG8_WAIT_L(0); PG8_BAR; PG8_MMA(0, 0, At, B0); PG8_MMA(0, 1, At, B1); PG8_BAR; PG8_SCHED;
;             PG8_LDA(At, 0, 1); PG8_STAGE(PG8_SB(0, 0), b2, voffB); PG8_STAGE(PG8_SB(0, 1), b2 + hsB, voffB); PG8_STAGE(PG8_SA(0, 0), a2, voffA);
;             PG8_WAIT_V(8); PG8_WAIT_L(0); PG8_BAR; PG8_MMA(1, 0, At, B0); PG8_MMA(1, 1, At, B1); PG8_BAR; PG8_SCHED;
	s_waitcnt lgkmcnt(0)
	v_mfma_f32_16x16x32_bf16 v[122:125], v[140:143], v[178:181], v[122:125]
	v_mfma_f32_16x16x32_bf16 v[126:129], v[154:157], v[178:181], v[126:129]
	v_mfma_f32_16x16x32_bf16 v[110:113], v[140:143], v[186:189], v[110:113]
	v_mfma_f32_16x16x32_bf16 v[106:109], v[154:157], v[186:189], v[106:109]
	v_mfma_f32_16x16x32_bf16 v[94:97], v[140:143], v[212:215], v[94:97]
	v_mfma_f32_16x16x32_bf16 v[90:93], v[154:157], v[212:215], v[90:93]
	v_mfma_f32_16x16x32_bf16 v[78:81], v[140:143], v[220:223], v[78:81]
	v_mfma_f32_16x16x32_bf16 v[74:77], v[154:157], v[220:223], v[74:77]
	v_mfma_f32_16x16x32_bf16 v[122:125], v[150:153], v[182:185], v[122:125]
	v_mfma_f32_16x16x32_bf16 v[126:129], v[158:161], v[182:185], v[126:129]
	v_mfma_f32_16x16x32_bf16 v[110:113], v[150:153], v[208:211], v[110:113]
	v_mfma_f32_16x16x32_bf16 v[106:109], v[158:161], v[208:211], v[106:109]
	v_mfma_f32_16x16x32_bf16 v[94:97], v[150:153], v[216:219], v[94:97]
	v_mfma_f32_16x16x32_bf16 v[90:93], v[158:161], v[216:219], v[90:93]
	v_mfma_f32_16x16x32_bf16 v[78:81], v[150:153], v[224:227], v[78:81]
	v_mfma_f32_16x16x32_bf16 v[74:77], v[158:161], v[224:227], v[74:77]
	v_mfma_f32_16x16x32_bf16 v[118:121], v[162:165], v[178:181], v[118:121]
	v_mfma_f32_16x16x32_bf16 v[114:117], v[170:173], v[178:181], v[114:117]
	v_mfma_f32_16x16x32_bf16 v[102:105], v[162:165], v[186:189], v[102:105]
	v_mfma_f32_16x16x32_bf16 v[98:101], v[170:173], v[186:189], v[98:101]
	v_mfma_f32_16x16x32_bf16 v[86:89], v[162:165], v[212:215], v[86:89]
	v_mfma_f32_16x16x32_bf16 v[82:85], v[170:173], v[212:215], v[82:85]
	v_mfma_f32_16x16x32_bf16 v[70:73], v[162:165], v[220:223], v[70:73]
	v_mfma_f32_16x16x32_bf16 v[66:69], v[170:173], v[220:223], v[66:69]
	v_mfma_f32_16x16x32_bf16 v[118:121], v[166:169], v[182:185], v[118:121]
	v_mfma_f32_16x16x32_bf16 v[114:117], v[174:177], v[182:185], v[114:117]
	v_mfma_f32_16x16x32_bf16 v[102:105], v[166:169], v[208:211], v[102:105]
	v_mfma_f32_16x16x32_bf16 v[98:101], v[174:177], v[208:211], v[98:101]
	v_mfma_f32_16x16x32_bf16 v[86:89], v[166:169], v[216:219], v[86:89]
	v_mfma_f32_16x16x32_bf16 v[82:85], v[174:177], v[216:219], v[82:85]
	v_mfma_f32_16x16x32_bf16 v[70:73], v[166:169], v[224:227], v[70:73]
	v_mfma_f32_16x16x32_bf16 v[66:69], v[174:177], v[224:227], v[66:69]
	s_barrier
	s_add_i32 s75, s75, s7
	v_lshl_add_u64 v[144:145], s[84:85], 0, v[0:1]
	s_mov_b32 m0, s75
	ds_read_b128 v[178:181], v149 offset:16384
	ds_read_b128 v[182:185], v149 offset:17408
	ds_read_b128 v[186:189], v149 offset:18432
	ds_read_b128 v[208:211], v149 offset:19456
	ds_read_b128 v[212:215], v149 offset:20480
	ds_read_b128 v[216:219], v149 offset:21504
	ds_read_b128 v[220:223], v149 offset:22528
	ds_read_b128 v[224:227], v149 offset:23552
	global_load_lds_dwordx4 v[144:145], off
	v_lshl_add_u64 v[190:191], s[84:85], 0, v[130:131]
	s_add_i32 m0, s75, 0x2000
	s_add_i32 s74, s74, s7
	global_load_lds_dwordx4 v[190:191], off
	v_lshl_add_u64 v[228:229], v[144:145], 0, s[22:23]
	s_mov_b32 m0, s74
	v_lshl_add_u64 v[230:231], s[46:47], 0, v[132:133]
	global_load_lds_dwordx4 v[228:229], off
	v_lshl_add_u64 v[228:229], v[190:191], 0, s[22:23]
	s_add_i32 m0, s74, 0x2000
	s_nop 0
	global_load_lds_dwordx4 v[228:229], off
	v_lshl_add_u64 v[228:229], s[46:47], 0, v[134:135]
	s_mov_b32 m0, s11
	s_nop 0
	global_load_lds_dwordx4 v[228:229], off
	s_mov_b32 m0, s12
	s_nop 0
	global_load_lds_dwordx4 v[230:231], off
	s_waitcnt vmcnt(8)
	s_waitcnt lgkmcnt(0)
	s_barrier
	s_waitcnt lgkmcnt(0)
	v_mfma_f32_16x16x32_bf16 v[62:65], v[140:143], v[178:181], v[62:65]
	v_mfma_f32_16x16x32_bf16 v[58:61], v[154:157], v[178:181], v[58:61]
	v_mfma_f32_16x16x32_bf16 v[46:49], v[140:143], v[186:189], v[46:49]
	v_mfma_f32_16x16x32_bf16 v[42:45], v[154:157], v[186:189], v[42:45]
	v_mfma_f32_16x16x32_bf16 v[30:33], v[140:143], v[212:215], v[30:33]
	v_mfma_f32_16x16x32_bf16 v[26:29], v[154:157], v[212:215], v[26:29]
	v_mfma_f32_16x16x32_bf16 v[14:17], v[140:143], v[220:223], v[14:17]
	v_mfma_f32_16x16x32_bf16 v[10:13], v[154:157], v[220:223], v[10:13]
	v_mfma_f32_16x16x32_bf16 v[62:65], v[150:153], v[182:185], v[62:65]
	v_mfma_f32_16x16x32_bf16 v[58:61], v[158:161], v[182:185], v[58:61]
	v_mfma_f32_16x16x32_bf16 v[46:49], v[150:153], v[208:211], v[46:49]
	v_mfma_f32_16x16x32_bf16 v[42:45], v[158:161], v[208:211], v[42:45]
	v_mfma_f32_16x16x32_bf16 v[30:33], v[150:153], v[216:219], v[30:33]
	v_mfma_f32_16x16x32_bf16 v[26:29], v[158:161], v[216:219], v[26:29]
	v_mfma_f32_16x16x32_bf16 v[14:17], v[150:153], v[224:227], v[14:17]
	v_mfma_f32_16x16x32_bf16 v[10:13], v[158:161], v[224:227], v[10:13]
	v_mfma_f32_16x16x32_bf16 v[54:57], v[162:165], v[178:181], v[54:57]
	v_mfma_f32_16x16x32_bf16 v[50:53], v[170:173], v[178:181], v[50:53]
	v_mfma_f32_16x16x32_bf16 v[38:41], v[162:165], v[186:189], v[38:41]
	v_mfma_f32_16x16x32_bf16 v[34:37], v[170:173], v[186:189], v[34:37]
	v_mfma_f32_16x16x32_bf16 v[22:25], v[162:165], v[212:215], v[22:25]
	v_mfma_f32_16x16x32_bf16 v[18:21], v[170:173], v[212:215], v[18:21]
	v_mfma_f32_16x16x32_bf16 v[6:9], v[162:165], v[220:223], v[6:9]
	v_mfma_f32_16x16x32_bf16 v[2:5], v[170:173], v[220:223], v[2:5]
	v_mfma_f32_16x16x32_bf16 v[54:57], v[166:169], v[182:185], v[54:57]
	v_mfma_f32_16x16x32_bf16 v[50:53], v[174:177], v[182:185], v[50:53]
	v_mfma_f32_16x16x32_bf16 v[38:41], v[166:169], v[208:211], v[38:41]
	v_mfma_f32_16x16x32_bf16 v[34:37], v[174:177], v[208:211], v[34:37]
	v_mfma_f32_16x16x32_bf16 v[22:25], v[166:169], v[216:219], v[22:25]
	v_mfma_f32_16x16x32_bf16 v[18:21], v[174:177], v[216:219], v[18:21]
	v_mfma_f32_16x16x32_bf16 v[6:9], v[166:169], v[224:227], v[6:9]
	v_mfma_f32_16x16x32_bf16 v[2:5], v[174:177], v[224:227], v[2:5]
	s_barrier
; #define PG8_STAGE(bufoff, gbase, voff) do { _Pragma("unroll") for (int _i = 0; _i < 2; ++_i) \
;         __builtin_amdgcn_global_load_lds((const unsigned*)((const char*)(gbase) + (voff)[_i]), (LAS unsigned*)(lds + (bufoff) + ldsw + _i * 8192), 16, 0, 0); } while (0)
; #define PG8_LDA(dst, b, h) do { _Pragma("unroll") for (int m = 0; m < 4; ++m) _Pragma("unroll") for (int k = 0; k < 2; ++k) dst[m][k] = *(const LAS bf16x8*)(lds + PG8_SA(b, h) + aoff + m * 2048 + k * 1024); } while (0)
; #define PG8_LDB(dst, b, h) do { _Pragma("unroll") for (int n = 0; n < 2; ++n) _Pragma("unroll") for (int k = 0; k < 2; ++k) dst[n][k] = *(const LAS bf16x8*)(lds + PG8_SB(b, h) + boff + n * 2048 + k * 1024); } while (0)
; #define PG8_MMA(ai, bj, At, Bt) do { __builtin_amdgcn_s_setprio(1); _Pragma("unroll") for (int m = 0; m < 4; ++m) _Pragma("unroll") for (int n = 0; n < 2; ++n) _Pragma("unroll") for (int k = 0; k < 2; ++k) \
;         acc[ai][bj][m][n] = __builtin_amdgcn_mfma_f32_16x16x32_bf16(Bt[n][k], At[m][k], acc[ai][bj][m][n], 0, 0, 0); __builtin_amdgcn_s_setprio(0); } while (0)
; #define PG8_WAIT_V(n) asm volatile("s_waitcnt vmcnt(" #n ")" ::: "memory")
; #define PG8_WAIT_L(n) asm volatile("s_waitcnt lgkmcnt(" #n ")" ::: "memory")
; #define PG8_BAR __builtin_amdgcn_s_barrier()
; #define PG8_SCHED __builtin_amdgcn_sched_barrier(0)
; template <class Epi, class Sched>
; __device__ __forceinline__ void gemm_phase(LAS unsigned char* lds, const Gemm g, const Sched& S, const Epi& E) {
;     ...
;             PG8_LDB(B0, 1, 0); PG8_LDB(B1, 1, 1); PG8_SCHED; PG8_LDA(At, 1, 0); PG8_STAGE(PG8_SA(0, 1), a2 + hsA, voffA);
;             PG8_WAIT_V(8); PG8_WAIT_L(0); PG8_BAR; PG8_MMA(0, 0, At, B0); PG8_MMA(0, 1, At, B1); PG8_BAR; PG8_SCHED;
	s_add_i32 s74, 0, 0x18000
	s_add_i32 s75, 0, 0x1c000
	v_add_u32_e32 v158, s74, v148
	v_add_u32_e32 v174, s75, v148
	ds_read_b128 v[140:143], v158
	ds_read_b128 v[150:153], v158 offset:1024
	ds_read_b128 v[154:157], v158 offset:2048
	ds_read_b128 v[158:161], v158 offset:3072
	ds_read_b128 v[162:165], v174
	ds_read_b128 v[166:169], v174 offset:1024
	ds_read_b128 v[170:173], v174 offset:2048
	ds_read_b128 v[174:177], v174 offset:3072
	s_add_u32 s46, s46, 0x40000
	s_addc_u32 s47, s47, 0
	s_mov_b32 m0, s16
	v_lshl_add_u64 v[232:233], s[46:47], 0, v[134:135]
	ds_read_b128 v[178:181], v149 offset:32768
	ds_read_b128 v[182:185], v149 offset:33792
	ds_read_b128 v[186:189], v149 offset:34816
	ds_read_b128 v[208:211], v149 offset:35840
	ds_read_b128 v[212:215], v149 offset:36864
	ds_read_b128 v[216:219], v149 offset:37888
	ds_read_b128 v[220:223], v149 offset:38912
	ds_read_b128 v[224:227], v149 offset:39936
	global_load_lds_dwordx4 v[232:233], off
	v_lshl_add_u64 v[232:233], s[46:47], 0, v[132:133]
	s_mov_b32 m0, s24
	s_nop 0
	global_load_lds_dwordx4 v[232:233], off
	s_waitcnt vmcnt(8)
	s_waitcnt lgkmcnt(0)
	s_barrier
	s_waitcnt lgkmcnt(0)
	v_mfma_f32_16x16x32_bf16 v[122:125], v[140:143], v[178:181], v[122:125]
	v_mfma_f32_16x16x32_bf16 v[126:129], v[154:157], v[178:181], v[126:129]
	v_mfma_f32_16x16x32_bf16 v[110:113], v[140:143], v[186:189], v[110:113]
	v_mfma_f32_16x16x32_bf16 v[106:109], v[154:157], v[186:189], v[106:109]
	v_mfma_f32_16x16x32_bf16 v[94:97], v[140:143], v[212:215], v[94:97]
	v_mfma_f32_16x16x32_bf16 v[90:93], v[154:157], v[212:215], v[90:93]
	v_mfma_f32_16x16x32_bf16 v[78:81], v[140:143], v[220:223], v[78:81]
	v_mfma_f32_16x16x32_bf16 v[74:77], v[154:157], v[220:223], v[74:77]
	v_mfma_f32_16x16x32_bf16 v[122:125], v[150:153], v[182:185], v[122:125]
	v_mfma_f32_16x16x32_bf16 v[126:129], v[158:161], v[182:185], v[126:129]
	v_mfma_f32_16x16x32_bf16 v[110:113], v[150:153], v[208:211], v[110:113]
	v_mfma_f32_16x16x32_bf16 v[106:109], v[158:161], v[208:211], v[106:109]
	v_mfma_f32_16x16x32_bf16 v[94:97], v[150:153], v[216:219], v[94:97]
	v_mfma_f32_16x16x32_bf16 v[90:93], v[158:161], v[216:219], v[90:93]
	v_mfma_f32_16x16x32_bf16 v[78:81], v[150:153], v[224:227], v[78:81]
	v_mfma_f32_16x16x32_bf16 v[74:77], v[158:161], v[224:227], v[74:77]
	v_mfma_f32_16x16x32_bf16 v[118:121], v[162:165], v[178:181], v[118:121]
	v_mfma_f32_16x16x32_bf16 v[114:117], v[170:173], v[178:181], v[114:117]
	v_mfma_f32_16x16x32_bf16 v[102:105], v[162:165], v[186:189], v[102:105]
	v_mfma_f32_16x16x32_bf16 v[98:101], v[170:173], v[186:189], v[98:101]
	v_mfma_f32_16x16x32_bf16 v[86:89], v[162:165], v[212:215], v[86:89]
	v_mfma_f32_16x16x32_bf16 v[82:85], v[170:173], v[212:215], v[82:85]
	v_mfma_f32_16x16x32_bf16 v[70:73], v[162:165], v[220:223], v[70:73]
	v_mfma_f32_16x16x32_bf16 v[66:69], v[170:173], v[220:223], v[66:69]
	v_mfma_f32_16x16x32_bf16 v[118:121], v[166:169], v[182:185], v[118:121]
	v_mfma_f32_16x16x32_bf16 v[114:117], v[174:177], v[182:185], v[114:117]
	v_mfma_f32_16x16x32_bf16 v[102:105], v[166:169], v[208:211], v[102:105]
	v_mfma_f32_16x16x32_bf16 v[98:101], v[174:177], v[208:211], v[98:101]
	v_mfma_f32_16x16x32_bf16 v[86:89], v[166:169], v[216:219], v[86:89]
	v_mfma_f32_16x16x32_bf16 v[82:85], v[174:177], v[216:219], v[82:85]
	v_mfma_f32_16x16x32_bf16 v[70:73], v[166:169], v[224:227], v[70:73]
	v_mfma_f32_16x16x32_bf16 v[66:69], v[174:177], v[224:227], v[66:69]
	s_barrier
; #define PG8_STAGE(bufoff, gbase, voff) do { _Pragma("unroll") for (int _i = 0; _i < 2; ++_i) \
;         __builtin_amdgcn_global_load_lds((const unsigned*)((const char*)(gbase) + (voff)[_i]), (LAS unsigned*)(lds + (bufoff) + ldsw + _i * 8192), 16, 0, 0); } while (0)
; #define PG8_LDA(dst, b, h) do { _Pragma("unroll") for (int m = 0; m < 4; ++m) _Pragma("unroll") for (int k = 0; k < 2; ++k) dst[m][k] = *(const LAS bf16x8*)(lds + PG8_SA(b, h) + aoff + m * 2048 + k * 1024); } while (0)
; #define PG8_MMA(ai, bj, At, Bt) do { __builtin_amdgcn_s_setprio(1); _Pragma("unroll") for (int m = 0; m < 4; ++m) _Pragma("unroll") for (int n = 0; n < 2; ++n) _Pragma("unroll") for (int k = 0; k < 2; ++k) \
;         acc[ai][bj][m][n] = __builtin_amdgcn_mfma_f32_16x16x32_bf16(Bt[n][k], At[m][k], acc[ai][bj][m][n], 0, 0, 0); __builtin_amdgcn_s_setprio(0); } while (0)
; #define PG8_WAIT_V(n) asm volatile("s_waitcnt vmcnt(" #n ")" ::: "memory")
; #define PG8_WAIT_L(n) asm volatile("s_waitcnt lgkmcnt(" #n ")" ::: "memory")
; #define PG8_BAR __builtin_amdgcn_s_barrier()
; #define PG8_SCHED __builtin_amdgcn_sched_barrier(0)
; template <class Epi, class Sched>
; __device__ __forceinline__ void gemm_phase(LAS unsigned char* lds, const Gemm g, const Sched& S, const Epi& E) {
;     ...
;             PG8_LDA(At, 1, 1); PG8_STAGE(PG8_SB(1, 0), b3, voffB); PG8_STAGE(PG8_SB(1, 1), b3 + hsB, voffB); PG8_STAGE(PG8_SA(1, 0), a3, voffA);
;             PG8_WAIT_V(8); PG8_WAIT_L(0); PG8_BAR; PG8_MMA(1, 0, At, B0); PG8_MMA(1, 1, At, B1); PG8_BAR; PG8_SCHED;
;         }
	s_add_i32 s46, s74, s7
	v_lshl_add_u64 v[232:233], v[144:145], 0, s[18:19]
	s_mov_b32 m0, s46
	ds_read_b128 v[178:181], v149 offset:49152
	ds_read_b128 v[182:185], v149 offset:50176
	ds_read_b128 v[186:189], v149 offset:51200
	ds_read_b128 v[208:211], v149 offset:52224
	ds_read_b128 v[212:215], v149 offset:53248
	ds_read_b128 v[216:219], v149 offset:54272
	ds_read_b128 v[220:223], v149 offset:55296
	ds_read_b128 v[224:227], v149 offset:56320
	global_load_lds_dwordx4 v[232:233], off
	v_lshl_add_u64 v[232:233], v[190:191], 0, s[18:19]
	s_add_i32 m0, s46, 0x2000
	s_add_i32 s46, s75, s7
	global_load_lds_dwordx4 v[232:233], off
	v_lshl_add_u64 v[144:145], v[144:145], 0, vcc
	s_mov_b32 m0, s46
	s_nop 0
	global_load_lds_dwordx4 v[144:145], off
	v_lshl_add_u64 v[144:145], v[190:191], 0, vcc
	s_add_i32 m0, s46, 0x2000
	s_nop 0
	global_load_lds_dwordx4 v[144:145], off
	v_lshl_add_u64 v[144:145], v[228:229], 0, s[18:19]
	s_mov_b32 m0, s49
	s_nop 0
	global_load_lds_dwordx4 v[144:145], off
	v_lshl_add_u64 v[144:145], v[230:231], 0, s[18:19]
	s_mov_b32 m0, s50
	s_nop 0
	global_load_lds_dwordx4 v[144:145], off
	s_waitcnt vmcnt(8)
	s_waitcnt lgkmcnt(0)
	s_barrier
	s_waitcnt lgkmcnt(0)
	v_mfma_f32_16x16x32_bf16 v[62:65], v[140:143], v[178:181], v[62:65]
	v_mfma_f32_16x16x32_bf16 v[58:61], v[154:157], v[178:181], v[58:61]
	v_mfma_f32_16x16x32_bf16 v[46:49], v[140:143], v[186:189], v[46:49]
	v_mfma_f32_16x16x32_bf16 v[42:45], v[154:157], v[186:189], v[42:45]
	v_mfma_f32_16x16x32_bf16 v[30:33], v[140:143], v[212:215], v[30:33]
	v_mfma_f32_16x16x32_bf16 v[26:29], v[154:157], v[212:215], v[26:29]
	v_mfma_f32_16x16x32_bf16 v[14:17], v[140:143], v[220:223], v[14:17]
	v_mfma_f32_16x16x32_bf16 v[10:13], v[154:157], v[220:223], v[10:13]
	v_mfma_f32_16x16x32_bf16 v[62:65], v[150:153], v[182:185], v[62:65]
	v_mfma_f32_16x16x32_bf16 v[58:61], v[158:161], v[182:185], v[58:61]
	v_mfma_f32_16x16x32_bf16 v[46:49], v[150:153], v[208:211], v[46:49]
	v_mfma_f32_16x16x32_bf16 v[42:45], v[158:161], v[208:211], v[42:45]
	v_mfma_f32_16x16x32_bf16 v[30:33], v[150:153], v[216:219], v[30:33]
	v_mfma_f32_16x16x32_bf16 v[26:29], v[158:161], v[216:219], v[26:29]
	v_mfma_f32_16x16x32_bf16 v[14:17], v[150:153], v[224:227], v[14:17]
	v_mfma_f32_16x16x32_bf16 v[10:13], v[158:161], v[224:227], v[10:13]
	v_mfma_f32_16x16x32_bf16 v[54:57], v[162:165], v[178:181], v[54:57]
	v_mfma_f32_16x16x32_bf16 v[50:53], v[170:173], v[178:181], v[50:53]
	v_mfma_f32_16x16x32_bf16 v[38:41], v[162:165], v[186:189], v[38:41]
	v_mfma_f32_16x16x32_bf16 v[34:37], v[170:173], v[186:189], v[34:37]
	v_mfma_f32_16x16x32_bf16 v[22:25], v[162:165], v[212:215], v[22:25]
	v_mfma_f32_16x16x32_bf16 v[18:21], v[170:173], v[212:215], v[18:21]
	v_mfma_f32_16x16x32_bf16 v[6:9], v[162:165], v[220:223], v[6:9]
	v_mfma_f32_16x16x32_bf16 v[2:5], v[170:173], v[220:223], v[2:5]
	v_mfma_f32_16x16x32_bf16 v[54:57], v[166:169], v[182:185], v[54:57]
	v_mfma_f32_16x16x32_bf16 v[50:53], v[174:177], v[182:185], v[50:53]
	v_mfma_f32_16x16x32_bf16 v[38:41], v[166:169], v[208:211], v[38:41]
	v_mfma_f32_16x16x32_bf16 v[34:37], v[174:177], v[208:211], v[34:37]
	v_mfma_f32_16x16x32_bf16 v[22:25], v[166:169], v[216:219], v[22:25]
	v_mfma_f32_16x16x32_bf16 v[18:21], v[174:177], v[216:219], v[18:21]
	v_mfma_f32_16x16x32_bf16 v[6:9], v[166:169], v[224:227], v[6:9]
	v_mfma_f32_16x16x32_bf16 v[2:5], v[174:177], v[224:227], v[2:5]
	s_barrier
	s_add_u32 s44, s44, 0x100
	s_addc_u32 s45, s45, 0
	s_add_u32 s80, s80, 0x100
	s_addc_u32 s82, s82, 0
	s_cmp_ge_i32 s83, s26
	s_mov_b32 s46, s83
	s_cbranch_scc0 .LBB0_536
	s_setprio 0
	v_readlane_b32 s82, v254, 45
	v_readlane_b32 s83, v254, 46

; #define PG8_STAGE(bufoff, gbase, voff) do { _Pragma("unroll") for (int _i = 0; _i < 2; ++_i) \
;         __builtin_amdgcn_global_load_lds((const unsigned*)((const char*)(gbase) + (voff)[_i]), (LAS unsigned*)(lds + (bufoff) + ldsw + _i * 8192), 16, 0, 0); } while (0)
; #define PG8_LDA(dst, b, h) do { _Pragma("unroll") for (int m = 0; m < 4; ++m) _Pragma("unroll") for (int k = 0; k < 2; ++k) dst[m][k] = *(const LAS bf16x8*)(lds + PG8_SA(b, h) + aoff + m * 2048 + k * 1024); } while (0)
; #define PG8_LDB(dst, b, h) do { _Pragma("unroll") for (int n = 0; n < 2; ++n) _Pragma("unroll") for (int k = 0; k < 2; ++k) dst[n][k] = *(const LAS bf16x8*)(lds + PG8_SB(b, h) + boff + n * 2048 + k * 1024); } while (0)
; #define PG8_WAIT_V(n) asm volatile("s_waitcnt vmcnt(" #n ")" ::: "memory")
; #define PG8_WAIT_L(n) asm volatile("s_waitcnt lgkmcnt(" #n ")" ::: "memory")
; #define PG8_BAR __builtin_amdgcn_s_barrier()
; template <class Epi, class Sched>
; __device__ __forceinline__ void gemm_phase(LAS unsigned char* lds, const Gemm g, const Sched& S, const Epi& E) {
;     ...
;         const bool has_next = S.next(ui + 1, nxt);
;         const char* nA = has_next ? (const char*)g.A + nxt.offA : cA; const char* nB = has_next ? (const char*)g.Bt + nxt.offB : cB;
;         for (int t = 0; t < nt; t += 2) {
;             const bool last = (t == nt - 2);
;             const char* a1 = cA + (size_t)(t + 1) * kstep;
;             const char* a2 = last ? nA : cA + (size_t)(t + 2) * kstep; const char* b2 = last ? nB : cB + (size_t)(t + 2) * kstep;
;             const char* a3 = a2 + kstep; const char* b3 = b2 + kstep;
;             if constexpr (Epi::MIDK) { if (t == (nt >> 1)) { int fr_ = fr, fq_ = fq; asm volatile("" : "+v"(fr_), "+v"(fq_)); E.mid(acc, cur, wr, wc, fr_, fq_); } }
;             PG8_LDB(B0, 0, 0); PG8_LDB(B1, 0, 1); PG8_SCHED; PG8_LDA(At, 0, 0); PG8_STAGE(PG8_SA(1, 1), a1 + hsA, voffA);
;             PG8_WAIT_V(8); PG8_WAIT_L(0); PG8_BAR; PG8_MMA(0, 0, At, B0); PG8_MMA(0, 1, At, B1); PG8_BAR; PG8_SCHED;
;     ...
; #pragma unroll
;         for (int a = 0; a < 2; ++a)
; #pragma unroll
;             for (int b = 0; b < 2; ++b)
; #pragma unroll
;                 for (int m = 0; m < 4; ++m)
; #pragma unroll
;                     for (int n = 0; n < 2; ++n) acc[a][b][m][n] = (f32x4){0.f, 0.f, 0.f, 0.f};
;         cur = nxt; cA = nA; cB = nB; ++ui;
.LBB0_635:
	s_add_u32 s38, s68, s36
	s_addc_u32 s39, s69, s37
	s_andn2_b64 vcc, exec, s[20:21]
	s_cbranch_vccnz .Lzc_17144
	s_and_b64 s[0:1], s[40:41], exec
	s_cselect_b32 s73, s39, s43
	s_cselect_b32 s76, s38, s42
	s_add_u32 s77, s42, 0x100
	v_mov_b32_e32 v2, 0
	s_addc_u32 s78, s43, 0
	s_mov_b32 s46, 0
	s_mov_b64 s[42:43], 0
	v_mov_b32_e32 v3, v2
	v_mov_b32_e32 v4, v2
	v_mov_b32_e32 v5, v2
	v_mov_b32_e32 v10, v2
	v_mov_b32_e32 v11, v2
	v_mov_b32_e32 v12, v2
	v_mov_b32_e32 v13, v2
	v_mov_b32_e32 v34, v2
	v_mov_b32_e32 v35, v2
	v_mov_b32_e32 v36, v2
	v_mov_b32_e32 v37, v2
	v_mov_b32_e32 v42, v2
	v_mov_b32_e32 v43, v2
	v_mov_b32_e32 v44, v2
	v_mov_b32_e32 v45, v2
	v_mov_b32_e32 v66, v2
	v_mov_b32_e32 v67, v2
	v_mov_b32_e32 v68, v2
	v_mov_b32_e32 v69, v2
	v_mov_b32_e32 v74, v2
	v_mov_b32_e32 v75, v2
	v_mov_b32_e32 v76, v2
	v_mov_b32_e32 v77, v2
	v_mov_b32_e32 v98, v2
	v_mov_b32_e32 v99, v2
	v_mov_b32_e32 v100, v2
	v_mov_b32_e32 v101, v2
	v_mov_b32_e32 v106, v2
	v_mov_b32_e32 v107, v2
	v_mov_b32_e32 v108, v2
	v_mov_b32_e32 v109, v2
	v_mov_b32_e32 v18, v2
	v_mov_b32_e32 v19, v2
	v_mov_b32_e32 v20, v2
	v_mov_b32_e32 v21, v2
	v_mov_b32_e32 v26, v2
	v_mov_b32_e32 v27, v2
	v_mov_b32_e32 v28, v2
	v_mov_b32_e32 v29, v2
	v_mov_b32_e32 v50, v2
	v_mov_b32_e32 v51, v2
	v_mov_b32_e32 v52, v2
	v_mov_b32_e32 v53, v2
	v_mov_b32_e32 v58, v2
	v_mov_b32_e32 v59, v2
	v_mov_b32_e32 v60, v2
	v_mov_b32_e32 v61, v2
	v_mov_b32_e32 v82, v2
	v_mov_b32_e32 v83, v2
	v_mov_b32_e32 v84, v2
	v_mov_b32_e32 v85, v2
	v_mov_b32_e32 v90, v2
	v_mov_b32_e32 v91, v2
	v_mov_b32_e32 v92, v2
	v_mov_b32_e32 v93, v2
	v_mov_b32_e32 v114, v2
	v_mov_b32_e32 v115, v2
	v_mov_b32_e32 v116, v2
	v_mov_b32_e32 v117, v2
	v_mov_b32_e32 v122, v2
	v_mov_b32_e32 v123, v2
	v_mov_b32_e32 v124, v2
	v_mov_b32_e32 v125, v2
	v_mov_b32_e32 v6, v2
	v_mov_b32_e32 v7, v2
	v_mov_b32_e32 v8, v2
	v_mov_b32_e32 v9, v2
	v_mov_b32_e32 v14, v2
	v_mov_b32_e32 v15, v2
	v_mov_b32_e32 v16, v2
	v_mov_b32_e32 v17, v2
	v_mov_b32_e32 v38, v2
	v_mov_b32_e32 v39, v2
	v_mov_b32_e32 v40, v2
	v_mov_b32_e32 v41, v2
	v_mov_b32_e32 v46, v2
	v_mov_b32_e32 v47, v2
	v_mov_b32_e32 v48, v2
	v_mov_b32_e32 v49, v2
	v_mov_b32_e32 v70, v2
	v_mov_b32_e32 v71, v2
	v_mov_b32_e32 v72, v2
	v_mov_b32_e32 v73, v2
	v_mov_b32_e32 v78, v2
	v_mov_b32_e32 v79, v2
	v_mov_b32_e32 v80, v2
	v_mov_b32_e32 v81, v2
	v_mov_b32_e32 v102, v2
	v_mov_b32_e32 v103, v2
	v_mov_b32_e32 v104, v2
	v_mov_b32_e32 v105, v2
	v_mov_b32_e32 v110, v2
	v_mov_b32_e32 v111, v2
	v_mov_b32_e32 v112, v2
	v_mov_b32_e32 v113, v2
	v_mov_b32_e32 v22, v2
	v_mov_b32_e32 v23, v2
	v_mov_b32_e32 v24, v2
	v_mov_b32_e32 v25, v2
	v_mov_b32_e32 v30, v2
	v_mov_b32_e32 v31, v2
	v_mov_b32_e32 v32, v2
	v_mov_b32_e32 v33, v2
	v_mov_b32_e32 v54, v2
	v_mov_b32_e32 v55, v2
	v_mov_b32_e32 v56, v2
	v_mov_b32_e32 v57, v2
	v_mov_b32_e32 v62, v2
	v_mov_b32_e32 v63, v2
	v_mov_b32_e32 v64, v2
	v_mov_b32_e32 v65, v2
	v_mov_b32_e32 v86, v2
	v_mov_b32_e32 v87, v2
	v_mov_b32_e32 v88, v2
	v_mov_b32_e32 v89, v2
	v_mov_b32_e32 v94, v2
	v_mov_b32_e32 v95, v2
	v_mov_b32_e32 v96, v2
	v_mov_b32_e32 v97, v2
	v_mov_b32_e32 v118, v2
	v_mov_b32_e32 v119, v2
	v_mov_b32_e32 v120, v2
	v_mov_b32_e32 v121, v2
	v_mov_b32_e32 v126, v2
	v_mov_b32_e32 v127, v2
	v_mov_b32_e32 v128, v2
	v_mov_b32_e32 v129, v2
	v_readfirstlane_b32 s0, v193
	s_lshr_b32 s0, s0, 8
	s_cmp_eq_u32 s0, 1
	s_cbranch_scc0 .Lnp_637
	s_setprio 1
.Lnp_637:
.LBB0_637:
	s_add_i32 s0, s46, 2
	s_add_u32 s44, s42, 0x100
	s_addc_u32 s45, s43, 0
	s_add_u32 s1, s77, s42
	s_addc_u32 s22, s78, s43
	s_cmp_eq_u32 s56, s46
	s_cselect_b32 s48, 0, s44
	s_cselect_b32 s23, 0, s45
	s_cselect_b32 s46, s76, s1
	s_cselect_b32 s47, s73, s22
	s_add_u32 s48, s58, s48
	s_addc_u32 s49, s59, s23
	s_add_i32 s1, 0, 0x10000
	v_add_u32_e32 v0, s1, v152
	s_add_i32 s22, 0, 0x14000
	ds_read_b128 v[142:145], v0
	ds_read_b128 v[146:149], v0 offset:1024
	ds_read_b128 v[154:157], v0 offset:2048
	ds_read_b128 v[158:161], v0 offset:3072
	v_add_u32_e32 v0, s22, v152
	ds_read_b128 v[162:165], v0
	ds_read_b128 v[166:169], v0 offset:1024
	ds_read_b128 v[170:173], v0 offset:2048
	ds_read_b128 v[174:177], v0 offset:3072
	v_lshl_add_u64 v[190:191], v[138:139], 0, s[42:43]
	s_add_i32 m0, s11, 0xc000
	ds_read_b128 v[178:181], v153
	ds_read_b128 v[182:185], v153 offset:1024
	ds_read_b128 v[186:189], v153 offset:2048
	ds_read_b128 v[208:211], v153 offset:3072
	ds_read_b128 v[212:215], v153 offset:4096
	ds_read_b128 v[216:219], v153 offset:5120
	ds_read_b128 v[220:223], v153 offset:6144
	ds_read_b128 v[224:227], v153 offset:7168
	global_load_lds_dwordx4 v[190:191], off
	v_lshl_add_u64 v[190:191], v[140:141], 0, s[42:43]
	s_add_i32 m0, s11, 0xe000
	s_nop 0
	global_load_lds_dwordx4 v[190:191], off
	s_waitcnt vmcnt(8)
	s_waitcnt lgkmcnt(0)
	s_barrier
; #define PG8_STAGE(bufoff, gbase, voff) do { _Pragma("unroll") for (int _i = 0; _i < 2; ++_i) \
;         __builtin_amdgcn_global_load_lds((const unsigned*)((const char*)(gbase) + (voff)[_i]), (LAS unsigned*)(lds + (bufoff) + ldsw + _i * 8192), 16, 0, 0); } while (0)
; #define PG8_LDA(dst, b, h) do { _Pragma("unroll") for (int m = 0; m < 4; ++m) _Pragma("unroll") for (int k = 0; k < 2; ++k) dst[m][k] = *(const LAS bf16x8*)(lds + PG8_SA(b, h) + aoff + m * 2048 + k * 1024); } while (0)
; #define PG8_MMA(ai, bj, At, Bt) do { __builtin_amdgcn_s_setprio(1); _Pragma("unroll") for (int m = 0; m < 4; ++m) _Pragma("unroll") for (int n = 0; n < 2; ++n) _Pragma("unroll") for (int k = 0; k < 2; ++k) \
;         acc[ai][bj][m][n] = __builtin_amdgcn_mfma_f32_16x16x32_bf16(Bt[n][k], At[m][k], acc[ai][bj][m][n], 0, 0, 0); __builtin_amdgcn_s_setprio(0); } while (0)
; #define PG8_WAIT_V(n) asm volatile("s_waitcnt vmcnt(" #n ")" ::: "memory")
; #define PG8_WAIT_L(n) asm volatile("s_waitcnt lgkmcnt(" #n ")" ::: "memory")
; #define PG8_BAR __builtin_amdgcn_s_barrier()
; #define PG8_SCHED __builtin_amdgcn_sched_barrier(0)
; template <class Epi, class Sched>
; __device__ __forceinline__ void gemm_phase(LAS unsigned char* lds, const Gemm g, const Sched& S, const Epi& E) {
;     ...
;             PG8_WAIT_V(8); PG8_WAIT_L(0); PG8_BAR; PG8_MMA(0, 0, At, B0); PG8_MMA(0, 1, At, B1); PG8_BAR; PG8_SCHED;
;             PG8_LDA(At, 0, 1); PG8_STAGE(PG8_SB(0, 0), b2, voffB); PG8_STAGE(PG8_SB(0, 1), b2 + hsB, voffB); PG8_STAGE(PG8_SA(0, 0), a2, voffA);
;             PG8_WAIT_V(8); PG8_WAIT_L(0); PG8_BAR; PG8_MMA(1, 0, At, B0); PG8_MMA(1, 1, At, B1); PG8_BAR; PG8_SCHED;
	s_waitcnt lgkmcnt(0)
	v_mfma_f32_16x16x32_bf16 v[126:129], v[142:145], v[178:181], v[126:129]
	v_mfma_f32_16x16x32_bf16 v[118:121], v[154:157], v[178:181], v[118:121]
	v_mfma_f32_16x16x32_bf16 v[94:97], v[142:145], v[186:189], v[94:97]
	v_mfma_f32_16x16x32_bf16 v[86:89], v[154:157], v[186:189], v[86:89]
	v_mfma_f32_16x16x32_bf16 v[62:65], v[142:145], v[212:215], v[62:65]
	v_mfma_f32_16x16x32_bf16 v[54:57], v[154:157], v[212:215], v[54:57]
	v_mfma_f32_16x16x32_bf16 v[30:33], v[142:145], v[220:223], v[30:33]
	v_mfma_f32_16x16x32_bf16 v[22:25], v[154:157], v[220:223], v[22:25]
	v_mfma_f32_16x16x32_bf16 v[126:129], v[146:149], v[182:185], v[126:129]
	v_mfma_f32_16x16x32_bf16 v[118:121], v[158:161], v[182:185], v[118:121]
	v_mfma_f32_16x16x32_bf16 v[94:97], v[146:149], v[208:211], v[94:97]
	v_mfma_f32_16x16x32_bf16 v[86:89], v[158:161], v[208:211], v[86:89]
	v_mfma_f32_16x16x32_bf16 v[62:65], v[146:149], v[216:219], v[62:65]
	v_mfma_f32_16x16x32_bf16 v[54:57], v[158:161], v[216:219], v[54:57]
	v_mfma_f32_16x16x32_bf16 v[30:33], v[146:149], v[224:227], v[30:33]
	v_mfma_f32_16x16x32_bf16 v[22:25], v[158:161], v[224:227], v[22:25]
	v_mfma_f32_16x16x32_bf16 v[110:113], v[162:165], v[178:181], v[110:113]
	v_mfma_f32_16x16x32_bf16 v[102:105], v[170:173], v[178:181], v[102:105]
	v_mfma_f32_16x16x32_bf16 v[78:81], v[162:165], v[186:189], v[78:81]
	v_mfma_f32_16x16x32_bf16 v[70:73], v[170:173], v[186:189], v[70:73]
	v_mfma_f32_16x16x32_bf16 v[46:49], v[162:165], v[212:215], v[46:49]
	v_mfma_f32_16x16x32_bf16 v[38:41], v[170:173], v[212:215], v[38:41]
	v_mfma_f32_16x16x32_bf16 v[14:17], v[162:165], v[220:223], v[14:17]
	v_mfma_f32_16x16x32_bf16 v[6:9], v[170:173], v[220:223], v[6:9]
	v_mfma_f32_16x16x32_bf16 v[110:113], v[166:169], v[182:185], v[110:113]
	v_mfma_f32_16x16x32_bf16 v[102:105], v[174:177], v[182:185], v[102:105]
	v_mfma_f32_16x16x32_bf16 v[78:81], v[166:169], v[208:211], v[78:81]
	v_mfma_f32_16x16x32_bf16 v[70:73], v[174:177], v[208:211], v[70:73]
	v_mfma_f32_16x16x32_bf16 v[46:49], v[166:169], v[216:219], v[46:49]
	v_mfma_f32_16x16x32_bf16 v[38:41], v[174:177], v[216:219], v[38:41]
	v_mfma_f32_16x16x32_bf16 v[14:17], v[166:169], v[224:227], v[14:17]
	v_mfma_f32_16x16x32_bf16 v[6:9], v[174:177], v[224:227], v[6:9]
	s_barrier
	s_add_i32 s1, s1, s7
	v_lshl_add_u64 v[190:191], s[46:47], 0, v[134:135]
	s_mov_b32 m0, s1
	ds_read_b128 v[178:181], v153 offset:16384
	ds_read_b128 v[182:185], v153 offset:17408
	ds_read_b128 v[186:189], v153 offset:18432
	ds_read_b128 v[208:211], v153 offset:19456
	ds_read_b128 v[212:215], v153 offset:20480
	ds_read_b128 v[216:219], v153 offset:21504
	ds_read_b128 v[220:223], v153 offset:22528
	ds_read_b128 v[224:227], v153 offset:23552
	global_load_lds_dwordx4 v[190:191], off
	s_add_i32 m0, s1, 0x2000
	s_add_u32 s42, s46, 0x10000
	v_lshl_add_u64 v[228:229], s[46:47], 0, v[130:131]
	s_addc_u32 s43, s47, 0
	s_add_i32 s1, s22, s7
	global_load_lds_dwordx4 v[228:229], off
	v_lshl_add_u64 v[230:231], s[42:43], 0, v[134:135]
	s_mov_b32 m0, s1
	v_lshl_add_u64 v[232:233], s[48:49], 0, v[132:133]
	global_load_lds_dwordx4 v[230:231], off
	v_lshl_add_u64 v[230:231], s[42:43], 0, v[130:131]
	s_add_i32 m0, s1, 0x2000
	s_nop 0
	global_load_lds_dwordx4 v[230:231], off
	v_lshl_add_u64 v[230:231], s[48:49], 0, v[136:137]
	s_mov_b32 m0, s11
	s_nop 0
	global_load_lds_dwordx4 v[230:231], off
	s_mov_b32 m0, s12
	s_nop 0
	global_load_lds_dwordx4 v[232:233], off
	s_waitcnt vmcnt(8)
	s_waitcnt lgkmcnt(0)
	s_barrier
	s_waitcnt lgkmcnt(0)
	v_mfma_f32_16x16x32_bf16 v[122:125], v[142:145], v[178:181], v[122:125]
	v_mfma_f32_16x16x32_bf16 v[114:117], v[154:157], v[178:181], v[114:117]
	v_mfma_f32_16x16x32_bf16 v[90:93], v[142:145], v[186:189], v[90:93]
	v_mfma_f32_16x16x32_bf16 v[82:85], v[154:157], v[186:189], v[82:85]
	v_mfma_f32_16x16x32_bf16 v[58:61], v[142:145], v[212:215], v[58:61]
	v_mfma_f32_16x16x32_bf16 v[50:53], v[154:157], v[212:215], v[50:53]
	v_mfma_f32_16x16x32_bf16 v[26:29], v[142:145], v[220:223], v[26:29]
	v_mfma_f32_16x16x32_bf16 v[18:21], v[154:157], v[220:223], v[18:21]
	v_mfma_f32_16x16x32_bf16 v[122:125], v[146:149], v[182:185], v[122:125]
	v_mfma_f32_16x16x32_bf16 v[114:117], v[158:161], v[182:185], v[114:117]
	v_mfma_f32_16x16x32_bf16 v[90:93], v[146:149], v[208:211], v[90:93]
	v_mfma_f32_16x16x32_bf16 v[82:85], v[158:161], v[208:211], v[82:85]
	v_mfma_f32_16x16x32_bf16 v[58:61], v[146:149], v[216:219], v[58:61]
	v_mfma_f32_16x16x32_bf16 v[50:53], v[158:161], v[216:219], v[50:53]
	v_mfma_f32_16x16x32_bf16 v[26:29], v[146:149], v[224:227], v[26:29]
	v_mfma_f32_16x16x32_bf16 v[18:21], v[158:161], v[224:227], v[18:21]
	v_mfma_f32_16x16x32_bf16 v[106:109], v[162:165], v[178:181], v[106:109]
	v_mfma_f32_16x16x32_bf16 v[98:101], v[170:173], v[178:181], v[98:101]
	v_mfma_f32_16x16x32_bf16 v[74:77], v[162:165], v[186:189], v[74:77]
	v_mfma_f32_16x16x32_bf16 v[66:69], v[170:173], v[186:189], v[66:69]
	v_mfma_f32_16x16x32_bf16 v[42:45], v[162:165], v[212:215], v[42:45]
	v_mfma_f32_16x16x32_bf16 v[34:37], v[170:173], v[212:215], v[34:37]
	v_mfma_f32_16x16x32_bf16 v[10:13], v[162:165], v[220:223], v[10:13]
	v_mfma_f32_16x16x32_bf16 v[2:5], v[170:173], v[220:223], v[2:5]
	v_mfma_f32_16x16x32_bf16 v[106:109], v[166:169], v[182:185], v[106:109]
	v_mfma_f32_16x16x32_bf16 v[98:101], v[174:177], v[182:185], v[98:101]
	v_mfma_f32_16x16x32_bf16 v[74:77], v[166:169], v[208:211], v[74:77]
	v_mfma_f32_16x16x32_bf16 v[66:69], v[174:177], v[208:211], v[66:69]
	v_mfma_f32_16x16x32_bf16 v[42:45], v[166:169], v[216:219], v[42:45]
	v_mfma_f32_16x16x32_bf16 v[34:37], v[174:177], v[216:219], v[34:37]
	v_mfma_f32_16x16x32_bf16 v[10:13], v[166:169], v[224:227], v[10:13]
	v_mfma_f32_16x16x32_bf16 v[2:5], v[174:177], v[224:227], v[2:5]
	s_barrier
; #define PG8_STAGE(bufoff, gbase, voff) do { _Pragma("unroll") for (int _i = 0; _i < 2; ++_i) \
;         __builtin_amdgcn_global_load_lds((const unsigned*)((const char*)(gbase) + (voff)[_i]), (LAS unsigned*)(lds + (bufoff) + ldsw + _i * 8192), 16, 0, 0); } while (0)
; #define PG8_LDA(dst, b, h) do { _Pragma("unroll") for (int m = 0; m < 4; ++m) _Pragma("unroll") for (int k = 0; k < 2; ++k) dst[m][k] = *(const LAS bf16x8*)(lds + PG8_SA(b, h) + aoff + m * 2048 + k * 1024); } while (0)
; #define PG8_LDB(dst, b, h) do { _Pragma("unroll") for (int n = 0; n < 2; ++n) _Pragma("unroll") for (int k = 0; k < 2; ++k) dst[n][k] = *(const LAS bf16x8*)(lds + PG8_SB(b, h) + boff + n * 2048 + k * 1024); } while (0)
; #define PG8_MMA(ai, bj, At, Bt) do { __builtin_amdgcn_s_setprio(1); _Pragma("unroll") for (int m = 0; m < 4; ++m) _Pragma("unroll") for (int n = 0; n < 2; ++n) _Pragma("unroll") for (int k = 0; k < 2; ++k) \
;         acc[ai][bj][m][n] = __builtin_amdgcn_mfma_f32_16x16x32_bf16(Bt[n][k], At[m][k], acc[ai][bj][m][n], 0, 0, 0); __builtin_amdgcn_s_setprio(0); } while (0)
; #define PG8_WAIT_V(n) asm volatile("s_waitcnt vmcnt(" #n ")" ::: "memory")
; #define PG8_WAIT_L(n) asm volatile("s_waitcnt lgkmcnt(" #n ")" ::: "memory")
; #define PG8_BAR __builtin_amdgcn_s_barrier()
; #define PG8_SCHED __builtin_amdgcn_sched_barrier(0)
; template <class Epi, class Sched>
; __device__ __forceinline__ void gemm_phase(LAS unsigned char* lds, const Gemm g, const Sched& S, const Epi& E) {
;     ...
;             PG8_LDB(B0, 1, 0); PG8_LDB(B1, 1, 1); PG8_SCHED; PG8_LDA(At, 1, 0); PG8_STAGE(PG8_SA(0, 1), a2 + hsA, voffA);
;             PG8_WAIT_V(8); PG8_WAIT_L(0); PG8_BAR; PG8_MMA(0, 0, At, B0); PG8_MMA(0, 1, At, B1); PG8_BAR; PG8_SCHED;
;             PG8_LDA(At, 1, 1); PG8_STAGE(PG8_SB(1, 0), b3, voffB); PG8_STAGE(PG8_SB(1, 1), b3 + hsB, voffB); PG8_STAGE(PG8_SA(1, 0), a3, voffA);
;             PG8_WAIT_V(8); PG8_WAIT_L(0); PG8_BAR; PG8_MMA(1, 0, At, B0); PG8_MMA(1, 1, At, B1); PG8_BAR; PG8_SCHED;
;         }
	s_add_i32 s1, 0, 0x18000
	v_add_u32_e32 v0, s1, v152
	s_add_i32 s22, 0, 0x1c000
	ds_read_b128 v[142:145], v0
	ds_read_b128 v[146:149], v0 offset:1024
	ds_read_b128 v[154:157], v0 offset:2048
	ds_read_b128 v[158:161], v0 offset:3072
	v_add_u32_e32 v0, s22, v152
	ds_read_b128 v[162:165], v0
	ds_read_b128 v[166:169], v0 offset:1024
	ds_read_b128 v[170:173], v0 offset:2048
	ds_read_b128 v[174:177], v0 offset:3072
	s_add_u32 s42, s48, 0x10000
	s_addc_u32 s43, s49, 0
	s_mov_b32 m0, s16
	v_lshl_add_u64 v[238:239], s[42:43], 0, v[136:137]
	ds_read_b128 v[178:181], v153 offset:32768
	ds_read_b128 v[182:185], v153 offset:33792
	ds_read_b128 v[186:189], v153 offset:34816
	ds_read_b128 v[208:211], v153 offset:35840
	ds_read_b128 v[212:215], v153 offset:36864
	ds_read_b128 v[216:219], v153 offset:37888
	ds_read_b128 v[220:223], v153 offset:38912
	ds_read_b128 v[224:227], v153 offset:39936
	global_load_lds_dwordx4 v[238:239], off
	v_lshl_add_u64 v[238:239], s[42:43], 0, v[132:133]
	s_mov_b32 m0, s24
	s_nop 0
	global_load_lds_dwordx4 v[238:239], off
	s_waitcnt vmcnt(8)
	s_waitcnt lgkmcnt(0)
	s_barrier
	s_waitcnt lgkmcnt(0)
	v_mfma_f32_16x16x32_bf16 v[126:129], v[142:145], v[178:181], v[126:129]
	v_mfma_f32_16x16x32_bf16 v[118:121], v[154:157], v[178:181], v[118:121]
	v_mfma_f32_16x16x32_bf16 v[94:97], v[142:145], v[186:189], v[94:97]
	v_mfma_f32_16x16x32_bf16 v[86:89], v[154:157], v[186:189], v[86:89]
	v_mfma_f32_16x16x32_bf16 v[62:65], v[142:145], v[212:215], v[62:65]
	v_mfma_f32_16x16x32_bf16 v[54:57], v[154:157], v[212:215], v[54:57]
	v_mfma_f32_16x16x32_bf16 v[30:33], v[142:145], v[220:223], v[30:33]
	v_mfma_f32_16x16x32_bf16 v[22:25], v[154:157], v[220:223], v[22:25]
	v_mfma_f32_16x16x32_bf16 v[126:129], v[146:149], v[182:185], v[126:129]
	v_mfma_f32_16x16x32_bf16 v[118:121], v[158:161], v[182:185], v[118:121]
	v_mfma_f32_16x16x32_bf16 v[94:97], v[146:149], v[208:211], v[94:97]
	v_mfma_f32_16x16x32_bf16 v[86:89], v[158:161], v[208:211], v[86:89]
	v_mfma_f32_16x16x32_bf16 v[62:65], v[146:149], v[216:219], v[62:65]
	v_mfma_f32_16x16x32_bf16 v[54:57], v[158:161], v[216:219], v[54:57]
	v_mfma_f32_16x16x32_bf16 v[30:33], v[146:149], v[224:227], v[30:33]
	v_mfma_f32_16x16x32_bf16 v[22:25], v[158:161], v[224:227], v[22:25]
	v_mfma_f32_16x16x32_bf16 v[110:113], v[162:165], v[178:181], v[110:113]
	v_mfma_f32_16x16x32_bf16 v[102:105], v[170:173], v[178:181], v[102:105]
	v_mfma_f32_16x16x32_bf16 v[78:81], v[162:165], v[186:189], v[78:81]
	v_mfma_f32_16x16x32_bf16 v[70:73], v[170:173], v[186:189], v[70:73]
	v_mfma_f32_16x16x32_bf16 v[46:49], v[162:165], v[212:215], v[46:49]
	v_mfma_f32_16x16x32_bf16 v[38:41], v[170:173], v[212:215], v[38:41]
	v_mfma_f32_16x16x32_bf16 v[14:17], v[162:165], v[220:223], v[14:17]
	v_mfma_f32_16x16x32_bf16 v[6:9], v[170:173], v[220:223], v[6:9]
	v_mfma_f32_16x16x32_bf16 v[110:113], v[166:169], v[182:185], v[110:113]
	v_mfma_f32_16x16x32_bf16 v[102:105], v[174:177], v[182:185], v[102:105]
	v_mfma_f32_16x16x32_bf16 v[78:81], v[166:169], v[208:211], v[78:81]
	v_mfma_f32_16x16x32_bf16 v[70:73], v[174:177], v[208:211], v[70:73]
	v_mfma_f32_16x16x32_bf16 v[46:49], v[166:169], v[216:219], v[46:49]
	v_mfma_f32_16x16x32_bf16 v[38:41], v[174:177], v[216:219], v[38:41]
	v_mfma_f32_16x16x32_bf16 v[14:17], v[166:169], v[224:227], v[14:17]
	v_mfma_f32_16x16x32_bf16 v[6:9], v[174:177], v[224:227], v[6:9]
	s_barrier
	s_add_i32 s1, s1, s7
	v_lshl_add_u64 v[190:191], v[190:191], 0, s[18:19]
	s_mov_b32 m0, s1
	ds_read_b128 v[178:181], v153 offset:49152
	ds_read_b128 v[182:185], v153 offset:50176
	ds_read_b128 v[186:189], v153 offset:51200
	ds_read_b128 v[208:211], v153 offset:52224
	ds_read_b128 v[212:215], v153 offset:53248
	ds_read_b128 v[216:219], v153 offset:54272
	ds_read_b128 v[220:223], v153 offset:55296
	ds_read_b128 v[224:227], v153 offset:56320
	global_load_lds_dwordx4 v[190:191], off
	s_add_i32 m0, s1, 0x2000
	s_add_u32 s42, s46, 0x10080
	v_lshl_add_u64 v[190:191], v[228:229], 0, s[18:19]
	s_addc_u32 s43, s47, 0
	s_add_i32 s1, s22, s7
	global_load_lds_dwordx4 v[190:191], off
	v_lshl_add_u64 v[190:191], s[42:43], 0, v[134:135]
	s_mov_b32 m0, s1
	s_nop 0
	global_load_lds_dwordx4 v[190:191], off
	v_lshl_add_u64 v[190:191], s[42:43], 0, v[130:131]
	s_add_i32 m0, s1, 0x2000
	s_nop 0
	global_load_lds_dwordx4 v[190:191], off
	v_lshl_add_u64 v[190:191], v[230:231], 0, s[18:19]
	s_mov_b32 m0, s51
	s_nop 0
	global_load_lds_dwordx4 v[190:191], off
	v_lshl_add_u64 v[190:191], v[232:233], 0, s[18:19]
	s_mov_b32 m0, s52
	s_nop 0
	global_load_lds_dwordx4 v[190:191], off
	s_waitcnt vmcnt(8)
	s_waitcnt lgkmcnt(0)
	s_barrier
	s_waitcnt lgkmcnt(0)
	v_mfma_f32_16x16x32_bf16 v[122:125], v[142:145], v[178:181], v[122:125]
	v_mfma_f32_16x16x32_bf16 v[114:117], v[154:157], v[178:181], v[114:117]
	v_mfma_f32_16x16x32_bf16 v[90:93], v[142:145], v[186:189], v[90:93]
	v_mfma_f32_16x16x32_bf16 v[82:85], v[154:157], v[186:189], v[82:85]
	v_mfma_f32_16x16x32_bf16 v[58:61], v[142:145], v[212:215], v[58:61]
	v_mfma_f32_16x16x32_bf16 v[50:53], v[154:157], v[212:215], v[50:53]
	v_mfma_f32_16x16x32_bf16 v[26:29], v[142:145], v[220:223], v[26:29]
	v_mfma_f32_16x16x32_bf16 v[18:21], v[154:157], v[220:223], v[18:21]
	v_mfma_f32_16x16x32_bf16 v[122:125], v[146:149], v[182:185], v[122:125]
	v_mfma_f32_16x16x32_bf16 v[114:117], v[158:161], v[182:185], v[114:117]
	v_mfma_f32_16x16x32_bf16 v[90:93], v[146:149], v[208:211], v[90:93]
	v_mfma_f32_16x16x32_bf16 v[82:85], v[158:161], v[208:211], v[82:85]
	v_mfma_f32_16x16x32_bf16 v[58:61], v[146:149], v[216:219], v[58:61]
	v_mfma_f32_16x16x32_bf16 v[50:53], v[158:161], v[216:219], v[50:53]
	v_mfma_f32_16x16x32_bf16 v[26:29], v[146:149], v[224:227], v[26:29]
	v_mfma_f32_16x16x32_bf16 v[18:21], v[158:161], v[224:227], v[18:21]
	v_mfma_f32_16x16x32_bf16 v[106:109], v[162:165], v[178:181], v[106:109]
	v_mfma_f32_16x16x32_bf16 v[98:101], v[170:173], v[178:181], v[98:101]
	v_mfma_f32_16x16x32_bf16 v[74:77], v[162:165], v[186:189], v[74:77]
	v_mfma_f32_16x16x32_bf16 v[66:69], v[170:173], v[186:189], v[66:69]
	v_mfma_f32_16x16x32_bf16 v[42:45], v[162:165], v[212:215], v[42:45]
	v_mfma_f32_16x16x32_bf16 v[34:37], v[170:173], v[212:215], v[34:37]
	v_mfma_f32_16x16x32_bf16 v[10:13], v[162:165], v[220:223], v[10:13]
	v_mfma_f32_16x16x32_bf16 v[2:5], v[170:173], v[220:223], v[2:5]
	v_mfma_f32_16x16x32_bf16 v[106:109], v[166:169], v[182:185], v[106:109]
	v_mfma_f32_16x16x32_bf16 v[98:101], v[174:177], v[182:185], v[98:101]
	v_mfma_f32_16x16x32_bf16 v[74:77], v[166:169], v[208:211], v[74:77]
	v_mfma_f32_16x16x32_bf16 v[66:69], v[174:177], v[208:211], v[66:69]
	v_mfma_f32_16x16x32_bf16 v[42:45], v[166:169], v[216:219], v[42:45]
	v_mfma_f32_16x16x32_bf16 v[34:37], v[174:177], v[216:219], v[34:37]
	v_mfma_f32_16x16x32_bf16 v[10:13], v[166:169], v[224:227], v[10:13]
	v_mfma_f32_16x16x32_bf16 v[2:5], v[174:177], v[224:227], v[2:5]
	s_barrier
	s_cmp_ge_i32 s0, s26
	s_mov_b64 s[42:43], s[44:45]
	s_mov_b32 s46, s0
	s_cbranch_scc0 .LBB0_637
	s_setprio 0

; #define PG8_STAGE(bufoff, gbase, voff) do { _Pragma("unroll") for (int _i = 0; _i < 2; ++_i) \
;         __builtin_amdgcn_global_load_lds((const unsigned*)((const char*)(gbase) + (voff)[_i]), (LAS unsigned*)(lds + (bufoff) + ldsw + _i * 8192), 16, 0, 0); } while (0)
; #define PG8_LDA(dst, b, h) do { _Pragma("unroll") for (int m = 0; m < 4; ++m) _Pragma("unroll") for (int k = 0; k < 2; ++k) dst[m][k] = *(const LAS bf16x8*)(lds + PG8_SA(b, h) + aoff + m * 2048 + k * 1024); } while (0)
; #define PG8_LDB(dst, b, h) do { _Pragma("unroll") for (int n = 0; n < 2; ++n) _Pragma("unroll") for (int k = 0; k < 2; ++k) dst[n][k] = *(const LAS bf16x8*)(lds + PG8_SB(b, h) + boff + n * 2048 + k * 1024); } while (0)
; #define PG8_WAIT_V(n) asm volatile("s_waitcnt vmcnt(" #n ")" ::: "memory")
; #define PG8_WAIT_L(n) asm volatile("s_waitcnt lgkmcnt(" #n ")" ::: "memory")
; #define PG8_BAR __builtin_amdgcn_s_barrier()
; template <class Epi, class Sched>
; __device__ __forceinline__ void gemm_phase(LAS unsigned char* lds, const Gemm g, const Sched& S, const Epi& E) {
;     ...
;         const bool has_next = S.next(ui + 1, nxt);
;         const char* nA = has_next ? (const char*)g.A + nxt.offA : cA; const char* nB = has_next ? (const char*)g.Bt + nxt.offB : cB;
;         for (int t = 0; t < nt; t += 2) {
;             const bool last = (t == nt - 2);
;             const char* a1 = cA + (size_t)(t + 1) * kstep;
;             const char* a2 = last ? nA : cA + (size_t)(t + 2) * kstep; const char* b2 = last ? nB : cB + (size_t)(t + 2) * kstep;
;             const char* a3 = a2 + kstep; const char* b3 = b2 + kstep;
;             if constexpr (Epi::MIDK) { if (t == (nt >> 1)) { int fr_ = fr, fq_ = fq; asm volatile("" : "+v"(fr_), "+v"(fq_)); E.mid(acc, cur, wr, wc, fr_, fq_); } }
;             PG8_LDB(B0, 0, 0); PG8_LDB(B1, 0, 1); PG8_SCHED; PG8_LDA(At, 0, 0); PG8_STAGE(PG8_SA(1, 1), a1 + hsA, voffA);
;             PG8_WAIT_V(8); PG8_WAIT_L(0); PG8_BAR; PG8_MMA(0, 0, At, B0); PG8_MMA(0, 1, At, B1); PG8_BAR; PG8_SCHED;
;     ...
; #pragma unroll
;         for (int a = 0; a < 2; ++a)
; #pragma unroll
;             for (int b = 0; b < 2; ++b)
; #pragma unroll
;                 for (int m = 0; m < 4; ++m)
; #pragma unroll
;                     for (int n = 0; n < 2; ++n) acc[a][b][m][n] = (f32x4){0.f, 0.f, 0.f, 0.f};
;         cur = nxt; cA = nA; cB = nB; ++ui;
.LBB0_658:
	s_add_u32 s8, s2, s50
	s_addc_u32 s9, s3, s51
	v_readlane_b32 s0, v254, 4
	v_readlane_b32 s1, v254, 5
	s_add_u32 s20, s0, s76
	s_addc_u32 s21, s1, s77
	s_andn2_b64 vcc, exec, s[34:35]
	s_cbranch_vccnz .Lzc_19087
	s_and_b64 s[0:1], s[38:39], exec
	s_cselect_b32 s47, s9, s37
	s_cselect_b32 s49, s8, s36
	s_cselect_b32 s83, s21, s41
	s_cselect_b32 vcc_lo, s20, s40
	s_add_u32 s36, s36, 0x40080
	s_addc_u32 s37, s37, 0
	s_add_u32 vcc_hi, s40, 0x100
	v_mov_b32_e32 v6, 0
	s_addc_u32 s96, s41, 0
	s_mov_b32 s40, 0
	v_mov_b32_e32 v7, v6
	v_mov_b32_e32 v8, v6
	v_mov_b32_e32 v9, v6
	v_mov_b32_e32 v14, v6
	v_mov_b32_e32 v15, v6
	v_mov_b32_e32 v16, v6
	v_mov_b32_e32 v17, v6
	v_mov_b32_e32 v22, v6
	v_mov_b32_e32 v23, v6
	v_mov_b32_e32 v24, v6
	v_mov_b32_e32 v25, v6
	v_mov_b32_e32 v26, v6
	v_mov_b32_e32 v27, v6
	v_mov_b32_e32 v28, v6
	v_mov_b32_e32 v29, v6
	v_mov_b32_e32 v38, v6
	v_mov_b32_e32 v39, v6
	v_mov_b32_e32 v40, v6
	v_mov_b32_e32 v41, v6
	v_mov_b32_e32 v42, v6
	v_mov_b32_e32 v43, v6
	v_mov_b32_e32 v44, v6
	v_mov_b32_e32 v45, v6
	v_mov_b32_e32 v54, v6
	v_mov_b32_e32 v55, v6
	v_mov_b32_e32 v56, v6
	v_mov_b32_e32 v57, v6
	v_mov_b32_e32 v58, v6
	v_mov_b32_e32 v59, v6
	v_mov_b32_e32 v60, v6
	v_mov_b32_e32 v61, v6
	v_mov_b32_e32 v2, v6
	v_mov_b32_e32 v3, v6
	v_mov_b32_e32 v4, v6
	v_mov_b32_e32 v5, v6
	v_mov_b32_e32 v10, v6
	v_mov_b32_e32 v11, v6
	v_mov_b32_e32 v12, v6
	v_mov_b32_e32 v13, v6
	v_mov_b32_e32 v18, v6
	v_mov_b32_e32 v19, v6
	v_mov_b32_e32 v20, v6
	v_mov_b32_e32 v21, v6
	v_mov_b32_e32 v30, v6
	v_mov_b32_e32 v31, v6
	v_mov_b32_e32 v32, v6
	v_mov_b32_e32 v33, v6
	v_mov_b32_e32 v34, v6
	v_mov_b32_e32 v35, v6
	v_mov_b32_e32 v36, v6
	v_mov_b32_e32 v37, v6
	v_mov_b32_e32 v46, v6
	v_mov_b32_e32 v47, v6
	v_mov_b32_e32 v48, v6
	v_mov_b32_e32 v49, v6
	v_mov_b32_e32 v50, v6
	v_mov_b32_e32 v51, v6
	v_mov_b32_e32 v52, v6
	v_mov_b32_e32 v53, v6
	v_mov_b32_e32 v62, v6
	v_mov_b32_e32 v63, v6
	v_mov_b32_e32 v64, v6
	v_mov_b32_e32 v65, v6
	v_mov_b32_e32 v70, v6
	v_mov_b32_e32 v71, v6
	v_mov_b32_e32 v72, v6
	v_mov_b32_e32 v73, v6
	v_mov_b32_e32 v74, v6
	v_mov_b32_e32 v75, v6
	v_mov_b32_e32 v76, v6
	v_mov_b32_e32 v77, v6
	v_mov_b32_e32 v86, v6
	v_mov_b32_e32 v87, v6
	v_mov_b32_e32 v88, v6
	v_mov_b32_e32 v89, v6
	v_mov_b32_e32 v90, v6
	v_mov_b32_e32 v91, v6
	v_mov_b32_e32 v92, v6
	v_mov_b32_e32 v93, v6
	v_mov_b32_e32 v102, v6
	v_mov_b32_e32 v103, v6
	v_mov_b32_e32 v104, v6
	v_mov_b32_e32 v105, v6
	v_mov_b32_e32 v106, v6
	v_mov_b32_e32 v107, v6
	v_mov_b32_e32 v108, v6
	v_mov_b32_e32 v109, v6
	v_mov_b32_e32 v118, v6
	v_mov_b32_e32 v119, v6
	v_mov_b32_e32 v120, v6
	v_mov_b32_e32 v121, v6
	v_mov_b32_e32 v126, v6
	v_mov_b32_e32 v127, v6
	v_mov_b32_e32 v128, v6
	v_mov_b32_e32 v129, v6
	v_mov_b32_e32 v66, v6
	v_mov_b32_e32 v67, v6
	v_mov_b32_e32 v68, v6
	v_mov_b32_e32 v69, v6
	v_mov_b32_e32 v78, v6
	v_mov_b32_e32 v79, v6
	v_mov_b32_e32 v80, v6
	v_mov_b32_e32 v81, v6
	v_mov_b32_e32 v82, v6
	v_mov_b32_e32 v83, v6
	v_mov_b32_e32 v84, v6
	v_mov_b32_e32 v85, v6
	v_mov_b32_e32 v94, v6
	v_mov_b32_e32 v95, v6
	v_mov_b32_e32 v96, v6
	v_mov_b32_e32 v97, v6
	v_mov_b32_e32 v98, v6
	v_mov_b32_e32 v99, v6
	v_mov_b32_e32 v100, v6
	v_mov_b32_e32 v101, v6
	v_mov_b32_e32 v110, v6
	v_mov_b32_e32 v111, v6
	v_mov_b32_e32 v112, v6
	v_mov_b32_e32 v113, v6
	v_mov_b32_e32 v114, v6
	v_mov_b32_e32 v115, v6
	v_mov_b32_e32 v116, v6
	v_mov_b32_e32 v117, v6
	v_mov_b32_e32 v122, v6
	v_mov_b32_e32 v123, v6
	v_mov_b32_e32 v124, v6
	v_mov_b32_e32 v125, v6
	v_readfirstlane_b32 s0, v193
	s_lshr_b32 s0, s0, 8
	s_cmp_eq_u32 s0, 1
	s_cbranch_scc0 .Lnp_660
	s_setprio 1
.Lnp_660:
.LBB0_660:
	s_add_i32 s0, s40, 2
	s_add_u32 s1, s36, 0xfffc0080
	s_addc_u32 s41, s37, -1
	s_add_i32 s74, 0, 0x10000
	s_cmp_eq_u32 s11, s40
	s_cselect_b32 s85, s47, s41
	s_cselect_b32 s84, s49, s1
	s_cselect_b32 s41, s83, s96
	s_cselect_b32 s40, vcc_lo, vcc_hi
	s_add_i32 s1, 0, 0x14000
	v_add_u32_e32 v154, s74, v165
	v_add_u32_e32 v162, s1, v165
	ds_read_b128 v[142:145], v154
	ds_read_b128 v[146:149], v154 offset:1024
	ds_read_b128 v[150:153], v154 offset:2048
	ds_read_b128 v[154:157], v154 offset:3072
	ds_read_b128 v[158:161], v162
	ds_read_b128 v[168:171], v162 offset:1024
	ds_read_b128 v[172:175], v162 offset:2048
	ds_read_b128 v[176:179], v162 offset:3072
	v_lshl_add_u64 v[228:229], s[36:37], 0, v[138:139]
	s_add_i32 m0, s16, 0xc000
	ds_read_b128 v[180:183], v166
	ds_read_b128 v[184:187], v166 offset:1024
	ds_read_b128 v[188:191], v166 offset:2048
	ds_read_b128 v[208:211], v166 offset:3072
	ds_read_b128 v[212:215], v166 offset:4096
	ds_read_b128 v[216:219], v166 offset:5120
	ds_read_b128 v[220:223], v166 offset:6144
	ds_read_b128 v[224:227], v166 offset:7168
	global_load_lds_dwordx4 v[228:229], off
	v_lshl_add_u64 v[228:229], s[36:37], 0, v[140:141]
	s_add_i32 m0, s16, 0xe000
	s_nop 0
	global_load_lds_dwordx4 v[228:229], off
	s_waitcnt vmcnt(8)
	s_waitcnt lgkmcnt(0)
	s_barrier
; #define PG8_STAGE(bufoff, gbase, voff) do { _Pragma("unroll") for (int _i = 0; _i < 2; ++_i) \
;         __builtin_amdgcn_global_load_lds((const unsigned*)((const char*)(gbase) + (voff)[_i]), (LAS unsigned*)(lds + (bufoff) + ldsw + _i * 8192), 16, 0, 0); } while (0)
; #define PG8_LDA(dst, b, h) do { _Pragma("unroll") for (int m = 0; m < 4; ++m) _Pragma("unroll") for (int k = 0; k < 2; ++k) dst[m][k] = *(const LAS bf16x8*)(lds + PG8_SA(b, h) + aoff + m * 2048 + k * 1024); } while (0)
; #define PG8_MMA(ai, bj, At, Bt) do { __builtin_amdgcn_s_setprio(1); _Pragma("unroll") for (int m = 0; m < 4; ++m) _Pragma("unroll") for (int n = 0; n < 2; ++n) _Pragma("unroll") for (int k = 0; k < 2; ++k) \
;         acc[ai][bj][m][n] = __builtin_amdgcn_mfma_f32_16x16x32_bf16(Bt[n][k], At[m][k], acc[ai][bj][m][n], 0, 0, 0); __builtin_amdgcn_s_setprio(0); } while (0)
; #define PG8_WAIT_V(n) asm volatile("s_waitcnt vmcnt(" #n ")" ::: "memory")
; #define PG8_WAIT_L(n) asm volatile("s_waitcnt lgkmcnt(" #n ")" ::: "memory")
; #define PG8_BAR __builtin_amdgcn_s_barrier()
; #define PG8_SCHED __builtin_amdgcn_sched_barrier(0)
; template <class Epi, class Sched>
; __device__ __forceinline__ void gemm_phase(LAS unsigned char* lds, const Gemm g, const Sched& S, const Epi& E) {
;     ...
;             PG8_WAIT_V(8); PG8_WAIT_L(0); PG8_BAR; PG8_MMA(0, 0, At, B0); PG8_MMA(0, 1, At, B1); PG8_BAR; PG8_SCHED;
;             PG8_LDA(At, 0, 1); PG8_STAGE(PG8_SB(0, 0), b2, voffB); PG8_STAGE(PG8_SB(0, 1), b2 + hsB, voffB); PG8_STAGE(PG8_SA(0, 0), a2, voffA);
;             PG8_WAIT_V(8); PG8_WAIT_L(0); PG8_BAR; PG8_MMA(1, 0, At, B0); PG8_MMA(1, 1, At, B1); PG8_BAR; PG8_SCHED;
	s_waitcnt lgkmcnt(0)
	v_mfma_f32_16x16x32_bf16 v[122:125], v[142:145], v[180:183], v[122:125]
	v_mfma_f32_16x16x32_bf16 v[114:117], v[150:153], v[180:183], v[114:117]
	v_mfma_f32_16x16x32_bf16 v[110:113], v[142:145], v[188:191], v[110:113]
	v_mfma_f32_16x16x32_bf16 v[98:101], v[150:153], v[188:191], v[98:101]
	v_mfma_f32_16x16x32_bf16 v[94:97], v[142:145], v[212:215], v[94:97]
	v_mfma_f32_16x16x32_bf16 v[82:85], v[150:153], v[212:215], v[82:85]
	v_mfma_f32_16x16x32_bf16 v[78:81], v[142:145], v[220:223], v[78:81]
	v_mfma_f32_16x16x32_bf16 v[66:69], v[150:153], v[220:223], v[66:69]
	v_mfma_f32_16x16x32_bf16 v[122:125], v[146:149], v[184:187], v[122:125]
	v_mfma_f32_16x16x32_bf16 v[114:117], v[154:157], v[184:187], v[114:117]
	v_mfma_f32_16x16x32_bf16 v[110:113], v[146:149], v[208:211], v[110:113]
	v_mfma_f32_16x16x32_bf16 v[98:101], v[154:157], v[208:211], v[98:101]
	v_mfma_f32_16x16x32_bf16 v[94:97], v[146:149], v[216:219], v[94:97]
	v_mfma_f32_16x16x32_bf16 v[82:85], v[154:157], v[216:219], v[82:85]
	v_mfma_f32_16x16x32_bf16 v[78:81], v[146:149], v[224:227], v[78:81]
	v_mfma_f32_16x16x32_bf16 v[66:69], v[154:157], v[224:227], v[66:69]
	v_mfma_f32_16x16x32_bf16 v[126:129], v[158:161], v[180:183], v[126:129]
	v_mfma_f32_16x16x32_bf16 v[118:121], v[172:175], v[180:183], v[118:121]
	v_mfma_f32_16x16x32_bf16 v[106:109], v[158:161], v[188:191], v[106:109]
	v_mfma_f32_16x16x32_bf16 v[102:105], v[172:175], v[188:191], v[102:105]
	v_mfma_f32_16x16x32_bf16 v[90:93], v[158:161], v[212:215], v[90:93]
	v_mfma_f32_16x16x32_bf16 v[86:89], v[172:175], v[212:215], v[86:89]
	v_mfma_f32_16x16x32_bf16 v[74:77], v[158:161], v[220:223], v[74:77]
	v_mfma_f32_16x16x32_bf16 v[70:73], v[172:175], v[220:223], v[70:73]
	v_mfma_f32_16x16x32_bf16 v[126:129], v[168:171], v[184:187], v[126:129]
	v_mfma_f32_16x16x32_bf16 v[118:121], v[176:179], v[184:187], v[118:121]
	v_mfma_f32_16x16x32_bf16 v[106:109], v[168:171], v[208:211], v[106:109]
	v_mfma_f32_16x16x32_bf16 v[102:105], v[176:179], v[208:211], v[102:105]
	v_mfma_f32_16x16x32_bf16 v[90:93], v[168:171], v[216:219], v[90:93]
	v_mfma_f32_16x16x32_bf16 v[86:89], v[176:179], v[216:219], v[86:89]
	v_mfma_f32_16x16x32_bf16 v[74:77], v[168:171], v[224:227], v[74:77]
	v_mfma_f32_16x16x32_bf16 v[70:73], v[176:179], v[224:227], v[70:73]
	s_barrier
	s_add_i32 s74, s74, s12
	v_lshl_add_u64 v[228:229], s[40:41], 0, v[0:1]
	s_mov_b32 m0, s74
	ds_read_b128 v[180:183], v166 offset:16384
	ds_read_b128 v[184:187], v166 offset:17408
	ds_read_b128 v[188:191], v166 offset:18432
	ds_read_b128 v[208:211], v166 offset:19456
	ds_read_b128 v[212:215], v166 offset:20480
	ds_read_b128 v[216:219], v166 offset:21504
	ds_read_b128 v[220:223], v166 offset:22528
	ds_read_b128 v[224:227], v166 offset:23552
	global_load_lds_dwordx4 v[228:229], off
	s_add_i32 m0, s74, 0x2000
	s_add_u32 s74, s40, 0x40000
	v_lshl_add_u64 v[230:231], s[40:41], 0, v[130:131]
	s_addc_u32 s75, s41, 0
	s_add_i32 s1, s1, s12
	global_load_lds_dwordx4 v[230:231], off
	v_lshl_add_u64 v[232:233], s[74:75], 0, v[0:1]
	s_mov_b32 m0, s1
	v_lshl_add_u64 v[238:239], s[84:85], 0, v[132:133]
	global_load_lds_dwordx4 v[232:233], off
	v_lshl_add_u64 v[232:233], s[74:75], 0, v[130:131]
	s_add_i32 m0, s1, 0x2000
	s_nop 0
	global_load_lds_dwordx4 v[232:233], off
	v_lshl_add_u64 v[232:233], s[84:85], 0, v[134:135]
	s_mov_b32 m0, s16
	s_nop 0
	global_load_lds_dwordx4 v[232:233], off
	s_mov_b32 m0, s52
	s_nop 0
	global_load_lds_dwordx4 v[238:239], off
	s_waitcnt vmcnt(8)
	s_waitcnt lgkmcnt(0)
	s_barrier
	s_waitcnt lgkmcnt(0)
	v_mfma_f32_16x16x32_bf16 v[62:65], v[142:145], v[180:183], v[62:65]
	v_mfma_f32_16x16x32_bf16 v[50:53], v[150:153], v[180:183], v[50:53]
	v_mfma_f32_16x16x32_bf16 v[46:49], v[142:145], v[188:191], v[46:49]
	v_mfma_f32_16x16x32_bf16 v[34:37], v[150:153], v[188:191], v[34:37]
	v_mfma_f32_16x16x32_bf16 v[30:33], v[142:145], v[212:215], v[30:33]
	v_mfma_f32_16x16x32_bf16 v[18:21], v[150:153], v[212:215], v[18:21]
	v_mfma_f32_16x16x32_bf16 v[10:13], v[142:145], v[220:223], v[10:13]
	v_mfma_f32_16x16x32_bf16 v[2:5], v[150:153], v[220:223], v[2:5]
	v_mfma_f32_16x16x32_bf16 v[62:65], v[146:149], v[184:187], v[62:65]
	v_mfma_f32_16x16x32_bf16 v[50:53], v[154:157], v[184:187], v[50:53]
	v_mfma_f32_16x16x32_bf16 v[46:49], v[146:149], v[208:211], v[46:49]
	v_mfma_f32_16x16x32_bf16 v[34:37], v[154:157], v[208:211], v[34:37]
	v_mfma_f32_16x16x32_bf16 v[30:33], v[146:149], v[216:219], v[30:33]
	v_mfma_f32_16x16x32_bf16 v[18:21], v[154:157], v[216:219], v[18:21]
	v_mfma_f32_16x16x32_bf16 v[10:13], v[146:149], v[224:227], v[10:13]
	v_mfma_f32_16x16x32_bf16 v[2:5], v[154:157], v[224:227], v[2:5]
	v_mfma_f32_16x16x32_bf16 v[58:61], v[158:161], v[180:183], v[58:61]
	v_mfma_f32_16x16x32_bf16 v[54:57], v[172:175], v[180:183], v[54:57]
	v_mfma_f32_16x16x32_bf16 v[42:45], v[158:161], v[188:191], v[42:45]
	v_mfma_f32_16x16x32_bf16 v[38:41], v[172:175], v[188:191], v[38:41]
	v_mfma_f32_16x16x32_bf16 v[26:29], v[158:161], v[212:215], v[26:29]
	v_mfma_f32_16x16x32_bf16 v[22:25], v[172:175], v[212:215], v[22:25]
	v_mfma_f32_16x16x32_bf16 v[14:17], v[158:161], v[220:223], v[14:17]
	v_mfma_f32_16x16x32_bf16 v[6:9], v[172:175], v[220:223], v[6:9]
	v_mfma_f32_16x16x32_bf16 v[58:61], v[168:171], v[184:187], v[58:61]
	v_mfma_f32_16x16x32_bf16 v[54:57], v[176:179], v[184:187], v[54:57]
	v_mfma_f32_16x16x32_bf16 v[42:45], v[168:171], v[208:211], v[42:45]
	v_mfma_f32_16x16x32_bf16 v[38:41], v[176:179], v[208:211], v[38:41]
	v_mfma_f32_16x16x32_bf16 v[26:29], v[168:171], v[216:219], v[26:29]
	v_mfma_f32_16x16x32_bf16 v[22:25], v[176:179], v[216:219], v[22:25]
	v_mfma_f32_16x16x32_bf16 v[14:17], v[168:171], v[224:227], v[14:17]
	v_mfma_f32_16x16x32_bf16 v[6:9], v[176:179], v[224:227], v[6:9]
	s_barrier
; #define PG8_STAGE(bufoff, gbase, voff) do { _Pragma("unroll") for (int _i = 0; _i < 2; ++_i) \
;         __builtin_amdgcn_global_load_lds((const unsigned*)((const char*)(gbase) + (voff)[_i]), (LAS unsigned*)(lds + (bufoff) + ldsw + _i * 8192), 16, 0, 0); } while (0)
; #define PG8_LDA(dst, b, h) do { _Pragma("unroll") for (int m = 0; m < 4; ++m) _Pragma("unroll") for (int k = 0; k < 2; ++k) dst[m][k] = *(const LAS bf16x8*)(lds + PG8_SA(b, h) + aoff + m * 2048 + k * 1024); } while (0)
; #define PG8_LDB(dst, b, h) do { _Pragma("unroll") for (int n = 0; n < 2; ++n) _Pragma("unroll") for (int k = 0; k < 2; ++k) dst[n][k] = *(const LAS bf16x8*)(lds + PG8_SB(b, h) + boff + n * 2048 + k * 1024); } while (0)
; #define PG8_MMA(ai, bj, At, Bt) do { __builtin_amdgcn_s_setprio(1); _Pragma("unroll") for (int m = 0; m < 4; ++m) _Pragma("unroll") for (int n = 0; n < 2; ++n) _Pragma("unroll") for (int k = 0; k < 2; ++k) \
;         acc[ai][bj][m][n] = __builtin_amdgcn_mfma_f32_16x16x32_bf16(Bt[n][k], At[m][k], acc[ai][bj][m][n], 0, 0, 0); __builtin_amdgcn_s_setprio(0); } while (0)
; #define PG8_WAIT_V(n) asm volatile("s_waitcnt vmcnt(" #n ")" ::: "memory")
; #define PG8_WAIT_L(n) asm volatile("s_waitcnt lgkmcnt(" #n ")" ::: "memory")
; #define PG8_BAR __builtin_amdgcn_s_barrier()
; #define PG8_SCHED __builtin_amdgcn_sched_barrier(0)
; template <class Epi, class Sched>
; __device__ __forceinline__ void gemm_phase(LAS unsigned char* lds, const Gemm g, const Sched& S, const Epi& E) {
;     ...
;             PG8_LDB(B0, 1, 0); PG8_LDB(B1, 1, 1); PG8_SCHED; PG8_LDA(At, 1, 0); PG8_STAGE(PG8_SA(0, 1), a2 + hsA, voffA);
;             PG8_WAIT_V(8); PG8_WAIT_L(0); PG8_BAR; PG8_MMA(0, 0, At, B0); PG8_MMA(0, 1, At, B1); PG8_BAR; PG8_SCHED;
	s_add_i32 s1, 0, 0x18000
	s_add_i32 s22, 0, 0x1c000
	v_add_u32_e32 v154, s1, v165
	v_add_u32_e32 v162, s22, v165
	ds_read_b128 v[142:145], v154
	ds_read_b128 v[146:149], v154 offset:1024
	ds_read_b128 v[150:153], v154 offset:2048
	ds_read_b128 v[154:157], v154 offset:3072
	ds_read_b128 v[158:161], v162
	ds_read_b128 v[168:171], v162 offset:1024
	ds_read_b128 v[172:175], v162 offset:2048
	ds_read_b128 v[176:179], v162 offset:3072
	s_add_u32 s74, s84, 0x40000
	s_addc_u32 s75, s85, 0
	s_mov_b32 m0, s64
	v_lshl_add_u64 v[240:241], s[74:75], 0, v[134:135]
	ds_read_b128 v[180:183], v166 offset:32768
	ds_read_b128 v[184:187], v166 offset:33792
	ds_read_b128 v[188:191], v166 offset:34816
	ds_read_b128 v[208:211], v166 offset:35840
	ds_read_b128 v[212:215], v166 offset:36864
	ds_read_b128 v[216:219], v166 offset:37888
	ds_read_b128 v[220:223], v166 offset:38912
	ds_read_b128 v[224:227], v166 offset:39936
	global_load_lds_dwordx4 v[240:241], off
	v_lshl_add_u64 v[240:241], s[74:75], 0, v[132:133]
	s_mov_b32 m0, s78
	s_nop 0
	global_load_lds_dwordx4 v[240:241], off
	s_waitcnt vmcnt(8)
	s_waitcnt lgkmcnt(0)
	s_barrier
	s_waitcnt lgkmcnt(0)
	v_mfma_f32_16x16x32_bf16 v[122:125], v[142:145], v[180:183], v[122:125]
	v_mfma_f32_16x16x32_bf16 v[114:117], v[150:153], v[180:183], v[114:117]
	v_mfma_f32_16x16x32_bf16 v[110:113], v[142:145], v[188:191], v[110:113]
	v_mfma_f32_16x16x32_bf16 v[98:101], v[150:153], v[188:191], v[98:101]
	v_mfma_f32_16x16x32_bf16 v[94:97], v[142:145], v[212:215], v[94:97]
	v_mfma_f32_16x16x32_bf16 v[82:85], v[150:153], v[212:215], v[82:85]
	v_mfma_f32_16x16x32_bf16 v[78:81], v[142:145], v[220:223], v[78:81]
	v_mfma_f32_16x16x32_bf16 v[66:69], v[150:153], v[220:223], v[66:69]
	v_mfma_f32_16x16x32_bf16 v[122:125], v[146:149], v[184:187], v[122:125]
	v_mfma_f32_16x16x32_bf16 v[114:117], v[154:157], v[184:187], v[114:117]
	v_mfma_f32_16x16x32_bf16 v[110:113], v[146:149], v[208:211], v[110:113]
	v_mfma_f32_16x16x32_bf16 v[98:101], v[154:157], v[208:211], v[98:101]
	v_mfma_f32_16x16x32_bf16 v[94:97], v[146:149], v[216:219], v[94:97]
	v_mfma_f32_16x16x32_bf16 v[82:85], v[154:157], v[216:219], v[82:85]
	v_mfma_f32_16x16x32_bf16 v[78:81], v[146:149], v[224:227], v[78:81]
	v_mfma_f32_16x16x32_bf16 v[66:69], v[154:157], v[224:227], v[66:69]
	v_mfma_f32_16x16x32_bf16 v[126:129], v[158:161], v[180:183], v[126:129]
	v_mfma_f32_16x16x32_bf16 v[118:121], v[172:175], v[180:183], v[118:121]
	v_mfma_f32_16x16x32_bf16 v[106:109], v[158:161], v[188:191], v[106:109]
	v_mfma_f32_16x16x32_bf16 v[102:105], v[172:175], v[188:191], v[102:105]
	v_mfma_f32_16x16x32_bf16 v[90:93], v[158:161], v[212:215], v[90:93]
	v_mfma_f32_16x16x32_bf16 v[86:89], v[172:175], v[212:215], v[86:89]
	v_mfma_f32_16x16x32_bf16 v[74:77], v[158:161], v[220:223], v[74:77]
	v_mfma_f32_16x16x32_bf16 v[70:73], v[172:175], v[220:223], v[70:73]
	v_mfma_f32_16x16x32_bf16 v[126:129], v[168:171], v[184:187], v[126:129]
	v_mfma_f32_16x16x32_bf16 v[118:121], v[176:179], v[184:187], v[118:121]
	v_mfma_f32_16x16x32_bf16 v[106:109], v[168:171], v[208:211], v[106:109]
	v_mfma_f32_16x16x32_bf16 v[102:105], v[176:179], v[208:211], v[102:105]
	v_mfma_f32_16x16x32_bf16 v[90:93], v[168:171], v[216:219], v[90:93]
	v_mfma_f32_16x16x32_bf16 v[86:89], v[176:179], v[216:219], v[86:89]
	v_mfma_f32_16x16x32_bf16 v[74:77], v[168:171], v[224:227], v[74:77]
	v_mfma_f32_16x16x32_bf16 v[70:73], v[176:179], v[224:227], v[70:73]
	s_barrier
; #define PG8_STAGE(bufoff, gbase, voff) do { _Pragma("unroll") for (int _i = 0; _i < 2; ++_i) \
;         __builtin_amdgcn_global_load_lds((const unsigned*)((const char*)(gbase) + (voff)[_i]), (LAS unsigned*)(lds + (bufoff) + ldsw + _i * 8192), 16, 0, 0); } while (0)
; #define PG8_LDA(dst, b, h) do { _Pragma("unroll") for (int m = 0; m < 4; ++m) _Pragma("unroll") for (int k = 0; k < 2; ++k) dst[m][k] = *(const LAS bf16x8*)(lds + PG8_SA(b, h) + aoff + m * 2048 + k * 1024); } while (0)
; #define PG8_MMA(ai, bj, At, Bt) do { __builtin_amdgcn_s_setprio(1); _Pragma("unroll") for (int m = 0; m < 4; ++m) _Pragma("unroll") for (int n = 0; n < 2; ++n) _Pragma("unroll") for (int k = 0; k < 2; ++k) \
;         acc[ai][bj][m][n] = __builtin_amdgcn_mfma_f32_16x16x32_bf16(Bt[n][k], At[m][k], acc[ai][bj][m][n], 0, 0, 0); __builtin_amdgcn_s_setprio(0); } while (0)
; #define PG8_WAIT_V(n) asm volatile("s_waitcnt vmcnt(" #n ")" ::: "memory")
; #define PG8_WAIT_L(n) asm volatile("s_waitcnt lgkmcnt(" #n ")" ::: "memory")
; #define PG8_BAR __builtin_amdgcn_s_barrier()
; #define PG8_SCHED __builtin_amdgcn_sched_barrier(0)
; template <class Epi, class Sched>
; __device__ __forceinline__ void gemm_phase(LAS unsigned char* lds, const Gemm g, const Sched& S, const Epi& E) {
;     ...
;             PG8_LDA(At, 1, 1); PG8_STAGE(PG8_SB(1, 0), b3, voffB); PG8_STAGE(PG8_SB(1, 1), b3 + hsB, voffB); PG8_STAGE(PG8_SA(1, 0), a3, voffA);
;             PG8_WAIT_V(8); PG8_WAIT_L(0); PG8_BAR; PG8_MMA(1, 0, At, B0); PG8_MMA(1, 1, At, B1); PG8_BAR; PG8_SCHED;
;         }
	s_add_i32 s1, s1, s12
	v_lshl_add_u64 v[228:229], v[228:229], 0, s[18:19]
	s_mov_b32 m0, s1
	ds_read_b128 v[180:183], v166 offset:49152
	ds_read_b128 v[184:187], v166 offset:50176
	ds_read_b128 v[188:191], v166 offset:51200
	ds_read_b128 v[208:211], v166 offset:52224
	ds_read_b128 v[212:215], v166 offset:53248
	ds_read_b128 v[216:219], v166 offset:54272
	ds_read_b128 v[220:223], v166 offset:55296
	ds_read_b128 v[224:227], v166 offset:56320
	global_load_lds_dwordx4 v[228:229], off
	s_add_i32 m0, s1, 0x2000
	s_add_u32 s40, s40, 0x40080
	v_lshl_add_u64 v[228:229], v[230:231], 0, s[18:19]
	s_addc_u32 s41, s41, 0
	s_add_i32 s1, s22, s12
	global_load_lds_dwordx4 v[228:229], off
	v_lshl_add_u64 v[228:229], s[40:41], 0, v[0:1]
	s_mov_b32 m0, s1
	s_nop 0
	global_load_lds_dwordx4 v[228:229], off
	v_lshl_add_u64 v[228:229], s[40:41], 0, v[130:131]
	s_add_i32 m0, s1, 0x2000
	s_nop 0
	global_load_lds_dwordx4 v[228:229], off
	v_lshl_add_u64 v[228:229], v[232:233], 0, s[18:19]
	s_mov_b32 m0, s26
	s_nop 0
	global_load_lds_dwordx4 v[228:229], off
	v_lshl_add_u64 v[228:229], v[238:239], 0, s[18:19]
	s_mov_b32 m0, s57
	s_nop 0
	global_load_lds_dwordx4 v[228:229], off
	s_waitcnt vmcnt(8)
	s_waitcnt lgkmcnt(0)
	s_barrier
	s_waitcnt lgkmcnt(0)
	v_mfma_f32_16x16x32_bf16 v[62:65], v[142:145], v[180:183], v[62:65]
	v_mfma_f32_16x16x32_bf16 v[50:53], v[150:153], v[180:183], v[50:53]
	v_mfma_f32_16x16x32_bf16 v[46:49], v[142:145], v[188:191], v[46:49]
	v_mfma_f32_16x16x32_bf16 v[34:37], v[150:153], v[188:191], v[34:37]
	v_mfma_f32_16x16x32_bf16 v[30:33], v[142:145], v[212:215], v[30:33]
	v_mfma_f32_16x16x32_bf16 v[18:21], v[150:153], v[212:215], v[18:21]
	v_mfma_f32_16x16x32_bf16 v[10:13], v[142:145], v[220:223], v[10:13]
	v_mfma_f32_16x16x32_bf16 v[2:5], v[150:153], v[220:223], v[2:5]
	v_mfma_f32_16x16x32_bf16 v[62:65], v[146:149], v[184:187], v[62:65]
	v_mfma_f32_16x16x32_bf16 v[50:53], v[154:157], v[184:187], v[50:53]
	v_mfma_f32_16x16x32_bf16 v[46:49], v[146:149], v[208:211], v[46:49]
	v_mfma_f32_16x16x32_bf16 v[34:37], v[154:157], v[208:211], v[34:37]
	v_mfma_f32_16x16x32_bf16 v[30:33], v[146:149], v[216:219], v[30:33]
	v_mfma_f32_16x16x32_bf16 v[18:21], v[154:157], v[216:219], v[18:21]
	v_mfma_f32_16x16x32_bf16 v[10:13], v[146:149], v[224:227], v[10:13]
	v_mfma_f32_16x16x32_bf16 v[2:5], v[154:157], v[224:227], v[2:5]
	v_mfma_f32_16x16x32_bf16 v[58:61], v[158:161], v[180:183], v[58:61]
	v_mfma_f32_16x16x32_bf16 v[54:57], v[172:175], v[180:183], v[54:57]
	v_mfma_f32_16x16x32_bf16 v[42:45], v[158:161], v[188:191], v[42:45]
	v_mfma_f32_16x16x32_bf16 v[38:41], v[172:175], v[188:191], v[38:41]
	v_mfma_f32_16x16x32_bf16 v[26:29], v[158:161], v[212:215], v[26:29]
	v_mfma_f32_16x16x32_bf16 v[22:25], v[172:175], v[212:215], v[22:25]
	v_mfma_f32_16x16x32_bf16 v[14:17], v[158:161], v[220:223], v[14:17]
	v_mfma_f32_16x16x32_bf16 v[6:9], v[172:175], v[220:223], v[6:9]
	v_mfma_f32_16x16x32_bf16 v[58:61], v[168:171], v[184:187], v[58:61]
	v_mfma_f32_16x16x32_bf16 v[54:57], v[176:179], v[184:187], v[54:57]
	v_mfma_f32_16x16x32_bf16 v[42:45], v[168:171], v[208:211], v[42:45]
	v_mfma_f32_16x16x32_bf16 v[38:41], v[176:179], v[208:211], v[38:41]
	v_mfma_f32_16x16x32_bf16 v[26:29], v[168:171], v[216:219], v[26:29]
	v_mfma_f32_16x16x32_bf16 v[22:25], v[176:179], v[216:219], v[22:25]
	v_mfma_f32_16x16x32_bf16 v[14:17], v[168:171], v[224:227], v[14:17]
	v_mfma_f32_16x16x32_bf16 v[6:9], v[176:179], v[224:227], v[6:9]
	s_barrier
	s_add_u32 s36, s36, 0x100
	s_addc_u32 s37, s37, 0
	s_add_u32 vcc_hi, vcc_hi, 0x100
	s_addc_u32 s96, s96, 0
	s_cmp_ge_i32 s0, s56
	s_mov_b32 s40, s0
	s_cbranch_scc0 .LBB0_660
	s_setprio 0
	v_readlane_b32 s96, v250, 43

; #define PG8_STAGE(bufoff, gbase, voff) do { _Pragma("unroll") for (int _i = 0; _i < 2; ++_i) \
;         __builtin_amdgcn_global_load_lds((const unsigned*)((const char*)(gbase) + (voff)[_i]), (LAS unsigned*)(lds + (bufoff) + ldsw + _i * 8192), 16, 0, 0); } while (0)
; #define PG8_LDA(dst, b, h) do { _Pragma("unroll") for (int m = 0; m < 4; ++m) _Pragma("unroll") for (int k = 0; k < 2; ++k) dst[m][k] = *(const LAS bf16x8*)(lds + PG8_SA(b, h) + aoff + m * 2048 + k * 1024); } while (0)
; #define PG8_LDB(dst, b, h) do { _Pragma("unroll") for (int n = 0; n < 2; ++n) _Pragma("unroll") for (int k = 0; k < 2; ++k) dst[n][k] = *(const LAS bf16x8*)(lds + PG8_SB(b, h) + boff + n * 2048 + k * 1024); } while (0)
; #define PG8_WAIT_V(n) asm volatile("s_waitcnt vmcnt(" #n ")" ::: "memory")
; #define PG8_WAIT_L(n) asm volatile("s_waitcnt lgkmcnt(" #n ")" ::: "memory")
; #define PG8_BAR __builtin_amdgcn_s_barrier()
; template <class Epi, class Sched>
; __device__ __forceinline__ void gemm_phase(LAS unsigned char* lds, const Gemm g, const Sched& S, const Epi& E) {
;     ...
;         const bool has_next = S.next(ui + 1, nxt);
;         const char* nA = has_next ? (const char*)g.A + nxt.offA : cA; const char* nB = has_next ? (const char*)g.Bt + nxt.offB : cB;
;         for (int t = 0; t < nt; t += 2) {
;             const bool last = (t == nt - 2);
;             const char* a1 = cA + (size_t)(t + 1) * kstep;
;             const char* a2 = last ? nA : cA + (size_t)(t + 2) * kstep; const char* b2 = last ? nB : cB + (size_t)(t + 2) * kstep;
;             const char* a3 = a2 + kstep; const char* b3 = b2 + kstep;
;             if constexpr (Epi::MIDK) { if (t == (nt >> 1)) { int fr_ = fr, fq_ = fq; asm volatile("" : "+v"(fr_), "+v"(fq_)); E.mid(acc, cur, wr, wc, fr_, fq_); } }
;             PG8_LDB(B0, 0, 0); PG8_LDB(B1, 0, 1); PG8_SCHED; PG8_LDA(At, 0, 0); PG8_STAGE(PG8_SA(1, 1), a1 + hsA, voffA);
;             PG8_WAIT_V(8); PG8_WAIT_L(0); PG8_BAR; PG8_MMA(0, 0, At, B0); PG8_MMA(0, 1, At, B1); PG8_BAR; PG8_SCHED;
;     ...
; #pragma unroll
;         for (int a = 0; a < 2; ++a)
; #pragma unroll
;             for (int b = 0; b < 2; ++b)
; #pragma unroll
;                 for (int m = 0; m < 4; ++m)
; #pragma unroll
;                     for (int n = 0; n < 2; ++n) acc[a][b][m][n] = (f32x4){0.f, 0.f, 0.f, 0.f};
;         cur = nxt; cA = nA; cB = nB; ++ui;
.LBB0_761:
	s_add_u32 s40, s54, s36
	s_addc_u32 s41, s55, s37
	s_andn2_b64 vcc, exec, s[8:9]
	s_cbranch_vccnz .Lzc_21902
	s_and_b64 s[44:45], s[38:39], exec
	s_cselect_b32 s52, s41, s43
	s_cselect_b32 s56, s40, s42
	s_add_u32 s57, s42, 0x100
	v_mov_b32_e32 v2, 0
	v_readlane_b32 s22, v250, 4
	s_addc_u32 s64, s43, 0
	s_mov_b32 s46, 0
	s_mov_b64 s[42:43], 0
	v_mov_b32_e32 v3, v2
	v_mov_b32_e32 v4, v2
	v_mov_b32_e32 v5, v2
	v_mov_b32_e32 v6, v2
	v_mov_b32_e32 v7, v2
	v_mov_b32_e32 v8, v2
	v_mov_b32_e32 v9, v2
	v_mov_b32_e32 v18, v2
	v_mov_b32_e32 v19, v2
	v_mov_b32_e32 v20, v2
	v_mov_b32_e32 v21, v2
	v_mov_b32_e32 v22, v2
	v_mov_b32_e32 v23, v2
	v_mov_b32_e32 v24, v2
	v_mov_b32_e32 v25, v2
	v_mov_b32_e32 v34, v2
	v_mov_b32_e32 v35, v2
	v_mov_b32_e32 v36, v2
	v_mov_b32_e32 v37, v2
	v_mov_b32_e32 v38, v2
	v_mov_b32_e32 v39, v2
	v_mov_b32_e32 v40, v2
	v_mov_b32_e32 v41, v2
	v_mov_b32_e32 v50, v2
	v_mov_b32_e32 v51, v2
	v_mov_b32_e32 v52, v2
	v_mov_b32_e32 v53, v2
	v_mov_b32_e32 v54, v2
	v_mov_b32_e32 v55, v2
	v_mov_b32_e32 v56, v2
	v_mov_b32_e32 v57, v2
	v_mov_b32_e32 v10, v2
	v_mov_b32_e32 v11, v2
	v_mov_b32_e32 v12, v2
	v_mov_b32_e32 v13, v2
	v_mov_b32_e32 v14, v2
	v_mov_b32_e32 v15, v2
	v_mov_b32_e32 v16, v2
	v_mov_b32_e32 v17, v2
	v_mov_b32_e32 v26, v2
	v_mov_b32_e32 v27, v2
	v_mov_b32_e32 v28, v2
	v_mov_b32_e32 v29, v2
	v_mov_b32_e32 v30, v2
	v_mov_b32_e32 v31, v2
	v_mov_b32_e32 v32, v2
	v_mov_b32_e32 v33, v2
	v_mov_b32_e32 v42, v2
	v_mov_b32_e32 v43, v2
	v_mov_b32_e32 v44, v2
	v_mov_b32_e32 v45, v2
	v_mov_b32_e32 v46, v2
	v_mov_b32_e32 v47, v2
	v_mov_b32_e32 v48, v2
	v_mov_b32_e32 v49, v2
	v_mov_b32_e32 v58, v2
	v_mov_b32_e32 v59, v2
	v_mov_b32_e32 v60, v2
	v_mov_b32_e32 v61, v2
	v_mov_b32_e32 v62, v2
	v_mov_b32_e32 v63, v2
	v_mov_b32_e32 v64, v2
	v_mov_b32_e32 v65, v2
	v_mov_b32_e32 v66, v2
	v_mov_b32_e32 v67, v2
	v_mov_b32_e32 v68, v2
	v_mov_b32_e32 v69, v2
	v_mov_b32_e32 v70, v2
	v_mov_b32_e32 v71, v2
	v_mov_b32_e32 v72, v2
	v_mov_b32_e32 v73, v2
	v_mov_b32_e32 v82, v2
	v_mov_b32_e32 v83, v2
	v_mov_b32_e32 v84, v2
	v_mov_b32_e32 v85, v2
	v_mov_b32_e32 v86, v2
	v_mov_b32_e32 v87, v2
	v_mov_b32_e32 v88, v2
	v_mov_b32_e32 v89, v2
	v_mov_b32_e32 v98, v2
	v_mov_b32_e32 v99, v2
	v_mov_b32_e32 v100, v2
	v_mov_b32_e32 v101, v2
	v_mov_b32_e32 v102, v2
	v_mov_b32_e32 v103, v2
	v_mov_b32_e32 v104, v2
	v_mov_b32_e32 v105, v2
	v_mov_b32_e32 v114, v2
	v_mov_b32_e32 v115, v2
	v_mov_b32_e32 v116, v2
	v_mov_b32_e32 v117, v2
	v_mov_b32_e32 v118, v2
	v_mov_b32_e32 v119, v2
	v_mov_b32_e32 v120, v2
	v_mov_b32_e32 v121, v2
	v_mov_b32_e32 v74, v2
	v_mov_b32_e32 v75, v2
	v_mov_b32_e32 v76, v2
	v_mov_b32_e32 v77, v2
	v_mov_b32_e32 v78, v2
	v_mov_b32_e32 v79, v2
	v_mov_b32_e32 v80, v2
	v_mov_b32_e32 v81, v2
	v_mov_b32_e32 v90, v2
	v_mov_b32_e32 v91, v2
	v_mov_b32_e32 v92, v2
	v_mov_b32_e32 v93, v2
	v_mov_b32_e32 v94, v2
	v_mov_b32_e32 v95, v2
	v_mov_b32_e32 v96, v2
	v_mov_b32_e32 v97, v2
	v_mov_b32_e32 v106, v2
	v_mov_b32_e32 v107, v2
	v_mov_b32_e32 v108, v2
	v_mov_b32_e32 v109, v2
	v_mov_b32_e32 v110, v2
	v_mov_b32_e32 v111, v2
	v_mov_b32_e32 v112, v2
	v_mov_b32_e32 v113, v2
	v_mov_b32_e32 v126, v2
	v_mov_b32_e32 v127, v2
	v_mov_b32_e32 v128, v2
	v_mov_b32_e32 v129, v2
	v_mov_b32_e32 v122, v2
	v_mov_b32_e32 v123, v2
	v_mov_b32_e32 v124, v2
	v_mov_b32_e32 v125, v2
	v_readlane_b32 s23, v250, 5
	v_readlane_b32 s78, v250, 36
	v_readfirstlane_b32 s73, v193
	s_lshr_b32 s73, s73, 8
	s_cmp_eq_u32 s73, 1
	s_cbranch_scc0 .Lnp_763
	s_setprio 1
.Lnp_763:
.LBB0_763:
	s_add_i32 s73, s46, 2
	s_add_u32 s44, s42, 0x100
	s_addc_u32 s45, s43, 0
	s_add_u32 s47, s57, s42
	s_addc_u32 s74, s64, s43
	s_cmp_eq_u32 s49, s46
	s_cselect_b32 s46, 0, s44
	s_cselect_b32 s75, 0, s45
	s_cselect_b32 s76, s56, s47
	s_cselect_b32 s77, s52, s74
	s_add_u32 s46, s22, s46
	s_addc_u32 s47, s23, s75
	s_add_i32 s74, 0, 0x10000
	v_add_u32_e32 v0, s74, v144
	s_add_i32 s75, 0, 0x14000
	ds_read_b128 v[146:149], v0
	ds_read_b128 v[150:153], v0 offset:1024
	ds_read_b128 v[154:157], v0 offset:2048
	ds_read_b128 v[158:161], v0 offset:3072
	v_add_u32_e32 v0, s75, v144
	ds_read_b128 v[162:165], v0
	ds_read_b128 v[166:169], v0 offset:1024
	ds_read_b128 v[170:173], v0 offset:2048
	ds_read_b128 v[174:177], v0 offset:3072
	v_lshl_add_u64 v[190:191], v[138:139], 0, s[42:43]
	s_add_i32 m0, s11, 0xc000
	ds_read_b128 v[178:181], v145
	ds_read_b128 v[182:185], v145 offset:1024
	ds_read_b128 v[186:189], v145 offset:2048
	ds_read_b128 v[208:211], v145 offset:3072
	ds_read_b128 v[212:215], v145 offset:4096
	ds_read_b128 v[216:219], v145 offset:5120
	ds_read_b128 v[220:223], v145 offset:6144
	ds_read_b128 v[224:227], v145 offset:7168
	global_load_lds_dwordx4 v[190:191], off
	v_lshl_add_u64 v[190:191], v[140:141], 0, s[42:43]
	s_add_i32 m0, s11, 0xe000
	s_nop 0
	global_load_lds_dwordx4 v[190:191], off
	s_waitcnt vmcnt(8)
	s_waitcnt lgkmcnt(0)
	s_barrier
; #define PG8_STAGE(bufoff, gbase, voff) do { _Pragma("unroll") for (int _i = 0; _i < 2; ++_i) \
;         __builtin_amdgcn_global_load_lds((const unsigned*)((const char*)(gbase) + (voff)[_i]), (LAS unsigned*)(lds + (bufoff) + ldsw + _i * 8192), 16, 0, 0); } while (0)
; #define PG8_LDA(dst, b, h) do { _Pragma("unroll") for (int m = 0; m < 4; ++m) _Pragma("unroll") for (int k = 0; k < 2; ++k) dst[m][k] = *(const LAS bf16x8*)(lds + PG8_SA(b, h) + aoff + m * 2048 + k * 1024); } while (0)
; #define PG8_MMA(ai, bj, At, Bt) do { __builtin_amdgcn_s_setprio(1); _Pragma("unroll") for (int m = 0; m < 4; ++m) _Pragma("unroll") for (int n = 0; n < 2; ++n) _Pragma("unroll") for (int k = 0; k < 2; ++k) \
;         acc[ai][bj][m][n] = __builtin_amdgcn_mfma_f32_16x16x32_bf16(Bt[n][k], At[m][k], acc[ai][bj][m][n], 0, 0, 0); __builtin_amdgcn_s_setprio(0); } while (0)
; #define PG8_WAIT_V(n) asm volatile("s_waitcnt vmcnt(" #n ")" ::: "memory")
; #define PG8_WAIT_L(n) asm volatile("s_waitcnt lgkmcnt(" #n ")" ::: "memory")
; #define PG8_BAR __builtin_amdgcn_s_barrier()
; #define PG8_SCHED __builtin_amdgcn_sched_barrier(0)
; template <class Epi, class Sched>
; __device__ __forceinline__ void gemm_phase(LAS unsigned char* lds, const Gemm g, const Sched& S, const Epi& E) {
;     ...
;             PG8_WAIT_V(8); PG8_WAIT_L(0); PG8_BAR; PG8_MMA(0, 0, At, B0); PG8_MMA(0, 1, At, B1); PG8_BAR; PG8_SCHED;
;             PG8_LDA(At, 0, 1); PG8_STAGE(PG8_SB(0, 0), b2, voffB); PG8_STAGE(PG8_SB(0, 1), b2 + hsB, voffB); PG8_STAGE(PG8_SA(0, 0), a2, voffA);
;             PG8_WAIT_V(8); PG8_WAIT_L(0); PG8_BAR; PG8_MMA(1, 0, At, B0); PG8_MMA(1, 1, At, B1); PG8_BAR; PG8_SCHED;
	s_waitcnt lgkmcnt(0)
	v_mfma_f32_16x16x32_bf16 v[122:125], v[146:149], v[178:181], v[122:125]
	v_mfma_f32_16x16x32_bf16 v[126:129], v[154:157], v[178:181], v[126:129]
	v_mfma_f32_16x16x32_bf16 v[110:113], v[146:149], v[186:189], v[110:113]
	v_mfma_f32_16x16x32_bf16 v[106:109], v[154:157], v[186:189], v[106:109]
	v_mfma_f32_16x16x32_bf16 v[94:97], v[146:149], v[212:215], v[94:97]
	v_mfma_f32_16x16x32_bf16 v[90:93], v[154:157], v[212:215], v[90:93]
	v_mfma_f32_16x16x32_bf16 v[78:81], v[146:149], v[220:223], v[78:81]
	v_mfma_f32_16x16x32_bf16 v[74:77], v[154:157], v[220:223], v[74:77]
	v_mfma_f32_16x16x32_bf16 v[122:125], v[150:153], v[182:185], v[122:125]
	v_mfma_f32_16x16x32_bf16 v[126:129], v[158:161], v[182:185], v[126:129]
	v_mfma_f32_16x16x32_bf16 v[110:113], v[150:153], v[208:211], v[110:113]
	v_mfma_f32_16x16x32_bf16 v[106:109], v[158:161], v[208:211], v[106:109]
	v_mfma_f32_16x16x32_bf16 v[94:97], v[150:153], v[216:219], v[94:97]
	v_mfma_f32_16x16x32_bf16 v[90:93], v[158:161], v[216:219], v[90:93]
	v_mfma_f32_16x16x32_bf16 v[78:81], v[150:153], v[224:227], v[78:81]
	v_mfma_f32_16x16x32_bf16 v[74:77], v[158:161], v[224:227], v[74:77]
	v_mfma_f32_16x16x32_bf16 v[118:121], v[162:165], v[178:181], v[118:121]
	v_mfma_f32_16x16x32_bf16 v[114:117], v[170:173], v[178:181], v[114:117]
	v_mfma_f32_16x16x32_bf16 v[102:105], v[162:165], v[186:189], v[102:105]
	v_mfma_f32_16x16x32_bf16 v[98:101], v[170:173], v[186:189], v[98:101]
	v_mfma_f32_16x16x32_bf16 v[86:89], v[162:165], v[212:215], v[86:89]
	v_mfma_f32_16x16x32_bf16 v[82:85], v[170:173], v[212:215], v[82:85]
	v_mfma_f32_16x16x32_bf16 v[70:73], v[162:165], v[220:223], v[70:73]
	v_mfma_f32_16x16x32_bf16 v[66:69], v[170:173], v[220:223], v[66:69]
	v_mfma_f32_16x16x32_bf16 v[118:121], v[166:169], v[182:185], v[118:121]
	v_mfma_f32_16x16x32_bf16 v[114:117], v[174:177], v[182:185], v[114:117]
	v_mfma_f32_16x16x32_bf16 v[102:105], v[166:169], v[208:211], v[102:105]
	v_mfma_f32_16x16x32_bf16 v[98:101], v[174:177], v[208:211], v[98:101]
	v_mfma_f32_16x16x32_bf16 v[86:89], v[166:169], v[216:219], v[86:89]
	v_mfma_f32_16x16x32_bf16 v[82:85], v[174:177], v[216:219], v[82:85]
	v_mfma_f32_16x16x32_bf16 v[70:73], v[166:169], v[224:227], v[70:73]
	v_mfma_f32_16x16x32_bf16 v[66:69], v[174:177], v[224:227], v[66:69]
	s_barrier
	s_add_i32 s42, s74, s7
	v_lshl_add_u64 v[190:191], s[76:77], 0, v[134:135]
	s_mov_b32 m0, s42
	ds_read_b128 v[178:181], v145 offset:16384
	ds_read_b128 v[182:185], v145 offset:17408
	ds_read_b128 v[186:189], v145 offset:18432
	ds_read_b128 v[208:211], v145 offset:19456
	ds_read_b128 v[212:215], v145 offset:20480
	ds_read_b128 v[216:219], v145 offset:21504
	ds_read_b128 v[220:223], v145 offset:22528
	ds_read_b128 v[224:227], v145 offset:23552
	global_load_lds_dwordx4 v[190:191], off
	s_add_i32 m0, s42, 0x2000
	s_add_u32 s42, s76, s78
	v_lshl_add_u64 v[228:229], s[76:77], 0, v[130:131]
	s_addc_u32 s43, s77, 0
	s_add_i32 s74, s75, s7
	global_load_lds_dwordx4 v[228:229], off
	v_lshl_add_u64 v[230:231], s[42:43], 0, v[134:135]
	s_mov_b32 m0, s74
	v_lshl_add_u64 v[232:233], s[42:43], 0, v[130:131]
	global_load_lds_dwordx4 v[230:231], off
	s_add_i32 m0, s74, 0x2000
	v_lshl_add_u64 v[238:239], s[46:47], 0, v[136:137]
	global_load_lds_dwordx4 v[232:233], off
	s_mov_b32 m0, s11
	v_lshl_add_u64 v[240:241], s[46:47], 0, v[132:133]
	global_load_lds_dwordx4 v[238:239], off
	s_mov_b32 m0, s10
	s_nop 0
	global_load_lds_dwordx4 v[240:241], off
	s_waitcnt vmcnt(8)
	s_waitcnt lgkmcnt(0)
	s_barrier
	s_waitcnt lgkmcnt(0)
	v_mfma_f32_16x16x32_bf16 v[62:65], v[146:149], v[178:181], v[62:65]
	v_mfma_f32_16x16x32_bf16 v[58:61], v[154:157], v[178:181], v[58:61]
	v_mfma_f32_16x16x32_bf16 v[46:49], v[146:149], v[186:189], v[46:49]
	v_mfma_f32_16x16x32_bf16 v[42:45], v[154:157], v[186:189], v[42:45]
	v_mfma_f32_16x16x32_bf16 v[30:33], v[146:149], v[212:215], v[30:33]
	v_mfma_f32_16x16x32_bf16 v[26:29], v[154:157], v[212:215], v[26:29]
	v_mfma_f32_16x16x32_bf16 v[14:17], v[146:149], v[220:223], v[14:17]
	v_mfma_f32_16x16x32_bf16 v[10:13], v[154:157], v[220:223], v[10:13]
	v_mfma_f32_16x16x32_bf16 v[62:65], v[150:153], v[182:185], v[62:65]
	v_mfma_f32_16x16x32_bf16 v[58:61], v[158:161], v[182:185], v[58:61]
	v_mfma_f32_16x16x32_bf16 v[46:49], v[150:153], v[208:211], v[46:49]
	v_mfma_f32_16x16x32_bf16 v[42:45], v[158:161], v[208:211], v[42:45]
	v_mfma_f32_16x16x32_bf16 v[30:33], v[150:153], v[216:219], v[30:33]
	v_mfma_f32_16x16x32_bf16 v[26:29], v[158:161], v[216:219], v[26:29]
	v_mfma_f32_16x16x32_bf16 v[14:17], v[150:153], v[224:227], v[14:17]
	v_mfma_f32_16x16x32_bf16 v[10:13], v[158:161], v[224:227], v[10:13]
	v_mfma_f32_16x16x32_bf16 v[54:57], v[162:165], v[178:181], v[54:57]
	v_mfma_f32_16x16x32_bf16 v[50:53], v[170:173], v[178:181], v[50:53]
	v_mfma_f32_16x16x32_bf16 v[38:41], v[162:165], v[186:189], v[38:41]
	v_mfma_f32_16x16x32_bf16 v[34:37], v[170:173], v[186:189], v[34:37]
	v_mfma_f32_16x16x32_bf16 v[22:25], v[162:165], v[212:215], v[22:25]
	v_mfma_f32_16x16x32_bf16 v[18:21], v[170:173], v[212:215], v[18:21]
	v_mfma_f32_16x16x32_bf16 v[6:9], v[162:165], v[220:223], v[6:9]
	v_mfma_f32_16x16x32_bf16 v[2:5], v[170:173], v[220:223], v[2:5]
	v_mfma_f32_16x16x32_bf16 v[54:57], v[166:169], v[182:185], v[54:57]
	v_mfma_f32_16x16x32_bf16 v[50:53], v[174:177], v[182:185], v[50:53]
	v_mfma_f32_16x16x32_bf16 v[38:41], v[166:169], v[208:211], v[38:41]
	v_mfma_f32_16x16x32_bf16 v[34:37], v[174:177], v[208:211], v[34:37]
	v_mfma_f32_16x16x32_bf16 v[22:25], v[166:169], v[216:219], v[22:25]
	v_mfma_f32_16x16x32_bf16 v[18:21], v[174:177], v[216:219], v[18:21]
	v_mfma_f32_16x16x32_bf16 v[6:9], v[166:169], v[224:227], v[6:9]
	v_mfma_f32_16x16x32_bf16 v[2:5], v[174:177], v[224:227], v[2:5]
	s_barrier
; #define PG8_STAGE(bufoff, gbase, voff) do { _Pragma("unroll") for (int _i = 0; _i < 2; ++_i) \
;         __builtin_amdgcn_global_load_lds((const unsigned*)((const char*)(gbase) + (voff)[_i]), (LAS unsigned*)(lds + (bufoff) + ldsw + _i * 8192), 16, 0, 0); } while (0)
; #define PG8_LDA(dst, b, h) do { _Pragma("unroll") for (int m = 0; m < 4; ++m) _Pragma("unroll") for (int k = 0; k < 2; ++k) dst[m][k] = *(const LAS bf16x8*)(lds + PG8_SA(b, h) + aoff + m * 2048 + k * 1024); } while (0)
; #define PG8_LDB(dst, b, h) do { _Pragma("unroll") for (int n = 0; n < 2; ++n) _Pragma("unroll") for (int k = 0; k < 2; ++k) dst[n][k] = *(const LAS bf16x8*)(lds + PG8_SB(b, h) + boff + n * 2048 + k * 1024); } while (0)
; #define PG8_MMA(ai, bj, At, Bt) do { __builtin_amdgcn_s_setprio(1); _Pragma("unroll") for (int m = 0; m < 4; ++m) _Pragma("unroll") for (int n = 0; n < 2; ++n) _Pragma("unroll") for (int k = 0; k < 2; ++k) \
;         acc[ai][bj][m][n] = __builtin_amdgcn_mfma_f32_16x16x32_bf16(Bt[n][k], At[m][k], acc[ai][bj][m][n], 0, 0, 0); __builtin_amdgcn_s_setprio(0); } while (0)
; #define PG8_WAIT_V(n) asm volatile("s_waitcnt vmcnt(" #n ")" ::: "memory")
; #define PG8_WAIT_L(n) asm volatile("s_waitcnt lgkmcnt(" #n ")" ::: "memory")
; #define PG8_BAR __builtin_amdgcn_s_barrier()
; #define PG8_SCHED __builtin_amdgcn_sched_barrier(0)
; template <class Epi, class Sched>
; __device__ __forceinline__ void gemm_phase(LAS unsigned char* lds, const Gemm g, const Sched& S, const Epi& E) {
;     ...
;             PG8_LDB(B0, 1, 0); PG8_LDB(B1, 1, 1); PG8_SCHED; PG8_LDA(At, 1, 0); PG8_STAGE(PG8_SA(0, 1), a2 + hsA, voffA);
;             PG8_WAIT_V(8); PG8_WAIT_L(0); PG8_BAR; PG8_MMA(0, 0, At, B0); PG8_MMA(0, 1, At, B1); PG8_BAR; PG8_SCHED;
;             PG8_LDA(At, 1, 1); PG8_STAGE(PG8_SB(1, 0), b3, voffB); PG8_STAGE(PG8_SB(1, 1), b3 + hsB, voffB); PG8_STAGE(PG8_SA(1, 0), a3, voffA);
;             PG8_WAIT_V(8); PG8_WAIT_L(0); PG8_BAR; PG8_MMA(1, 0, At, B0); PG8_MMA(1, 1, At, B1); PG8_BAR; PG8_SCHED;
;         }
	s_add_i32 s74, 0, 0x18000
	v_add_u32_e32 v0, s74, v144
	s_add_i32 s75, 0, 0x1c000
	ds_read_b128 v[146:149], v0
	ds_read_b128 v[150:153], v0 offset:1024
	ds_read_b128 v[154:157], v0 offset:2048
	ds_read_b128 v[158:161], v0 offset:3072
	v_add_u32_e32 v0, s75, v144
	ds_read_b128 v[162:165], v0
	ds_read_b128 v[166:169], v0 offset:1024
	ds_read_b128 v[170:173], v0 offset:2048
	ds_read_b128 v[174:177], v0 offset:3072
	s_add_u32 s42, s46, 0x20000
	s_addc_u32 s43, s47, 0
	s_mov_b32 m0, s12
	v_lshl_add_u64 v[242:243], s[42:43], 0, v[136:137]
	ds_read_b128 v[178:181], v145 offset:32768
	ds_read_b128 v[182:185], v145 offset:33792
	ds_read_b128 v[186:189], v145 offset:34816
	ds_read_b128 v[208:211], v145 offset:35840
	ds_read_b128 v[212:215], v145 offset:36864
	ds_read_b128 v[216:219], v145 offset:37888
	ds_read_b128 v[220:223], v145 offset:38912
	ds_read_b128 v[224:227], v145 offset:39936
	global_load_lds_dwordx4 v[242:243], off
	v_lshl_add_u64 v[242:243], s[42:43], 0, v[132:133]
	s_mov_b32 m0, s16
	s_nop 0
	global_load_lds_dwordx4 v[242:243], off
	s_waitcnt vmcnt(8)
	s_waitcnt lgkmcnt(0)
	s_barrier
	s_waitcnt lgkmcnt(0)
	v_mfma_f32_16x16x32_bf16 v[122:125], v[146:149], v[178:181], v[122:125]
	v_mfma_f32_16x16x32_bf16 v[126:129], v[154:157], v[178:181], v[126:129]
	v_mfma_f32_16x16x32_bf16 v[110:113], v[146:149], v[186:189], v[110:113]
	v_mfma_f32_16x16x32_bf16 v[106:109], v[154:157], v[186:189], v[106:109]
	v_mfma_f32_16x16x32_bf16 v[94:97], v[146:149], v[212:215], v[94:97]
	v_mfma_f32_16x16x32_bf16 v[90:93], v[154:157], v[212:215], v[90:93]
	v_mfma_f32_16x16x32_bf16 v[78:81], v[146:149], v[220:223], v[78:81]
	v_mfma_f32_16x16x32_bf16 v[74:77], v[154:157], v[220:223], v[74:77]
	v_mfma_f32_16x16x32_bf16 v[122:125], v[150:153], v[182:185], v[122:125]
	v_mfma_f32_16x16x32_bf16 v[126:129], v[158:161], v[182:185], v[126:129]
	v_mfma_f32_16x16x32_bf16 v[110:113], v[150:153], v[208:211], v[110:113]
	v_mfma_f32_16x16x32_bf16 v[106:109], v[158:161], v[208:211], v[106:109]
	v_mfma_f32_16x16x32_bf16 v[94:97], v[150:153], v[216:219], v[94:97]
	v_mfma_f32_16x16x32_bf16 v[90:93], v[158:161], v[216:219], v[90:93]
	v_mfma_f32_16x16x32_bf16 v[78:81], v[150:153], v[224:227], v[78:81]
	v_mfma_f32_16x16x32_bf16 v[74:77], v[158:161], v[224:227], v[74:77]
	v_mfma_f32_16x16x32_bf16 v[118:121], v[162:165], v[178:181], v[118:121]
	v_mfma_f32_16x16x32_bf16 v[114:117], v[170:173], v[178:181], v[114:117]
	v_mfma_f32_16x16x32_bf16 v[102:105], v[162:165], v[186:189], v[102:105]
	v_mfma_f32_16x16x32_bf16 v[98:101], v[170:173], v[186:189], v[98:101]
	v_mfma_f32_16x16x32_bf16 v[86:89], v[162:165], v[212:215], v[86:89]
	v_mfma_f32_16x16x32_bf16 v[82:85], v[170:173], v[212:215], v[82:85]
	v_mfma_f32_16x16x32_bf16 v[70:73], v[162:165], v[220:223], v[70:73]
	v_mfma_f32_16x16x32_bf16 v[66:69], v[170:173], v[220:223], v[66:69]
	v_mfma_f32_16x16x32_bf16 v[118:121], v[166:169], v[182:185], v[118:121]
	v_mfma_f32_16x16x32_bf16 v[114:117], v[174:177], v[182:185], v[114:117]
	v_mfma_f32_16x16x32_bf16 v[102:105], v[166:169], v[208:211], v[102:105]
	v_mfma_f32_16x16x32_bf16 v[98:101], v[174:177], v[208:211], v[98:101]
	v_mfma_f32_16x16x32_bf16 v[86:89], v[166:169], v[216:219], v[86:89]
	v_mfma_f32_16x16x32_bf16 v[82:85], v[174:177], v[216:219], v[82:85]
	v_mfma_f32_16x16x32_bf16 v[70:73], v[166:169], v[224:227], v[70:73]
	v_mfma_f32_16x16x32_bf16 v[66:69], v[174:177], v[224:227], v[66:69]
	s_barrier
	s_add_i32 s42, s74, s7
	v_lshl_add_u64 v[190:191], v[190:191], 0, s[18:19]
	s_mov_b32 m0, s42
	ds_read_b128 v[178:181], v145 offset:49152
	ds_read_b128 v[182:185], v145 offset:50176
	ds_read_b128 v[186:189], v145 offset:51200
	ds_read_b128 v[208:211], v145 offset:52224
	ds_read_b128 v[212:215], v145 offset:53248
	ds_read_b128 v[216:219], v145 offset:54272
	ds_read_b128 v[220:223], v145 offset:55296
	ds_read_b128 v[224:227], v145 offset:56320
	global_load_lds_dwordx4 v[190:191], off
	v_lshl_add_u64 v[190:191], v[228:229], 0, s[18:19]
	s_add_i32 m0, s42, 0x2000
	s_add_i32 s42, s75, s7
	global_load_lds_dwordx4 v[190:191], off
	v_lshl_add_u64 v[190:191], v[230:231], 0, s[18:19]
	s_mov_b32 m0, s42
	s_nop 0
	global_load_lds_dwordx4 v[190:191], off
	v_lshl_add_u64 v[190:191], v[232:233], 0, s[18:19]
	s_add_i32 m0, s42, 0x2000
	s_nop 0
	global_load_lds_dwordx4 v[190:191], off
	v_lshl_add_u64 v[190:191], v[238:239], 0, s[18:19]
	s_mov_b32 m0, s30
	s_nop 0
	global_load_lds_dwordx4 v[190:191], off
	v_lshl_add_u64 v[190:191], v[240:241], 0, s[18:19]
	s_mov_b32 m0, s48
	s_nop 0
	global_load_lds_dwordx4 v[190:191], off
	s_waitcnt vmcnt(8)
	s_waitcnt lgkmcnt(0)
	s_barrier
	s_waitcnt lgkmcnt(0)
	v_mfma_f32_16x16x32_bf16 v[62:65], v[146:149], v[178:181], v[62:65]
	v_mfma_f32_16x16x32_bf16 v[58:61], v[154:157], v[178:181], v[58:61]
	v_mfma_f32_16x16x32_bf16 v[46:49], v[146:149], v[186:189], v[46:49]
	v_mfma_f32_16x16x32_bf16 v[42:45], v[154:157], v[186:189], v[42:45]
	v_mfma_f32_16x16x32_bf16 v[30:33], v[146:149], v[212:215], v[30:33]
	v_mfma_f32_16x16x32_bf16 v[26:29], v[154:157], v[212:215], v[26:29]
	v_mfma_f32_16x16x32_bf16 v[14:17], v[146:149], v[220:223], v[14:17]
	v_mfma_f32_16x16x32_bf16 v[10:13], v[154:157], v[220:223], v[10:13]
	v_mfma_f32_16x16x32_bf16 v[62:65], v[150:153], v[182:185], v[62:65]
	v_mfma_f32_16x16x32_bf16 v[58:61], v[158:161], v[182:185], v[58:61]
	v_mfma_f32_16x16x32_bf16 v[46:49], v[150:153], v[208:211], v[46:49]
	v_mfma_f32_16x16x32_bf16 v[42:45], v[158:161], v[208:211], v[42:45]
	v_mfma_f32_16x16x32_bf16 v[30:33], v[150:153], v[216:219], v[30:33]
	v_mfma_f32_16x16x32_bf16 v[26:29], v[158:161], v[216:219], v[26:29]
	v_mfma_f32_16x16x32_bf16 v[14:17], v[150:153], v[224:227], v[14:17]
	v_mfma_f32_16x16x32_bf16 v[10:13], v[158:161], v[224:227], v[10:13]
	v_mfma_f32_16x16x32_bf16 v[54:57], v[162:165], v[178:181], v[54:57]
	v_mfma_f32_16x16x32_bf16 v[50:53], v[170:173], v[178:181], v[50:53]
	v_mfma_f32_16x16x32_bf16 v[38:41], v[162:165], v[186:189], v[38:41]
	v_mfma_f32_16x16x32_bf16 v[34:37], v[170:173], v[186:189], v[34:37]
	v_mfma_f32_16x16x32_bf16 v[22:25], v[162:165], v[212:215], v[22:25]
	v_mfma_f32_16x16x32_bf16 v[18:21], v[170:173], v[212:215], v[18:21]
	v_mfma_f32_16x16x32_bf16 v[6:9], v[162:165], v[220:223], v[6:9]
	v_mfma_f32_16x16x32_bf16 v[2:5], v[170:173], v[220:223], v[2:5]
	v_mfma_f32_16x16x32_bf16 v[54:57], v[166:169], v[182:185], v[54:57]
	v_mfma_f32_16x16x32_bf16 v[50:53], v[174:177], v[182:185], v[50:53]
	v_mfma_f32_16x16x32_bf16 v[38:41], v[166:169], v[208:211], v[38:41]
	v_mfma_f32_16x16x32_bf16 v[34:37], v[174:177], v[208:211], v[34:37]
	v_mfma_f32_16x16x32_bf16 v[22:25], v[166:169], v[216:219], v[22:25]
	v_mfma_f32_16x16x32_bf16 v[18:21], v[174:177], v[216:219], v[18:21]
	v_mfma_f32_16x16x32_bf16 v[6:9], v[166:169], v[224:227], v[6:9]
	v_mfma_f32_16x16x32_bf16 v[2:5], v[174:177], v[224:227], v[2:5]
	s_barrier
	s_cmp_ge_i32 s73, s24
	s_mov_b64 s[42:43], s[44:45]
	s_mov_b32 s46, s73
	s_cbranch_scc0 .LBB0_763
	s_setprio 0

; #define PG8_STAGE(bufoff, gbase, voff) do { _Pragma("unroll") for (int _i = 0; _i < 2; ++_i) \
;         __builtin_amdgcn_global_load_lds((const unsigned*)((const char*)(gbase) + (voff)[_i]), (LAS unsigned*)(lds + (bufoff) + ldsw + _i * 8192), 16, 0, 0); } while (0)
; #define PG8_LDA(dst, b, h) do { _Pragma("unroll") for (int m = 0; m < 4; ++m) _Pragma("unroll") for (int k = 0; k < 2; ++k) dst[m][k] = *(const LAS bf16x8*)(lds + PG8_SA(b, h) + aoff + m * 2048 + k * 1024); } while (0)
; #define PG8_LDB(dst, b, h) do { _Pragma("unroll") for (int n = 0; n < 2; ++n) _Pragma("unroll") for (int k = 0; k < 2; ++k) dst[n][k] = *(const LAS bf16x8*)(lds + PG8_SB(b, h) + boff + n * 2048 + k * 1024); } while (0)
; #define PG8_WAIT_V(n) asm volatile("s_waitcnt vmcnt(" #n ")" ::: "memory")
; #define PG8_WAIT_L(n) asm volatile("s_waitcnt lgkmcnt(" #n ")" ::: "memory")
; #define PG8_BAR __builtin_amdgcn_s_barrier()
; template <class Epi, class Sched>
; __device__ __forceinline__ void gemm_phase(LAS unsigned char* lds, const Gemm g, const Sched& S, const Epi& E) {
;     ...
;         const bool has_next = S.next(ui + 1, nxt);
;         const char* nA = has_next ? (const char*)g.A + nxt.offA : cA; const char* nB = has_next ? (const char*)g.Bt + nxt.offB : cB;
;         for (int t = 0; t < nt; t += 2) {
;             const bool last = (t == nt - 2);
;             const char* a1 = cA + (size_t)(t + 1) * kstep;
;             const char* a2 = last ? nA : cA + (size_t)(t + 2) * kstep; const char* b2 = last ? nB : cB + (size_t)(t + 2) * kstep;
;             const char* a3 = a2 + kstep; const char* b3 = b2 + kstep;
;             if constexpr (Epi::MIDK) { if (t == (nt >> 1)) { int fr_ = fr, fq_ = fq; asm volatile("" : "+v"(fr_), "+v"(fq_)); E.mid(acc, cur, wr, wc, fr_, fq_); } }
;             PG8_LDB(B0, 0, 0); PG8_LDB(B1, 0, 1); PG8_SCHED; PG8_LDA(At, 0, 0); PG8_STAGE(PG8_SA(1, 1), a1 + hsA, voffA);
;             PG8_WAIT_V(8); PG8_WAIT_L(0); PG8_BAR; PG8_MMA(0, 0, At, B0); PG8_MMA(0, 1, At, B1); PG8_BAR; PG8_SCHED;
;     ...
; #pragma unroll
;         for (int a = 0; a < 2; ++a)
; #pragma unroll
;             for (int b = 0; b < 2; ++b)
; #pragma unroll
;                 for (int m = 0; m < 4; ++m)
; #pragma unroll
;                     for (int n = 0; n < 2; ++n) acc[a][b][m][n] = (f32x4){0.f, 0.f, 0.f, 0.f};
;         cur = nxt; cA = nA; cB = nB; ++ui;
.LBB0_910:
	s_add_u32 s46, s54, s42
	s_addc_u32 s47, s55, s43
	v_readlane_b32 s22, v254, 12
	v_readlane_b32 s23, v254, 13
	s_add_u32 s48, s22, s44
	s_addc_u32 s49, s23, s45
	s_andn2_b64 vcc, exec, s[20:21]
	s_waitcnt lgkmcnt(0)
	s_cbranch_vccnz .Lzc_25928
	s_and_b64 s[76:77], s[36:37], exec
	s_cselect_b32 s39, s47, s1
	s_cselect_b32 s41, s46, s0
	s_cselect_b32 s82, s49, s51
	s_cselect_b32 s83, s48, s50
	s_add_u32 s0, s0, 0x40080
	s_addc_u32 s1, s1, 0
	s_add_u32 s84, s50, 0x100
	v_mov_b32_e32 v2, 0
	s_addc_u32 s85, s51, 0
	s_mov_b32 s50, 0
	v_mov_b32_e32 v3, v2
	v_mov_b32_e32 v4, v2
	v_mov_b32_e32 v5, v2
	v_mov_b32_e32 v6, v2
	v_mov_b32_e32 v7, v2
	v_mov_b32_e32 v8, v2
	v_mov_b32_e32 v9, v2
	v_mov_b32_e32 v18, v2
	v_mov_b32_e32 v19, v2
	v_mov_b32_e32 v20, v2
	v_mov_b32_e32 v21, v2
	v_mov_b32_e32 v22, v2
	v_mov_b32_e32 v23, v2
	v_mov_b32_e32 v24, v2
	v_mov_b32_e32 v25, v2
	v_mov_b32_e32 v34, v2
	v_mov_b32_e32 v35, v2
	v_mov_b32_e32 v36, v2
	v_mov_b32_e32 v37, v2
	v_mov_b32_e32 v38, v2
	v_mov_b32_e32 v39, v2
	v_mov_b32_e32 v40, v2
	v_mov_b32_e32 v41, v2
	v_mov_b32_e32 v50, v2
	v_mov_b32_e32 v51, v2
	v_mov_b32_e32 v52, v2
	v_mov_b32_e32 v53, v2
	v_mov_b32_e32 v54, v2
	v_mov_b32_e32 v55, v2
	v_mov_b32_e32 v56, v2
	v_mov_b32_e32 v57, v2
	v_mov_b32_e32 v10, v2
	v_mov_b32_e32 v11, v2
	v_mov_b32_e32 v12, v2
	v_mov_b32_e32 v13, v2
	v_mov_b32_e32 v14, v2
	v_mov_b32_e32 v15, v2
	v_mov_b32_e32 v16, v2
	v_mov_b32_e32 v17, v2
	v_mov_b32_e32 v26, v2
	v_mov_b32_e32 v27, v2
	v_mov_b32_e32 v28, v2
	v_mov_b32_e32 v29, v2
	v_mov_b32_e32 v30, v2
	v_mov_b32_e32 v31, v2
	v_mov_b32_e32 v32, v2
	v_mov_b32_e32 v33, v2
	v_mov_b32_e32 v42, v2
	v_mov_b32_e32 v43, v2
	v_mov_b32_e32 v44, v2
	v_mov_b32_e32 v45, v2
	v_mov_b32_e32 v46, v2
	v_mov_b32_e32 v47, v2
	v_mov_b32_e32 v48, v2
	v_mov_b32_e32 v49, v2
	v_mov_b32_e32 v58, v2
	v_mov_b32_e32 v59, v2
	v_mov_b32_e32 v60, v2
	v_mov_b32_e32 v61, v2
	v_mov_b32_e32 v62, v2
	v_mov_b32_e32 v63, v2
	v_mov_b32_e32 v64, v2
	v_mov_b32_e32 v65, v2
	v_mov_b32_e32 v66, v2
	v_mov_b32_e32 v67, v2
	v_mov_b32_e32 v68, v2
	v_mov_b32_e32 v69, v2
	v_mov_b32_e32 v70, v2
	v_mov_b32_e32 v71, v2
	v_mov_b32_e32 v72, v2
	v_mov_b32_e32 v73, v2
	v_mov_b32_e32 v82, v2
	v_mov_b32_e32 v83, v2
	v_mov_b32_e32 v84, v2
	v_mov_b32_e32 v85, v2
	v_mov_b32_e32 v86, v2
	v_mov_b32_e32 v87, v2
	v_mov_b32_e32 v88, v2
	v_mov_b32_e32 v89, v2
	v_mov_b32_e32 v98, v2
	v_mov_b32_e32 v99, v2
	v_mov_b32_e32 v100, v2
	v_mov_b32_e32 v101, v2
	v_mov_b32_e32 v102, v2
	v_mov_b32_e32 v103, v2
	v_mov_b32_e32 v104, v2
	v_mov_b32_e32 v105, v2
	v_mov_b32_e32 v114, v2
	v_mov_b32_e32 v115, v2
	v_mov_b32_e32 v116, v2
	v_mov_b32_e32 v117, v2
	v_mov_b32_e32 v118, v2
	v_mov_b32_e32 v119, v2
	v_mov_b32_e32 v120, v2
	v_mov_b32_e32 v121, v2
	v_mov_b32_e32 v74, v2
	v_mov_b32_e32 v75, v2
	v_mov_b32_e32 v76, v2
	v_mov_b32_e32 v77, v2
	v_mov_b32_e32 v78, v2
	v_mov_b32_e32 v79, v2
	v_mov_b32_e32 v80, v2
	v_mov_b32_e32 v81, v2
	v_mov_b32_e32 v90, v2
	v_mov_b32_e32 v91, v2
	v_mov_b32_e32 v92, v2
	v_mov_b32_e32 v93, v2
	v_mov_b32_e32 v94, v2
	v_mov_b32_e32 v95, v2
	v_mov_b32_e32 v96, v2
	v_mov_b32_e32 v97, v2
	v_mov_b32_e32 v106, v2
	v_mov_b32_e32 v107, v2
	v_mov_b32_e32 v108, v2
	v_mov_b32_e32 v109, v2
	v_mov_b32_e32 v110, v2
	v_mov_b32_e32 v111, v2
	v_mov_b32_e32 v112, v2
	v_mov_b32_e32 v113, v2
	v_mov_b32_e32 v126, v2
	v_mov_b32_e32 v127, v2
	v_mov_b32_e32 v128, v2
	v_mov_b32_e32 v129, v2
	v_mov_b32_e32 v122, v2
	v_mov_b32_e32 v123, v2
	v_mov_b32_e32 v124, v2
	v_mov_b32_e32 v125, v2
	v_readfirstlane_b32 s96, v193
	s_lshr_b32 s96, s96, 8
	s_cmp_eq_u32 s96, 1
	s_cbranch_scc0 .Lnp_912
	s_setprio 1
.Lnp_912:
.LBB0_912:
	s_add_i32 s96, s50, 2
	s_add_u32 s51, s0, 0xfffc0080
	s_addc_u32 s74, s1, -1
	s_add_i32 s75, 0, 0x10000
	s_cmp_eq_u32 s73, s50
	s_cselect_b32 s77, s39, s74
	s_cselect_b32 s76, s41, s51
	s_cselect_b32 s51, s82, s85
	s_cselect_b32 s50, s83, s84
	s_add_i32 s74, 0, 0x14000
	v_add_u32_e32 v142, s75, v184
	v_add_u32_e32 v168, s74, v184
	ds_read_b128 v[130:133], v142
	ds_read_b128 v[134:137], v142 offset:1024
	ds_read_b128 v[138:141], v142 offset:2048
	ds_read_b128 v[142:145], v142 offset:3072
	ds_read_b128 v[146:149], v168
	ds_read_b128 v[150:153], v168 offset:1024
	ds_read_b128 v[164:167], v168 offset:2048
	ds_read_b128 v[168:171], v168 offset:3072
	v_lshl_add_u64 v[180:181], s[0:1], 0, v[160:161]
	s_add_i32 m0, s11, 0xc000
	ds_read_b128 v[172:175], v185
	ds_read_b128 v[176:179], v185 offset:1024
	ds_read_b128 v[186:189], v185 offset:2048
	ds_read_b128 v[208:211], v185 offset:3072
	ds_read_b128 v[212:215], v185 offset:4096
	ds_read_b128 v[216:219], v185 offset:5120
	ds_read_b128 v[220:223], v185 offset:6144
	ds_read_b128 v[224:227], v185 offset:7168
	global_load_lds_dwordx4 v[180:181], off
	v_lshl_add_u64 v[180:181], s[0:1], 0, v[162:163]
	s_add_i32 m0, s11, 0xe000
	s_nop 0
	global_load_lds_dwordx4 v[180:181], off
	s_waitcnt vmcnt(8)
	s_waitcnt lgkmcnt(0)
	s_barrier
; #define PG8_STAGE(bufoff, gbase, voff) do { _Pragma("unroll") for (int _i = 0; _i < 2; ++_i) \
;         __builtin_amdgcn_global_load_lds((const unsigned*)((const char*)(gbase) + (voff)[_i]), (LAS unsigned*)(lds + (bufoff) + ldsw + _i * 8192), 16, 0, 0); } while (0)
; #define PG8_LDA(dst, b, h) do { _Pragma("unroll") for (int m = 0; m < 4; ++m) _Pragma("unroll") for (int k = 0; k < 2; ++k) dst[m][k] = *(const LAS bf16x8*)(lds + PG8_SA(b, h) + aoff + m * 2048 + k * 1024); } while (0)
; #define PG8_MMA(ai, bj, At, Bt) do { __builtin_amdgcn_s_setprio(1); _Pragma("unroll") for (int m = 0; m < 4; ++m) _Pragma("unroll") for (int n = 0; n < 2; ++n) _Pragma("unroll") for (int k = 0; k < 2; ++k) \
;         acc[ai][bj][m][n] = __builtin_amdgcn_mfma_f32_16x16x32_bf16(Bt[n][k], At[m][k], acc[ai][bj][m][n], 0, 0, 0); __builtin_amdgcn_s_setprio(0); } while (0)
; #define PG8_WAIT_V(n) asm volatile("s_waitcnt vmcnt(" #n ")" ::: "memory")
; #define PG8_WAIT_L(n) asm volatile("s_waitcnt lgkmcnt(" #n ")" ::: "memory")
; #define PG8_BAR __builtin_amdgcn_s_barrier()
; #define PG8_SCHED __builtin_amdgcn_sched_barrier(0)
; template <class Epi, class Sched>
; __device__ __forceinline__ void gemm_phase(LAS unsigned char* lds, const Gemm g, const Sched& S, const Epi& E) {
;     ...
;             PG8_WAIT_V(8); PG8_WAIT_L(0); PG8_BAR; PG8_MMA(0, 0, At, B0); PG8_MMA(0, 1, At, B1); PG8_BAR; PG8_SCHED;
;             PG8_LDA(At, 0, 1); PG8_STAGE(PG8_SB(0, 0), b2, voffB); PG8_STAGE(PG8_SB(0, 1), b2 + hsB, voffB); PG8_STAGE(PG8_SA(0, 0), a2, voffA);
;             PG8_WAIT_V(8); PG8_WAIT_L(0); PG8_BAR; PG8_MMA(1, 0, At, B0); PG8_MMA(1, 1, At, B1); PG8_BAR; PG8_SCHED;
	s_waitcnt lgkmcnt(0)
	v_mfma_f32_16x16x32_bf16 v[122:125], v[130:133], v[172:175], v[122:125]
	v_mfma_f32_16x16x32_bf16 v[126:129], v[138:141], v[172:175], v[126:129]
	v_mfma_f32_16x16x32_bf16 v[110:113], v[130:133], v[186:189], v[110:113]
	v_mfma_f32_16x16x32_bf16 v[106:109], v[138:141], v[186:189], v[106:109]
	v_mfma_f32_16x16x32_bf16 v[94:97], v[130:133], v[212:215], v[94:97]
	v_mfma_f32_16x16x32_bf16 v[90:93], v[138:141], v[212:215], v[90:93]
	v_mfma_f32_16x16x32_bf16 v[78:81], v[130:133], v[220:223], v[78:81]
	v_mfma_f32_16x16x32_bf16 v[74:77], v[138:141], v[220:223], v[74:77]
	v_mfma_f32_16x16x32_bf16 v[122:125], v[134:137], v[176:179], v[122:125]
	v_mfma_f32_16x16x32_bf16 v[126:129], v[142:145], v[176:179], v[126:129]
	v_mfma_f32_16x16x32_bf16 v[110:113], v[134:137], v[208:211], v[110:113]
	v_mfma_f32_16x16x32_bf16 v[106:109], v[142:145], v[208:211], v[106:109]
	v_mfma_f32_16x16x32_bf16 v[94:97], v[134:137], v[216:219], v[94:97]
	v_mfma_f32_16x16x32_bf16 v[90:93], v[142:145], v[216:219], v[90:93]
	v_mfma_f32_16x16x32_bf16 v[78:81], v[134:137], v[224:227], v[78:81]
	v_mfma_f32_16x16x32_bf16 v[74:77], v[142:145], v[224:227], v[74:77]
	v_mfma_f32_16x16x32_bf16 v[118:121], v[146:149], v[172:175], v[118:121]
	v_mfma_f32_16x16x32_bf16 v[114:117], v[164:167], v[172:175], v[114:117]
	v_mfma_f32_16x16x32_bf16 v[102:105], v[146:149], v[186:189], v[102:105]
	v_mfma_f32_16x16x32_bf16 v[98:101], v[164:167], v[186:189], v[98:101]
	v_mfma_f32_16x16x32_bf16 v[86:89], v[146:149], v[212:215], v[86:89]
	v_mfma_f32_16x16x32_bf16 v[82:85], v[164:167], v[212:215], v[82:85]
	v_mfma_f32_16x16x32_bf16 v[70:73], v[146:149], v[220:223], v[70:73]
	v_mfma_f32_16x16x32_bf16 v[66:69], v[164:167], v[220:223], v[66:69]
	v_mfma_f32_16x16x32_bf16 v[118:121], v[150:153], v[176:179], v[118:121]
	v_mfma_f32_16x16x32_bf16 v[114:117], v[168:171], v[176:179], v[114:117]
	v_mfma_f32_16x16x32_bf16 v[102:105], v[150:153], v[208:211], v[102:105]
	v_mfma_f32_16x16x32_bf16 v[98:101], v[168:171], v[208:211], v[98:101]
	v_mfma_f32_16x16x32_bf16 v[86:89], v[150:153], v[216:219], v[86:89]
	v_mfma_f32_16x16x32_bf16 v[82:85], v[168:171], v[216:219], v[82:85]
	v_mfma_f32_16x16x32_bf16 v[70:73], v[150:153], v[224:227], v[70:73]
	v_mfma_f32_16x16x32_bf16 v[66:69], v[168:171], v[224:227], v[66:69]
	s_barrier
	s_add_i32 s75, s75, s7
	v_lshl_add_u64 v[180:181], s[50:51], 0, v[0:1]
	s_mov_b32 m0, s75
	ds_read_b128 v[172:175], v185 offset:16384
	ds_read_b128 v[176:179], v185 offset:17408
	ds_read_b128 v[186:189], v185 offset:18432
	ds_read_b128 v[208:211], v185 offset:19456
	ds_read_b128 v[212:215], v185 offset:20480
	ds_read_b128 v[216:219], v185 offset:21504
	ds_read_b128 v[220:223], v185 offset:22528
	ds_read_b128 v[224:227], v185 offset:23552
	global_load_lds_dwordx4 v[180:181], off
	s_add_i32 m0, s75, 0x2000
	s_add_u32 vcc_lo, s50, 0x40000
	v_lshl_add_u64 v[190:191], s[50:51], 0, v[154:155]
	s_addc_u32 vcc_hi, s51, 0
	s_add_i32 s74, s74, s7
	global_load_lds_dwordx4 v[190:191], off
	v_lshl_add_u64 v[228:229], vcc, 0, v[0:1]
	s_mov_b32 m0, s74
	v_lshl_add_u64 v[230:231], s[76:77], 0, v[156:157]
	global_load_lds_dwordx4 v[228:229], off
	v_lshl_add_u64 v[228:229], vcc, 0, v[154:155]
	s_add_i32 m0, s74, 0x2000
	s_nop 0
	global_load_lds_dwordx4 v[228:229], off
	v_lshl_add_u64 v[228:229], s[76:77], 0, v[158:159]
	s_mov_b32 m0, s11
	s_nop 0
	global_load_lds_dwordx4 v[228:229], off
	s_mov_b32 m0, s12
	s_nop 0
	global_load_lds_dwordx4 v[230:231], off
	s_waitcnt vmcnt(8)
	s_waitcnt lgkmcnt(0)
	s_barrier
	s_waitcnt lgkmcnt(0)
	v_mfma_f32_16x16x32_bf16 v[62:65], v[130:133], v[172:175], v[62:65]
	v_mfma_f32_16x16x32_bf16 v[58:61], v[138:141], v[172:175], v[58:61]
	v_mfma_f32_16x16x32_bf16 v[46:49], v[130:133], v[186:189], v[46:49]
	v_mfma_f32_16x16x32_bf16 v[42:45], v[138:141], v[186:189], v[42:45]
	v_mfma_f32_16x16x32_bf16 v[30:33], v[130:133], v[212:215], v[30:33]
	v_mfma_f32_16x16x32_bf16 v[26:29], v[138:141], v[212:215], v[26:29]
	v_mfma_f32_16x16x32_bf16 v[14:17], v[130:133], v[220:223], v[14:17]
	v_mfma_f32_16x16x32_bf16 v[10:13], v[138:141], v[220:223], v[10:13]
	v_mfma_f32_16x16x32_bf16 v[62:65], v[134:137], v[176:179], v[62:65]
	v_mfma_f32_16x16x32_bf16 v[58:61], v[142:145], v[176:179], v[58:61]
	v_mfma_f32_16x16x32_bf16 v[46:49], v[134:137], v[208:211], v[46:49]
	v_mfma_f32_16x16x32_bf16 v[42:45], v[142:145], v[208:211], v[42:45]
	v_mfma_f32_16x16x32_bf16 v[30:33], v[134:137], v[216:219], v[30:33]
	v_mfma_f32_16x16x32_bf16 v[26:29], v[142:145], v[216:219], v[26:29]
	v_mfma_f32_16x16x32_bf16 v[14:17], v[134:137], v[224:227], v[14:17]
	v_mfma_f32_16x16x32_bf16 v[10:13], v[142:145], v[224:227], v[10:13]
	v_mfma_f32_16x16x32_bf16 v[54:57], v[146:149], v[172:175], v[54:57]
	v_mfma_f32_16x16x32_bf16 v[50:53], v[164:167], v[172:175], v[50:53]
	v_mfma_f32_16x16x32_bf16 v[38:41], v[146:149], v[186:189], v[38:41]
	v_mfma_f32_16x16x32_bf16 v[34:37], v[164:167], v[186:189], v[34:37]
	v_mfma_f32_16x16x32_bf16 v[22:25], v[146:149], v[212:215], v[22:25]
	v_mfma_f32_16x16x32_bf16 v[18:21], v[164:167], v[212:215], v[18:21]
	v_mfma_f32_16x16x32_bf16 v[6:9], v[146:149], v[220:223], v[6:9]
	v_mfma_f32_16x16x32_bf16 v[2:5], v[164:167], v[220:223], v[2:5]
	v_mfma_f32_16x16x32_bf16 v[54:57], v[150:153], v[176:179], v[54:57]
	v_mfma_f32_16x16x32_bf16 v[50:53], v[168:171], v[176:179], v[50:53]
	v_mfma_f32_16x16x32_bf16 v[38:41], v[150:153], v[208:211], v[38:41]
	v_mfma_f32_16x16x32_bf16 v[34:37], v[168:171], v[208:211], v[34:37]
	v_mfma_f32_16x16x32_bf16 v[22:25], v[150:153], v[216:219], v[22:25]
	v_mfma_f32_16x16x32_bf16 v[18:21], v[168:171], v[216:219], v[18:21]
	v_mfma_f32_16x16x32_bf16 v[6:9], v[150:153], v[224:227], v[6:9]
	v_mfma_f32_16x16x32_bf16 v[2:5], v[168:171], v[224:227], v[2:5]
	s_barrier
; #define PG8_STAGE(bufoff, gbase, voff) do { _Pragma("unroll") for (int _i = 0; _i < 2; ++_i) \
;         __builtin_amdgcn_global_load_lds((const unsigned*)((const char*)(gbase) + (voff)[_i]), (LAS unsigned*)(lds + (bufoff) + ldsw + _i * 8192), 16, 0, 0); } while (0)
; #define PG8_LDA(dst, b, h) do { _Pragma("unroll") for (int m = 0; m < 4; ++m) _Pragma("unroll") for (int k = 0; k < 2; ++k) dst[m][k] = *(const LAS bf16x8*)(lds + PG8_SA(b, h) + aoff + m * 2048 + k * 1024); } while (0)
; #define PG8_LDB(dst, b, h) do { _Pragma("unroll") for (int n = 0; n < 2; ++n) _Pragma("unroll") for (int k = 0; k < 2; ++k) dst[n][k] = *(const LAS bf16x8*)(lds + PG8_SB(b, h) + boff + n * 2048 + k * 1024); } while (0)
; #define PG8_MMA(ai, bj, At, Bt) do { __builtin_amdgcn_s_setprio(1); _Pragma("unroll") for (int m = 0; m < 4; ++m) _Pragma("unroll") for (int n = 0; n < 2; ++n) _Pragma("unroll") for (int k = 0; k < 2; ++k) \
;         acc[ai][bj][m][n] = __builtin_amdgcn_mfma_f32_16x16x32_bf16(Bt[n][k], At[m][k], acc[ai][bj][m][n], 0, 0, 0); __builtin_amdgcn_s_setprio(0); } while (0)
; #define PG8_WAIT_V(n) asm volatile("s_waitcnt vmcnt(" #n ")" ::: "memory")
; #define PG8_WAIT_L(n) asm volatile("s_waitcnt lgkmcnt(" #n ")" ::: "memory")
; #define PG8_BAR __builtin_amdgcn_s_barrier()
; #define PG8_SCHED __builtin_amdgcn_sched_barrier(0)
; template <class Epi, class Sched>
; __device__ __forceinline__ void gemm_phase(LAS unsigned char* lds, const Gemm g, const Sched& S, const Epi& E) {
;     ...
;             PG8_LDB(B0, 1, 0); PG8_LDB(B1, 1, 1); PG8_SCHED; PG8_LDA(At, 1, 0); PG8_STAGE(PG8_SA(0, 1), a2 + hsA, voffA);
;             PG8_WAIT_V(8); PG8_WAIT_L(0); PG8_BAR; PG8_MMA(0, 0, At, B0); PG8_MMA(0, 1, At, B1); PG8_BAR; PG8_SCHED;
	s_add_i32 s74, 0, 0x18000
	s_add_i32 s75, 0, 0x1c000
	v_add_u32_e32 v142, s74, v184
	v_add_u32_e32 v168, s75, v184
	ds_read_b128 v[130:133], v142
	ds_read_b128 v[134:137], v142 offset:1024
	ds_read_b128 v[138:141], v142 offset:2048
	ds_read_b128 v[142:145], v142 offset:3072
	ds_read_b128 v[146:149], v168
	ds_read_b128 v[150:153], v168 offset:1024
	ds_read_b128 v[164:167], v168 offset:2048
	ds_read_b128 v[168:171], v168 offset:3072
	s_add_u32 s76, s76, 0x40000
	s_addc_u32 s77, s77, 0
	s_mov_b32 m0, s16
	v_lshl_add_u64 v[232:233], s[76:77], 0, v[158:159]
	ds_read_b128 v[172:175], v185 offset:32768
	ds_read_b128 v[176:179], v185 offset:33792
	ds_read_b128 v[186:189], v185 offset:34816
	ds_read_b128 v[208:211], v185 offset:35840
	ds_read_b128 v[212:215], v185 offset:36864
	ds_read_b128 v[216:219], v185 offset:37888
	ds_read_b128 v[220:223], v185 offset:38912
	ds_read_b128 v[224:227], v185 offset:39936
	global_load_lds_dwordx4 v[232:233], off
	v_lshl_add_u64 v[232:233], s[76:77], 0, v[156:157]
	s_mov_b32 m0, s24
	s_nop 0
	global_load_lds_dwordx4 v[232:233], off
	s_waitcnt vmcnt(8)
	s_waitcnt lgkmcnt(0)
	s_barrier
	s_waitcnt lgkmcnt(0)
	v_mfma_f32_16x16x32_bf16 v[122:125], v[130:133], v[172:175], v[122:125]
	v_mfma_f32_16x16x32_bf16 v[126:129], v[138:141], v[172:175], v[126:129]
	v_mfma_f32_16x16x32_bf16 v[110:113], v[130:133], v[186:189], v[110:113]
	v_mfma_f32_16x16x32_bf16 v[106:109], v[138:141], v[186:189], v[106:109]
	v_mfma_f32_16x16x32_bf16 v[94:97], v[130:133], v[212:215], v[94:97]
	v_mfma_f32_16x16x32_bf16 v[90:93], v[138:141], v[212:215], v[90:93]
	v_mfma_f32_16x16x32_bf16 v[78:81], v[130:133], v[220:223], v[78:81]
	v_mfma_f32_16x16x32_bf16 v[74:77], v[138:141], v[220:223], v[74:77]
	v_mfma_f32_16x16x32_bf16 v[122:125], v[134:137], v[176:179], v[122:125]
	v_mfma_f32_16x16x32_bf16 v[126:129], v[142:145], v[176:179], v[126:129]
	v_mfma_f32_16x16x32_bf16 v[110:113], v[134:137], v[208:211], v[110:113]
	v_mfma_f32_16x16x32_bf16 v[106:109], v[142:145], v[208:211], v[106:109]
	v_mfma_f32_16x16x32_bf16 v[94:97], v[134:137], v[216:219], v[94:97]
	v_mfma_f32_16x16x32_bf16 v[90:93], v[142:145], v[216:219], v[90:93]
	v_mfma_f32_16x16x32_bf16 v[78:81], v[134:137], v[224:227], v[78:81]
	v_mfma_f32_16x16x32_bf16 v[74:77], v[142:145], v[224:227], v[74:77]
	v_mfma_f32_16x16x32_bf16 v[118:121], v[146:149], v[172:175], v[118:121]
	v_mfma_f32_16x16x32_bf16 v[114:117], v[164:167], v[172:175], v[114:117]
	v_mfma_f32_16x16x32_bf16 v[102:105], v[146:149], v[186:189], v[102:105]
	v_mfma_f32_16x16x32_bf16 v[98:101], v[164:167], v[186:189], v[98:101]
	v_mfma_f32_16x16x32_bf16 v[86:89], v[146:149], v[212:215], v[86:89]
	v_mfma_f32_16x16x32_bf16 v[82:85], v[164:167], v[212:215], v[82:85]
	v_mfma_f32_16x16x32_bf16 v[70:73], v[146:149], v[220:223], v[70:73]
	v_mfma_f32_16x16x32_bf16 v[66:69], v[164:167], v[220:223], v[66:69]
	v_mfma_f32_16x16x32_bf16 v[118:121], v[150:153], v[176:179], v[118:121]
	v_mfma_f32_16x16x32_bf16 v[114:117], v[168:171], v[176:179], v[114:117]
	v_mfma_f32_16x16x32_bf16 v[102:105], v[150:153], v[208:211], v[102:105]
	v_mfma_f32_16x16x32_bf16 v[98:101], v[168:171], v[208:211], v[98:101]
	v_mfma_f32_16x16x32_bf16 v[86:89], v[150:153], v[216:219], v[86:89]
	v_mfma_f32_16x16x32_bf16 v[82:85], v[168:171], v[216:219], v[82:85]
	v_mfma_f32_16x16x32_bf16 v[70:73], v[150:153], v[224:227], v[70:73]
	v_mfma_f32_16x16x32_bf16 v[66:69], v[168:171], v[224:227], v[66:69]
	s_barrier
; #define PG8_STAGE(bufoff, gbase, voff) do { _Pragma("unroll") for (int _i = 0; _i < 2; ++_i) \
;         __builtin_amdgcn_global_load_lds((const unsigned*)((const char*)(gbase) + (voff)[_i]), (LAS unsigned*)(lds + (bufoff) + ldsw + _i * 8192), 16, 0, 0); } while (0)
; #define PG8_LDA(dst, b, h) do { _Pragma("unroll") for (int m = 0; m < 4; ++m) _Pragma("unroll") for (int k = 0; k < 2; ++k) dst[m][k] = *(const LAS bf16x8*)(lds + PG8_SA(b, h) + aoff + m * 2048 + k * 1024); } while (0)
; #define PG8_MMA(ai, bj, At, Bt) do { __builtin_amdgcn_s_setprio(1); _Pragma("unroll") for (int m = 0; m < 4; ++m) _Pragma("unroll") for (int n = 0; n < 2; ++n) _Pragma("unroll") for (int k = 0; k < 2; ++k) \
;         acc[ai][bj][m][n] = __builtin_amdgcn_mfma_f32_16x16x32_bf16(Bt[n][k], At[m][k], acc[ai][bj][m][n], 0, 0, 0); __builtin_amdgcn_s_setprio(0); } while (0)
; #define PG8_WAIT_V(n) asm volatile("s_waitcnt vmcnt(" #n ")" ::: "memory")
; #define PG8_WAIT_L(n) asm volatile("s_waitcnt lgkmcnt(" #n ")" ::: "memory")
; #define PG8_BAR __builtin_amdgcn_s_barrier()
; #define PG8_SCHED __builtin_amdgcn_sched_barrier(0)
; template <class Epi, class Sched>
; __device__ __forceinline__ void gemm_phase(LAS unsigned char* lds, const Gemm g, const Sched& S, const Epi& E) {
;     ...
;             PG8_LDA(At, 1, 1); PG8_STAGE(PG8_SB(1, 0), b3, voffB); PG8_STAGE(PG8_SB(1, 1), b3 + hsB, voffB); PG8_STAGE(PG8_SA(1, 0), a3, voffA);
;             PG8_WAIT_V(8); PG8_WAIT_L(0); PG8_BAR; PG8_MMA(1, 0, At, B0); PG8_MMA(1, 1, At, B1); PG8_BAR; PG8_SCHED;
;         }
	s_add_i32 s74, s74, s7
	v_lshl_add_u64 v[180:181], v[180:181], 0, s[18:19]
	s_mov_b32 m0, s74
	ds_read_b128 v[172:175], v185 offset:49152
	ds_read_b128 v[176:179], v185 offset:50176
	ds_read_b128 v[186:189], v185 offset:51200
	ds_read_b128 v[208:211], v185 offset:52224
	ds_read_b128 v[212:215], v185 offset:53248
	ds_read_b128 v[216:219], v185 offset:54272
	ds_read_b128 v[220:223], v185 offset:55296
	ds_read_b128 v[224:227], v185 offset:56320
	global_load_lds_dwordx4 v[180:181], off
	s_add_i32 m0, s74, 0x2000
	s_add_u32 s50, s50, 0x40080
	v_lshl_add_u64 v[180:181], v[190:191], 0, s[18:19]
	s_addc_u32 s51, s51, 0
	s_add_i32 s74, s75, s7
	global_load_lds_dwordx4 v[180:181], off
	v_lshl_add_u64 v[180:181], s[50:51], 0, v[0:1]
	s_mov_b32 m0, s74
	s_nop 0
	global_load_lds_dwordx4 v[180:181], off
	v_lshl_add_u64 v[180:181], s[50:51], 0, v[154:155]
	s_add_i32 m0, s74, 0x2000
	s_nop 0
	global_load_lds_dwordx4 v[180:181], off
	v_lshl_add_u64 v[180:181], v[228:229], 0, s[18:19]
	s_mov_b32 m0, s57
	s_nop 0
	global_load_lds_dwordx4 v[180:181], off
	v_lshl_add_u64 v[180:181], v[230:231], 0, s[18:19]
	s_mov_b32 m0, s64
	s_nop 0
	global_load_lds_dwordx4 v[180:181], off
	s_waitcnt vmcnt(8)
	s_waitcnt lgkmcnt(0)
	s_barrier
	s_waitcnt lgkmcnt(0)
	v_mfma_f32_16x16x32_bf16 v[62:65], v[130:133], v[172:175], v[62:65]
	v_mfma_f32_16x16x32_bf16 v[58:61], v[138:141], v[172:175], v[58:61]
	v_mfma_f32_16x16x32_bf16 v[46:49], v[130:133], v[186:189], v[46:49]
	v_mfma_f32_16x16x32_bf16 v[42:45], v[138:141], v[186:189], v[42:45]
	v_mfma_f32_16x16x32_bf16 v[30:33], v[130:133], v[212:215], v[30:33]
	v_mfma_f32_16x16x32_bf16 v[26:29], v[138:141], v[212:215], v[26:29]
	v_mfma_f32_16x16x32_bf16 v[14:17], v[130:133], v[220:223], v[14:17]
	v_mfma_f32_16x16x32_bf16 v[10:13], v[138:141], v[220:223], v[10:13]
	v_mfma_f32_16x16x32_bf16 v[62:65], v[134:137], v[176:179], v[62:65]
	v_mfma_f32_16x16x32_bf16 v[58:61], v[142:145], v[176:179], v[58:61]
	v_mfma_f32_16x16x32_bf16 v[46:49], v[134:137], v[208:211], v[46:49]
	v_mfma_f32_16x16x32_bf16 v[42:45], v[142:145], v[208:211], v[42:45]
	v_mfma_f32_16x16x32_bf16 v[30:33], v[134:137], v[216:219], v[30:33]
	v_mfma_f32_16x16x32_bf16 v[26:29], v[142:145], v[216:219], v[26:29]
	v_mfma_f32_16x16x32_bf16 v[14:17], v[134:137], v[224:227], v[14:17]
	v_mfma_f32_16x16x32_bf16 v[10:13], v[142:145], v[224:227], v[10:13]
	v_mfma_f32_16x16x32_bf16 v[54:57], v[146:149], v[172:175], v[54:57]
	v_mfma_f32_16x16x32_bf16 v[50:53], v[164:167], v[172:175], v[50:53]
	v_mfma_f32_16x16x32_bf16 v[38:41], v[146:149], v[186:189], v[38:41]
	v_mfma_f32_16x16x32_bf16 v[34:37], v[164:167], v[186:189], v[34:37]
	v_mfma_f32_16x16x32_bf16 v[22:25], v[146:149], v[212:215], v[22:25]
	v_mfma_f32_16x16x32_bf16 v[18:21], v[164:167], v[212:215], v[18:21]
	v_mfma_f32_16x16x32_bf16 v[6:9], v[146:149], v[220:223], v[6:9]
	v_mfma_f32_16x16x32_bf16 v[2:5], v[164:167], v[220:223], v[2:5]
	v_mfma_f32_16x16x32_bf16 v[54:57], v[150:153], v[176:179], v[54:57]
	v_mfma_f32_16x16x32_bf16 v[50:53], v[168:171], v[176:179], v[50:53]
	v_mfma_f32_16x16x32_bf16 v[38:41], v[150:153], v[208:211], v[38:41]
	v_mfma_f32_16x16x32_bf16 v[34:37], v[168:171], v[208:211], v[34:37]
	v_mfma_f32_16x16x32_bf16 v[22:25], v[150:153], v[216:219], v[22:25]
	v_mfma_f32_16x16x32_bf16 v[18:21], v[168:171], v[216:219], v[18:21]
	v_mfma_f32_16x16x32_bf16 v[6:9], v[150:153], v[224:227], v[6:9]
	v_mfma_f32_16x16x32_bf16 v[2:5], v[168:171], v[224:227], v[2:5]
	s_barrier
	s_add_u32 s0, s0, 0x100
	s_addc_u32 s1, s1, 0
	s_add_u32 s84, s84, 0x100
	s_addc_u32 s85, s85, 0
	s_cmp_ge_i32 s96, s30
	s_mov_b32 s50, s96
	s_cbranch_scc0 .LBB0_912
	s_setprio 0
	v_readlane_b32 s82, v254, 45
	v_readlane_b32 s83, v254, 46
	v_readlane_b32 s96, v250, 43
